# lane sums: the remaining xor-16/32 hops (attention epilogue, row phases) use v_mov + v_permlane16/32_swap + add instead of ds_bpermute + wait
# speedup vs baseline: 1.0072x; 1.0009x over previous
.LBB0_403:
	s_ashr_i32 s1, s0, 31
	s_lshl_b64 s[6:7], s[0:1], 11
	v_lshl_add_u64 v[58:59], v[52:53], 0, s[6:7]
	s_waitcnt lgkmcnt(0)
	global_load_dwordx4 v[32:35], v[58:59], off
	global_load_dwordx4 v[36:39], v[58:59], off offset:1024
	s_add_i32 s4, s0, s83
	s_min_i32 s8, s4, 0xffff
	s_ashr_i32 s9, s8, 31
	s_lshl_b64 s[12:13], s[8:9], 11
	v_lshl_add_u64 v[40:41], v[52:53], 0, s[12:13]
	global_load_dwordx4 v[68:71], v[40:41], off
	global_load_dwordx4 v[48:51], v[40:41], off offset:1024
	s_lshl_b64 s[0:1], s[0:1], 12
	v_lshl_add_u64 v[42:43], v[56:57], 0, s[0:1]
	flat_load_dwordx4 v[72:75], v[42:43]
	flat_load_dwordx4 v[76:79], v[42:43] offset:16
	flat_load_dwordx4 v[82:85], v[42:43] offset:2048
	flat_load_dwordx4 v[96:99], v[42:43] offset:2064
	s_lshl_b64 s[0:1], s[8:9], 12
	v_lshl_add_u64 v[60:61], v[56:57], 0, s[0:1]
	flat_load_dwordx4 v[44:47], v[60:61]
	flat_load_dwordx4 v[40:43], v[60:61] offset:16
	s_cmp_lt_i32 s4, 0x10000
	s_waitcnt vmcnt(0)
	v_and_b32_e32 v81, 0xffff0000, v32
	v_and_b32_e32 v87, 0xffff0000, v33
	v_and_b32_e32 v101, 0xffff0000, v34
	v_and_b32_e32 v103, 0xffff0000, v35
	v_lshlrev_b32_e32 v80, 16, v32
	v_lshlrev_b32_e32 v86, 16, v33
	v_lshlrev_b32_e32 v100, 16, v34
	v_lshlrev_b32_e32 v102, 16, v35
	v_and_b32_e32 v105, 0xffff0000, v36
	v_and_b32_e32 v107, 0xffff0000, v37
	v_mul_f32_e32 v32, v81, v81
	v_mul_f32_e32 v33, v87, v87
	v_mul_f32_e32 v34, v101, v101
	v_mul_f32_e32 v35, v103, v103
	v_lshlrev_b32_e32 v104, 16, v36
	v_lshlrev_b32_e32 v106, 16, v37
	v_and_b32_e32 v109, 0xffff0000, v38
	v_and_b32_e32 v111, 0xffff0000, v39
	v_mul_f32_e32 v36, v105, v105
	v_mul_f32_e32 v37, v107, v107
	v_fmac_f32_e32 v32, v80, v80
	v_fmac_f32_e32 v33, v86, v86
	v_fmac_f32_e32 v34, v100, v100
	v_fmac_f32_e32 v35, v102, v102
	v_lshlrev_b32_e32 v108, 16, v38
	v_lshlrev_b32_e32 v110, 16, v39
	v_mul_f32_e32 v38, v109, v109
	v_mul_f32_e32 v39, v111, v111
	v_fmac_f32_e32 v36, v104, v104
	v_fmac_f32_e32 v37, v106, v106
	v_add_f32_e32 v32, v32, v33
	v_add_f32_e32 v33, v34, v35
	v_fmac_f32_e32 v38, v108, v108
	v_fmac_f32_e32 v39, v110, v110
	v_add_f32_e32 v34, v36, v37
	v_add_f32_e32 v32, v32, v33
	v_add_f32_e32 v35, v38, v39
	v_add_f32_e32 v32, v32, v34
	v_add_f32_e32 v32, v35, v32
	s_nop 1
	v_lshlrev_b32_e32 v66, 16, v71
	v_and_b32_e32 v67, 0xffff0000, v71
	v_lshlrev_b32_e32 v64, 16, v68
	v_and_b32_e32 v65, 0xffff0000, v68
	s_waitcnt lgkmcnt(0)
	v_add_f32_dpp v32, v32, v32 quad_perm:[1,0,3,2] row_mask:0xf bank_mask:0xf
	s_nop 1
	v_lshlrev_b32_e32 v68, 16, v69
	v_and_b32_e32 v69, 0xffff0000, v69
	s_waitcnt lgkmcnt(0)
	v_add_f32_dpp v32, v32, v32 quad_perm:[2,3,0,1] row_mask:0xf bank_mask:0xf
	s_nop 1
	s_waitcnt lgkmcnt(0)
	v_add_f32_dpp v32, v32, v32 row_half_mirror row_mask:0xf bank_mask:0xf
	s_nop 1
	s_waitcnt lgkmcnt(0)
	v_add_f32_dpp v62, v32, v32 row_mirror row_mask:0xf bank_mask:0xf
	v_mov_b32_e32 v63, v62
	flat_load_dwordx4 v[36:39], v[60:61] offset:2048
	flat_load_dwordx4 v[32:35], v[60:61] offset:2064
	s_waitcnt lgkmcnt(0)
	v_permlane16_swap_b32_e32 v62, v63
	v_add_f32_e32 v60, v62, v63
	v_mov_b32_e32 v61, v60
	v_lshlrev_b32_e32 v62, 16, v70
	v_and_b32_e32 v63, 0xffff0000, v70
	s_waitcnt lgkmcnt(0)
	v_permlane32_swap_b32_e32 v60, v61
	v_add_f32_e32 v60, v60, v61
	v_fmamk_f32 v60, v60, 0x3a800000, v94
	v_mul_f32_e32 v61, 0x4f800000, v60
	v_cmp_gt_f32_e32 vcc, s10, v60
	s_nop 1
	v_cndmask_b32_e32 v61, v60, v61, vcc
	v_sqrt_f32_e32 v70, v61
	v_lshlrev_b32_e32 v60, 16, v48
	v_add_u32_e32 v71, -1, v70
	v_add_u32_e32 v112, 1, v70
	v_fma_f32 v113, -v71, v70, v61
	v_fma_f32 v114, -v112, v70, v61
	v_cmp_ge_f32_e64 s[0:1], 0, v113
	s_nop 1
	v_cndmask_b32_e64 v70, v70, v71, s[0:1]
	v_cmp_lt_f32_e64 s[0:1], 0, v114
	s_nop 1
	v_cndmask_b32_e64 v70, v70, v112, s[0:1]
	v_mul_f32_e32 v71, 0x37800000, v70
	v_cndmask_b32_e32 v70, v70, v71, vcc
	v_cmp_class_f32_e32 vcc, v61, v95
	s_nop 1
	v_cndmask_b32_e32 v70, v70, v61, vcc
	v_div_scale_f32 v71, s[0:1], v70, v70, 1.0
	v_rcp_f32_e32 v112, v71
	v_and_b32_e32 v61, 0xffff0000, v48
	v_div_scale_f32 v48, vcc, 1.0, v70, 1.0
	v_fma_f32 v113, -v71, v112, 1.0
	v_fmac_f32_e32 v112, v113, v112
	v_mul_f32_e32 v113, v48, v112
	v_fma_f32 v114, -v71, v113, v48
	v_fmac_f32_e32 v113, v114, v112
	v_fma_f32 v48, -v71, v113, v48
	v_div_fmas_f32 v48, v48, v112, v113
	v_div_fixup_f32 v48, v48, v70, 1.0
	v_mul_f32_e32 v48, 0.5, v48
	v_pk_mul_f32 v[80:81], v[48:49], v[80:81] op_sel_hi:[0,1]
	v_pk_mul_f32 v[70:71], v[48:49], v[86:87] op_sel_hi:[0,1]
	v_pk_mul_f32 v[86:87], v[48:49], v[100:101] op_sel_hi:[0,1]
	v_pk_mul_f32 v[100:101], v[48:49], v[102:103] op_sel_hi:[0,1]
	v_pk_mul_f32 v[102:103], v[48:49], v[104:105] op_sel_hi:[0,1]
	v_pk_mul_f32 v[104:105], v[48:49], v[106:107] op_sel_hi:[0,1]
	v_pk_mul_f32 v[106:107], v[48:49], v[108:109] op_sel_hi:[0,1]
	v_pk_mul_f32 v[108:109], v[48:49], v[110:111] op_sel_hi:[0,1]
	v_pk_fma_f32 v[70:71], v[2:3], v[70:71], v[74:75]
	v_pk_fma_f32 v[72:73], v[0:1], v[80:81], v[72:73]
	v_pk_fma_f32 v[74:75], v[6:7], v[100:101], v[78:79]
	v_pk_fma_f32 v[78:79], v[4:5], v[86:87], v[76:77]
	v_pk_fma_f32 v[80:81], v[10:11], v[104:105], v[84:85]
	v_pk_fma_f32 v[84:85], v[14:15], v[108:109], v[98:99]
	v_pk_fma_f32 v[86:87], v[12:13], v[106:107], v[96:97]
	v_pk_mul_f32 v[76:77], v[70:71], v[70:71]
	v_pk_mul_f32 v[96:97], v[72:73], v[72:73]
	v_pk_mul_f32 v[98:99], v[74:75], v[74:75]
	v_pk_mul_f32 v[100:101], v[78:79], v[78:79]
	v_pk_fma_f32 v[82:83], v[8:9], v[102:103], v[82:83]
	v_pk_mov_b32 v[104:105], v[96:97], v[76:77] op_sel:[1,0]
	v_mov_b32_e32 v97, v77
	v_pk_mov_b32 v[76:77], v[100:101], v[98:99] op_sel:[1,0]
	v_mov_b32_e32 v101, v99
	v_mul_f32_e32 v48, v82, v82
	v_mul_f32_e32 v102, v80, v80
	v_pk_add_f32 v[96:97], v[104:105], v[96:97]
	v_pk_add_f32 v[76:77], v[76:77], v[100:101]
	v_pk_fma_f32 v[98:99], v[82:83], v[82:83], v[48:49] op_sel_hi:[1,1,0]
	v_pk_fma_f32 v[102:103], v[80:81], v[80:81], v[102:103] op_sel_hi:[1,1,0]
	v_pk_add_f32 v[96:97], v[96:97], v[96:97] op_sel_hi:[0,1]
	v_pk_add_f32 v[76:77], v[76:77], v[76:77] op_sel_hi:[0,1]
	v_mul_f32_e32 v98, v86, v86
	v_mul_f32_e32 v102, v87, v87
	v_mul_f32_e32 v96, v84, v84
	v_mul_f32_e32 v76, v85, v85
	v_pk_add_f32 v[98:99], v[98:99], v[102:103]
	v_pk_add_f32 v[76:77], v[96:97], v[76:77]
	v_mul_f32_e32 v100, v63, v63
	v_pk_add_f32 v[76:77], v[98:99], v[76:77]
	v_mul_f32_e32 v98, v65, v65
	v_add_f32_e32 v96, v76, v77
	s_nop 1
	v_mul_f32_e32 v99, v69, v69
	v_fmac_f32_e32 v98, v64, v64
	v_fmac_f32_e32 v99, v68, v68
	v_add_f32_e32 v98, v98, v99
	s_waitcnt lgkmcnt(0)
	v_add_f32_dpp v96, v96, v96 quad_perm:[1,0,3,2] row_mask:0xf bank_mask:0xf
	s_nop 1
	v_mul_f32_e32 v101, v67, v67
	v_fmac_f32_e32 v100, v62, v62
	v_fmac_f32_e32 v101, v66, v66
	v_and_b32_e32 v77, 0xffff0000, v49
	s_waitcnt lgkmcnt(0)
	v_add_f32_dpp v96, v96, v96 quad_perm:[2,3,0,1] row_mask:0xf bank_mask:0xf
	s_nop 1
	v_lshlrev_b32_e32 v76, 16, v49
	v_lshlrev_b32_e32 v48, 16, v50
	v_and_b32_e32 v49, 0xffff0000, v50
	v_lshlrev_b32_e32 v50, 16, v51
	s_waitcnt lgkmcnt(0)
	v_add_f32_dpp v96, v96, v96 row_half_mirror row_mask:0xf bank_mask:0xf
	s_nop 1
	v_and_b32_e32 v51, 0xffff0000, v51
	v_mul_f32_e32 v102, v61, v61
	v_fmac_f32_e32 v102, v60, v60
	s_waitcnt lgkmcnt(0)
	v_add_f32_dpp v99, v96, v96 row_mirror row_mask:0xf bank_mask:0xf
	v_mov_b32_e32 v103, v99
	v_add_f32_e32 v96, v100, v101
	v_add_f32_e32 v100, v98, v96
	v_cvt_pk_bf16_f32 v96, v72, v73
	v_cvt_pk_bf16_f32 v97, v70, v71
	s_waitcnt lgkmcnt(0)
	v_permlane16_swap_b32_e32 v99, v103
	v_add_f32_e32 v101, v99, v103
	v_mov_b32_e32 v103, v101
	v_cvt_pk_bf16_f32 v98, v78, v79
	v_cvt_pk_bf16_f32 v99, v74, v75
	global_store_dwordx4 v[58:59], v[96:99], off
	s_waitcnt lgkmcnt(0)
	s_nop 0
	v_permlane32_swap_b32_e32 v101, v103
	v_add_f32_e32 v97, v101, v103
	v_fmamk_f32 v97, v97, 0x3a800000, v94
	v_mul_f32_e32 v98, 0x4f800000, v97
	v_cmp_gt_f32_e32 vcc, s10, v97
	v_cvt_pk_bf16_f32 v96, v82, v83
	s_nop 1
	v_cndmask_b32_e32 v101, v97, v98, vcc
	v_sqrt_f32_e32 v103, v101
	v_cvt_pk_bf16_f32 v97, v80, v81
	v_cvt_pk_bf16_f32 v98, v86, v87
	v_cvt_pk_bf16_f32 v99, v84, v85
	global_store_dwordx4 v[58:59], v[96:99], off offset:1024
	v_add_u32_e32 v104, -1, v103
	v_add_u32_e32 v105, 1, v103
	v_fma_f32 v106, -v104, v103, v101
	v_fma_f32 v107, -v105, v103, v101
	v_cmp_ge_f32_e64 s[0:1], 0, v106
	v_mul_f32_e32 v97, v49, v49
	v_mul_f32_e32 v98, v51, v51
	v_cndmask_b32_e64 v103, v103, v104, s[0:1]
	v_cmp_lt_f32_e64 s[0:1], 0, v107
	v_fmac_f32_e32 v97, v48, v48
	v_fmac_f32_e32 v98, v50, v50
	v_cndmask_b32_e64 v103, v103, v105, s[0:1]
	v_mul_f32_e32 v104, 0x37800000, v103
	v_cndmask_b32_e32 v103, v103, v104, vcc
	v_cmp_class_f32_e32 vcc, v101, v95
	v_add_f32_e32 v97, v97, v98
	s_nop 0
	v_cndmask_b32_e32 v101, v103, v101, vcc
	v_div_scale_f32 v103, s[0:1], v101, v101, 1.0
	v_rcp_f32_e32 v104, v103
	v_div_scale_f32 v58, vcc, 1.0, v101, 1.0
	v_fma_f32 v59, -v103, v104, 1.0
	v_fmac_f32_e32 v104, v59, v104
	v_mul_f32_e32 v59, v58, v104
	v_fma_f32 v96, -v103, v59, v58
	v_fmac_f32_e32 v59, v96, v104
	v_mul_f32_e32 v96, v77, v77
	v_fmac_f32_e32 v96, v76, v76
	v_add_f32_e32 v96, v102, v96
	v_add_f32_e32 v96, v100, v96
	v_add_f32_e32 v96, v97, v96
	s_nop 1
	v_fma_f32 v58, -v103, v59, v58
	v_div_fmas_f32 v58, v58, v104, v59
	v_div_fixup_f32 v58, v58, v101, 1.0
	v_pk_mul_f32 v[86:87], v[86:87], v[58:59] op_sel_hi:[1,0]
	s_waitcnt lgkmcnt(0)
	v_add_f32_dpp v59, v96, v96 quad_perm:[1,0,3,2] row_mask:0xf bank_mask:0xf
	s_nop 1
	v_pk_mul_f32 v[84:85], v[84:85], v[58:59] op_sel_hi:[1,0]
	v_pk_mul_f32 v[82:83], v[82:83], v[58:59] op_sel_hi:[1,0]
	v_pk_mul_f32 v[84:85], v[30:31], v[84:85]
	v_pk_mul_f32 v[82:83], v[24:25], v[82:83]
	s_waitcnt lgkmcnt(0)
	v_add_f32_dpp v59, v59, v59 quad_perm:[2,3,0,1] row_mask:0xf bank_mask:0xf
	s_nop 1
	v_pk_mul_f32 v[80:81], v[80:81], v[58:59] op_sel_hi:[1,0]
	v_pk_mul_f32 v[78:79], v[78:79], v[58:59] op_sel_hi:[1,0]
	v_pk_mul_f32 v[86:87], v[28:29], v[86:87]
	v_pk_mul_f32 v[78:79], v[20:21], v[78:79]
	s_waitcnt lgkmcnt(0)
	v_add_f32_dpp v59, v59, v59 row_half_mirror row_mask:0xf bank_mask:0xf
	s_nop 1
	v_pk_mul_f32 v[74:75], v[74:75], v[58:59] op_sel_hi:[1,0]
	v_pk_mul_f32 v[72:73], v[72:73], v[58:59] op_sel_hi:[1,0]
	v_pk_mul_f32 v[74:75], v[22:23], v[74:75]
	v_pk_mul_f32 v[80:81], v[26:27], v[80:81]
	s_waitcnt lgkmcnt(0)
	v_add_f32_dpp v98, v59, v59 row_mirror row_mask:0xf bank_mask:0xf
	v_mov_b32_e32 v99, v98
	v_pk_mul_f32 v[58:59], v[70:71], v[58:59] op_sel_hi:[1,0]
	v_pk_mul_f32 v[70:71], v[16:17], v[72:73]
	v_pk_mul_f32 v[58:59], v[18:19], v[58:59]
	v_cvt_pk_bf16_f32 v70, v70, v71
	s_waitcnt lgkmcnt(0)
	v_permlane16_swap_b32_e32 v98, v99
	v_add_f32_e32 v98, v98, v99
	ds_bpermute_b32 v99, v93, v98
	v_cvt_pk_bf16_f32 v71, v58, v59
	v_lshl_add_u64 v[96:97], v[54:55], 0, s[6:7]
	v_cvt_pk_bf16_f32 v72, v78, v79
	v_cvt_pk_bf16_f32 v73, v74, v75
	s_waitcnt lgkmcnt(0)
	v_add_f32_e32 v58, v98, v99
	v_fmamk_f32 v58, v58, 0x3a800000, v94
	v_mul_f32_e32 v59, 0x4f800000, v58
	v_cmp_gt_f32_e32 vcc, s10, v58
	global_store_dwordx4 v[96:97], v[70:73], off
	s_mov_b64 s[6:7], -1
	v_cndmask_b32_e32 v58, v58, v59, vcc
	v_sqrt_f32_e32 v59, v58
	v_cvt_pk_bf16_f32 v70, v82, v83
	v_cvt_pk_bf16_f32 v71, v80, v81
	s_nop 0
	v_add_u32_e32 v72, -1, v59
	v_fma_f32 v73, -v72, v59, v58
	v_cmp_ge_f32_e64 s[0:1], 0, v73
	v_add_u32_e32 v73, 1, v59
	s_nop 0
	v_cndmask_b32_e64 v72, v59, v72, s[0:1]
	v_fma_f32 v59, -v73, v59, v58
	v_cmp_lt_f32_e64 s[0:1], 0, v59
	s_nop 1
	v_cndmask_b32_e64 v59, v72, v73, s[0:1]
	v_mul_f32_e32 v72, 0x37800000, v59
	v_cndmask_b32_e32 v59, v59, v72, vcc
	v_cmp_class_f32_e32 vcc, v58, v95
	v_cvt_pk_bf16_f32 v72, v86, v87
	v_cvt_pk_bf16_f32 v73, v84, v85
	global_store_dwordx4 v[96:97], v[70:73], off offset:1024
	s_nop 0
	v_cndmask_b32_e32 v58, v59, v58, vcc
	v_div_scale_f32 v59, s[0:1], v58, v58, 1.0
	v_rcp_f32_e32 v74, v59
	s_cselect_b64 s[0:1], -1, 0
	v_fma_f32 v70, -v59, v74, 1.0
	v_fmac_f32_e32 v74, v70, v74
	v_div_scale_f32 v70, vcc, 1.0, v58, 1.0
	v_mul_f32_e32 v71, v70, v74
	v_fma_f32 v72, -v59, v71, v70
	v_fmac_f32_e32 v71, v72, v74
	v_fma_f32 v59, -v59, v71, v70
	v_div_fmas_f32 v59, v59, v74, v71
	v_div_fixup_f32 v58, v59, v58, 1.0
	v_mul_f32_e32 v70, 0.5, v58
	v_pk_mul_f32 v[68:69], v[70:71], v[68:69] op_sel_hi:[0,1]
	v_pk_mul_f32 v[58:59], v[70:71], v[64:65] op_sel_hi:[0,1]
	v_pk_fma_f32 v[58:59], v[0:1], v[58:59], v[44:45]
	v_pk_fma_f32 v[44:45], v[2:3], v[68:69], v[46:47]
	v_pk_mul_f32 v[64:65], v[70:71], v[66:67] op_sel_hi:[0,1]
	v_pk_mul_f32 v[46:47], v[70:71], v[62:63] op_sel_hi:[0,1]
	v_pk_fma_f32 v[46:47], v[4:5], v[46:47], v[40:41]
	v_pk_fma_f32 v[40:41], v[6:7], v[64:65], v[42:43]
	v_pk_mul_f32 v[62:63], v[70:71], v[76:77] op_sel_hi:[0,1]
	v_pk_mul_f32 v[42:43], v[70:71], v[60:61] op_sel_hi:[0,1]
	s_waitcnt vmcnt(0)
	v_pk_fma_f32 v[42:43], v[8:9], v[42:43], v[36:37]
	v_pk_fma_f32 v[36:37], v[10:11], v[62:63], v[38:39]
	v_pk_mul_f32 v[50:51], v[70:71], v[50:51] op_sel_hi:[0,1]
	v_pk_mul_f32 v[38:39], v[70:71], v[48:49] op_sel_hi:[0,1]
	v_pk_fma_f32 v[38:39], v[12:13], v[38:39], v[32:33]
	v_pk_fma_f32 v[32:33], v[14:15], v[50:51], v[34:35]
	s_and_b64 vcc, exec, s[0:1]
	s_cbranch_vccnz .LBB0_405
	s_mov_b64 s[6:7], 0

.LBB0_407:
	v_mul_f32_e32 v34, v58, v58
	v_mul_f32_e32 v35, v44, v44
	v_fmac_f32_e32 v34, v59, v59
	v_fmac_f32_e32 v35, v45, v45
	v_add_f32_e32 v34, v35, v34
	v_mul_f32_e32 v35, v46, v46
	v_mul_f32_e32 v48, v40, v40
	v_fmac_f32_e32 v35, v47, v47
	v_fmac_f32_e32 v48, v41, v41
	v_add_f32_e32 v35, v48, v35
	v_add_f32_e32 v34, v35, v34
	v_mul_f32_e32 v35, v42, v42
	v_mul_f32_e32 v48, v36, v36
	v_fmac_f32_e32 v35, v43, v43
	v_fmac_f32_e32 v48, v37, v37
	v_add_f32_e32 v35, v48, v35
	v_add_f32_e32 v34, v35, v34
	v_mul_f32_e32 v35, v38, v38
	v_mul_f32_e32 v48, v32, v32
	v_fmac_f32_e32 v35, v39, v39
	v_fmac_f32_e32 v48, v33, v33
	v_add_f32_e32 v35, v48, v35
	v_add_f32_e32 v34, v35, v34
	s_nop 1
	s_andn2_b64 vcc, exec, s[0:1]
	s_waitcnt lgkmcnt(0)
	v_add_f32_dpp v34, v34, v34 quad_perm:[1,0,3,2] row_mask:0xf bank_mask:0xf
	s_nop 1
	s_waitcnt lgkmcnt(0)
	v_add_f32_dpp v34, v34, v34 quad_perm:[2,3,0,1] row_mask:0xf bank_mask:0xf
	s_nop 1
	s_waitcnt lgkmcnt(0)
	v_add_f32_dpp v34, v34, v34 row_half_mirror row_mask:0xf bank_mask:0xf
	s_nop 1
	s_waitcnt lgkmcnt(0)
	v_add_f32_dpp v34, v34, v34 row_mirror row_mask:0xf bank_mask:0xf
	v_mov_b32_e32 v35, v34
	s_waitcnt lgkmcnt(0)
	s_nop 0
	v_permlane16_swap_b32_e32 v34, v35
	v_add_f32_e32 v34, v34, v35
	ds_bpermute_b32 v35, v93, v34
	s_cbranch_vccnz .LBB0_402
	s_waitcnt lgkmcnt(0)
	v_add_f32_e32 v34, v34, v35
	v_fmamk_f32 v34, v34, 0x3a800000, v94
	v_mul_f32_e32 v35, 0x4f800000, v34
	v_cmp_gt_f32_e32 vcc, s10, v34
	s_ashr_i32 s5, s4, 31
	s_nop 0
	v_cndmask_b32_e32 v34, v34, v35, vcc
	v_sqrt_f32_e32 v35, v34
	s_nop 0
	v_add_u32_e32 v48, -1, v35
	v_fma_f32 v50, -v48, v35, v34
	v_add_u32_e32 v49, 1, v35
	v_cmp_ge_f32_e64 s[0:1], 0, v50
	s_nop 1
	v_cndmask_b32_e64 v48, v35, v48, s[0:1]
	v_fma_f32 v35, -v49, v35, v34
	v_cmp_lt_f32_e64 s[0:1], 0, v35
	s_nop 1
	v_cndmask_b32_e64 v35, v48, v49, s[0:1]
	v_mul_f32_e32 v48, 0x37800000, v35
	v_cndmask_b32_e32 v35, v35, v48, vcc
	v_cmp_class_f32_e32 vcc, v34, v95
	s_nop 1
	v_cndmask_b32_e32 v34, v35, v34, vcc
	v_div_scale_f32 v35, s[0:1], v34, v34, 1.0
	v_rcp_f32_e32 v48, v35
	s_lshl_b64 s[0:1], s[4:5], 11
	v_fma_f32 v49, -v35, v48, 1.0
	v_fmac_f32_e32 v48, v49, v48
	v_div_scale_f32 v49, vcc, 1.0, v34, 1.0
	v_mul_f32_e32 v50, v49, v48
	v_fma_f32 v51, -v35, v50, v49
	v_fmac_f32_e32 v50, v51, v48
	v_fma_f32 v35, -v35, v50, v49
	v_div_fmas_f32 v35, v35, v48, v50
	v_div_fixup_f32 v34, v35, v34, 1.0
	v_pk_mul_f32 v[32:33], v[32:33], v[34:35] op_sel_hi:[1,0]
	v_pk_mul_f32 v[38:39], v[38:39], v[34:35] op_sel_hi:[1,0]
	v_pk_mul_f32 v[48:49], v[30:31], v[32:33]
	v_pk_mul_f32 v[32:33], v[42:43], v[34:35] op_sel_hi:[1,0]
	v_pk_mul_f32 v[36:37], v[36:37], v[34:35] op_sel_hi:[1,0]
	v_pk_mul_f32 v[42:43], v[24:25], v[32:33]
	v_pk_mul_f32 v[32:33], v[46:47], v[34:35] op_sel_hi:[1,0]
	v_pk_mul_f32 v[40:41], v[40:41], v[34:35] op_sel_hi:[1,0]
	v_pk_mul_f32 v[46:47], v[20:21], v[32:33]
	v_pk_mul_f32 v[32:33], v[58:59], v[34:35] op_sel_hi:[1,0]
	v_pk_mul_f32 v[34:35], v[44:45], v[34:35] op_sel_hi:[1,0]
	v_pk_mul_f32 v[32:33], v[16:17], v[32:33]
	v_pk_mul_f32 v[34:35], v[18:19], v[34:35]
	v_pk_mul_f32 v[40:41], v[22:23], v[40:41]
	v_lshl_add_u64 v[44:45], v[54:55], 0, s[0:1]
	v_cvt_pk_bf16_f32 v32, v32, v33
	v_cvt_pk_bf16_f32 v33, v34, v35
	v_cvt_pk_bf16_f32 v34, v46, v47
	v_cvt_pk_bf16_f32 v35, v40, v41
	v_pk_mul_f32 v[38:39], v[28:29], v[38:39]
	v_pk_mul_f32 v[36:37], v[26:27], v[36:37]
	global_store_dwordx4 v[44:45], v[32:35], off
	s_nop 1
	v_cvt_pk_bf16_f32 v32, v42, v43
	v_cvt_pk_bf16_f32 v33, v36, v37
	v_cvt_pk_bf16_f32 v34, v38, v39
	v_cvt_pk_bf16_f32 v35, v48, v49
	global_store_dwordx4 v[44:45], v[32:35], off offset:1024
	s_branch .LBB0_402

.LBB0_1029:
	s_or_b64 exec, exec, s[0:1]
	s_waitcnt lgkmcnt(0)
	v_add_u32_e32 v64, s33, v188
	ds_read_b128 v[76:79], v64
	ds_read_b128 v[72:75], v64 offset:32
	ds_read_b128 v[68:71], v64 offset:64
	ds_read_b128 v[64:67], v64 offset:96
	s_waitcnt vmcnt(0) lgkmcnt(0)
	s_barrier
	flat_load_dword v84, v[150:151]
	flat_load_dword v85, v[150:151] offset:128
	flat_load_dword v86, v[150:151] offset:256
	flat_load_dword v87, v[150:151] offset:384
	ds_read_u16 v81, v222
	v_and_b32_e32 v80, 64, v209
	v_rcp_f32_e32 v76, v76
	v_add_u32_e32 v83, 64, v80
	ds_read_u16 v80, v221
	ds_read_u16 v82, v221 offset:128
	ds_read_u16 v88, v222 offset:128
	s_waitcnt lgkmcnt(0)
	v_lshlrev_b32_e32 v81, 16, v81
	v_mul_f32_e32 v48, v210, v48
	v_fma_f32 v89, -v48, v76, v81
	v_lshlrev_b32_e32 v48, 16, v80
	v_mul_f32_e32 v32, v210, v32
	v_fma_f32 v90, -v32, v76, v48
	v_lshlrev_b32_e32 v32, 16, v88
	v_mul_f32_e32 v16, v210, v16
	v_fma_f32 v88, -v16, v76, v32
	v_lshlrev_b32_e32 v16, 16, v82
	v_mul_f32_e32 v0, v210, v0
	v_mul_f32_e32 v48, v90, v90
	v_fma_f32 v91, -v0, v76, v16
	v_xor_b32_e32 v0, 1, v209
	v_fmac_f32_e32 v48, v89, v89
	v_cmp_lt_i32_e32 vcc, v0, v83
	v_fmac_f32_e32 v48, v88, v88
	v_fmac_f32_e32 v48, v91, v91
	v_cndmask_b32_e32 v0, v209, v0, vcc
	v_lshlrev_b32_e32 v32, 2, v0
	s_nop 1
	v_xor_b32_e32 v16, 2, v209
	v_cmp_lt_i32_e32 vcc, v16, v83
	v_rcp_f32_e32 v77, v77
	v_mul_f32_e32 v49, v210, v49
	v_cndmask_b32_e32 v16, v209, v16, vcc
	s_waitcnt lgkmcnt(0)
	v_add_f32_dpp v0, v48, v48 quad_perm:[1,0,3,2] row_mask:0xf bank_mask:0xf
	v_lshlrev_b32_e32 v80, 2, v16
	s_nop 1
	v_mul_f32_e32 v33, v210, v33
	v_mul_f32_e32 v17, v210, v17
	v_mul_f32_e32 v1, v210, v1
	v_mul_f32_e32 v34, v210, v34
	s_waitcnt lgkmcnt(0)
	v_add_f32_dpp v0, v0, v0 quad_perm:[2,3,0,1] row_mask:0xf bank_mask:0xf
	v_xor_b32_e32 v16, 4, v209
	v_cmp_lt_i32_e32 vcc, v16, v83
	v_mul_f32_e32 v50, v210, v50
	v_mul_f32_e32 v18, v210, v18
	v_cndmask_b32_e32 v16, v209, v16, vcc
	v_lshlrev_b32_e32 v81, 2, v16
	s_nop 1
	v_mul_f32_e32 v2, v210, v2
	v_mul_f32_e32 v35, v210, v35
	v_mul_f32_e32 v19, v210, v19
	v_mul_f32_e32 v3, v210, v3
	s_waitcnt lgkmcnt(0)
	v_add_f32_dpp v0, v0, v0 row_half_mirror row_mask:0xf bank_mask:0xf
	v_xor_b32_e32 v16, 8, v209
	v_cmp_lt_i32_e32 vcc, v16, v83
	v_mul_f32_e32 v20, v210, v20
	v_mul_f32_e32 v4, v210, v4
	v_cndmask_b32_e32 v16, v209, v16, vcc
	v_lshlrev_b32_e32 v82, 2, v16
	s_nop 1
	v_mul_f32_e32 v5, v210, v5
	v_mul_f32_e32 v6, v210, v6
	v_mul_f32_e32 v7, v210, v7
	v_mul_f32_e32 v8, v210, v8
	s_waitcnt lgkmcnt(0)
	v_add_f32_dpp v0, v0, v0 row_mirror row_mask:0xf bank_mask:0xf
	v_xor_b32_e32 v16, 16, v209
	v_cmp_lt_i32_e32 vcc, v16, v83
	s_lshl_b32 s2, s2, 1
	s_add_i32 s73, s73, s82
	v_cndmask_b32_e32 v16, v209, v16, vcc
	v_lshlrev_b32_e32 v83, 2, v16
	v_mov_b32_e32 v16, v0
	s_add_i32 s68, s68, s69
	s_cmpk_gt_i32 s73, 0x7ff
	s_waitcnt lgkmcnt(0)
	v_permlane16_swap_b32_e32 v0, v16
	v_add_f32_e32 v0, v0, v16
	v_fmamk_f32 v0, v0, 0x3c000000, v198
	v_mul_f32_e32 v16, 0x4f800000, v0
	v_cmp_gt_f32_e32 vcc, s72, v0
	s_nop 1
	v_cndmask_b32_e32 v0, v0, v16, vcc
	v_sqrt_f32_e32 v16, v0
	s_nop 0
	v_add_u32_e32 v48, -1, v16
	v_add_u32_e32 v76, 1, v16
	v_fma_f32 v92, -v48, v16, v0
	v_fma_f32 v93, -v76, v16, v0
	v_cmp_ge_f32_e64 s[0:1], 0, v92
	s_nop 1
	v_cndmask_b32_e64 v16, v16, v48, s[0:1]
	v_cmp_lt_f32_e64 s[0:1], 0, v93
	s_nop 1
	v_cndmask_b32_e64 v16, v16, v76, s[0:1]
	v_mul_f32_e32 v48, 0x37800000, v16
	v_cndmask_b32_e32 v16, v16, v48, vcc
	v_cmp_class_f32_e32 vcc, v0, v199
	s_waitcnt vmcnt(0)
	v_mul_f32_e32 v48, 0x3f4ccccd, v84
	v_mul_f32_e32 v76, 0x3f4ccccd, v85
	v_cndmask_b32_e32 v84, v16, v0, vcc
	v_div_scale_f32 v92, s[0:1], v84, v84, 1.0
	v_rcp_f32_e32 v93, v92
	v_mul_f32_e32 v16, 0x3f4ccccd, v86
	v_mul_f32_e32 v0, 0x3f4ccccd, v87
	v_fma_f32 v85, -v92, v93, 1.0
	v_fmac_f32_e32 v93, v85, v93
	v_div_scale_f32 v85, vcc, 1.0, v84, 1.0
	v_mul_f32_e32 v86, v85, v93
	v_fma_f32 v87, -v92, v86, v85
	v_fmac_f32_e32 v86, v87, v93
	v_fma_f32 v85, -v92, v86, v85
	v_div_fmas_f32 v85, v85, v93, v86
	v_div_fixup_f32 v84, v85, v84, 1.0
	v_mul_f32_e32 v85, v89, v84
	v_mul_f32_e32 v85, v48, v85
	v_cvt_pk_bf16_f32 v85, v85, v133
	ds_write_b16 v222, v85
	v_mul_f32_e32 v85, v90, v84
	v_mul_f32_e32 v85, v76, v85
	v_cvt_pk_bf16_f32 v85, v85, v133
	ds_write_b16 v221, v85
	v_mul_f32_e32 v85, v88, v84
	v_mul_f32_e32 v85, v16, v85
	v_mul_f32_e32 v84, v91, v84
	v_cvt_pk_bf16_f32 v85, v85, v133
	v_mul_f32_e32 v84, v0, v84
	ds_write_b16 v222, v85 offset:128
	v_cvt_pk_bf16_f32 v84, v84, v133
	ds_read_u16 v85, v220 offset:256
	ds_read_u16 v86, v219 offset:256
	ds_read_u16 v87, v219 offset:384
	ds_read_u16 v88, v220 offset:384
	ds_write_b16 v221, v84 offset:128
	s_waitcnt lgkmcnt(4)
	v_lshlrev_b32_e32 v85, 16, v85
	v_fma_f32 v49, -v49, v77, v85
	s_waitcnt lgkmcnt(3)
	v_lshlrev_b32_e32 v85, 16, v86
	v_fma_f32 v33, -v33, v77, v85
	v_mul_f32_e32 v85, v33, v33
	s_waitcnt lgkmcnt(1)
	v_lshlrev_b32_e32 v86, 16, v88
	v_fmac_f32_e32 v85, v49, v49
	v_fma_f32 v17, -v17, v77, v86
	v_lshlrev_b32_e32 v86, 16, v87
	v_fmac_f32_e32 v85, v17, v17
	v_fma_f32 v1, -v1, v77, v86
	v_fmac_f32_e32 v85, v1, v1
	s_nop 1
	s_waitcnt lgkmcnt(0)
	v_add_f32_dpp v77, v85, v85 quad_perm:[1,0,3,2] row_mask:0xf bank_mask:0xf
	s_nop 1
	s_waitcnt lgkmcnt(0)
	v_add_f32_dpp v77, v77, v77 quad_perm:[2,3,0,1] row_mask:0xf bank_mask:0xf
	s_nop 1
	s_waitcnt lgkmcnt(0)
	v_add_f32_dpp v77, v77, v77 row_half_mirror row_mask:0xf bank_mask:0xf
	s_nop 1
	s_waitcnt lgkmcnt(0)
	v_add_f32_dpp v77, v77, v77 row_mirror row_mask:0xf bank_mask:0xf
	v_mov_b32_e32 v85, v77
	s_waitcnt lgkmcnt(0)
	s_nop 0
	v_permlane16_swap_b32_e32 v77, v85
	v_add_f32_e32 v77, v77, v85
	v_fmamk_f32 v77, v77, 0x3c000000, v198
	v_mul_f32_e32 v85, 0x4f800000, v77
	v_cmp_gt_f32_e32 vcc, s72, v77
	s_nop 1
	v_cndmask_b32_e32 v77, v77, v85, vcc
	v_sqrt_f32_e32 v85, v77
	s_nop 0
	v_add_u32_e32 v86, -1, v85
	v_fma_f32 v87, -v86, v85, v77
	v_cmp_ge_f32_e64 s[0:1], 0, v87
	v_add_u32_e32 v87, 1, v85
	s_nop 0
	v_cndmask_b32_e64 v86, v85, v86, s[0:1]
	v_fma_f32 v85, -v87, v85, v77
	v_cmp_lt_f32_e64 s[0:1], 0, v85
	s_nop 1
	v_cndmask_b32_e64 v85, v86, v87, s[0:1]
	v_mul_f32_e32 v86, 0x37800000, v85
	v_cndmask_b32_e32 v85, v85, v86, vcc
	v_cmp_class_f32_e32 vcc, v77, v199
	s_nop 1
	v_cndmask_b32_e32 v77, v85, v77, vcc
	v_div_scale_f32 v85, s[0:1], v77, v77, 1.0
	v_rcp_f32_e32 v86, v85
	s_nop 0
	v_fma_f32 v84, -v85, v86, 1.0
	v_fmac_f32_e32 v86, v84, v86
	v_div_scale_f32 v84, vcc, 1.0, v77, 1.0
	v_mul_f32_e32 v87, v84, v86
	v_fma_f32 v88, -v85, v87, v84
	v_fmac_f32_e32 v87, v88, v86
	v_fma_f32 v84, -v85, v87, v84
	v_div_fmas_f32 v84, v84, v86, v87
	v_div_fixup_f32 v77, v84, v77, 1.0
	v_mul_f32_e32 v49, v49, v77
	v_mul_f32_e32 v33, v33, v77
	v_mul_f32_e32 v17, v17, v77
	v_mul_f32_e32 v49, v48, v49
	v_mul_f32_e32 v33, v76, v33
	v_mul_f32_e32 v17, v16, v17
	v_mul_f32_e32 v1, v1, v77
	v_cvt_pk_bf16_f32 v49, v49, v133
	ds_write_b16 v220, v49 offset:256
	v_cvt_pk_bf16_f32 v33, v33, v133
	ds_write_b16 v219, v33 offset:256
	v_cvt_pk_bf16_f32 v17, v17, v133
	v_mul_f32_e32 v1, v0, v1
	ds_write_b16 v220, v17 offset:384
	v_cvt_pk_bf16_f32 v1, v1, v133
	ds_read_u16 v17, v218 offset:512
	v_rcp_f32_e32 v33, v78
	ds_read_u16 v49, v217 offset:512
	ds_read_u16 v77, v217 offset:640
	ds_read_u16 v78, v218 offset:640
	ds_write_b16 v219, v1 offset:384
	s_waitcnt lgkmcnt(3)
	v_lshlrev_b32_e32 v49, 16, v49
	v_lshlrev_b32_e32 v17, 16, v17
	v_fma_f32 v34, -v34, v33, v49
	v_fma_f32 v17, -v50, v33, v17
	v_mul_f32_e32 v49, v34, v34
	s_waitcnt lgkmcnt(1)
	v_lshlrev_b32_e32 v50, 16, v78
	v_fmac_f32_e32 v49, v17, v17
	v_fma_f32 v18, -v18, v33, v50
	v_lshlrev_b32_e32 v50, 16, v77
	v_fmac_f32_e32 v49, v18, v18
	v_fma_f32 v2, -v2, v33, v50
	v_fmac_f32_e32 v49, v2, v2
	s_nop 1
	s_waitcnt lgkmcnt(0)
	v_add_f32_dpp v33, v49, v49 quad_perm:[1,0,3,2] row_mask:0xf bank_mask:0xf
	s_nop 1
	s_waitcnt lgkmcnt(0)
	v_add_f32_dpp v33, v33, v33 quad_perm:[2,3,0,1] row_mask:0xf bank_mask:0xf
	s_nop 1
	s_waitcnt lgkmcnt(0)
	v_add_f32_dpp v33, v33, v33 row_half_mirror row_mask:0xf bank_mask:0xf
	s_nop 1
	s_waitcnt lgkmcnt(0)
	v_add_f32_dpp v33, v33, v33 row_mirror row_mask:0xf bank_mask:0xf
	v_mov_b32_e32 v49, v33
	s_waitcnt lgkmcnt(0)
	s_nop 0
	v_permlane16_swap_b32_e32 v33, v49
	v_add_f32_e32 v33, v33, v49
	v_fmamk_f32 v33, v33, 0x3c000000, v198
	v_mul_f32_e32 v49, 0x4f800000, v33
	v_cmp_gt_f32_e32 vcc, s72, v33
	s_nop 1
	v_cndmask_b32_e32 v33, v33, v49, vcc
	v_sqrt_f32_e32 v49, v33
	s_nop 0
	v_add_u32_e32 v50, -1, v49
	v_fma_f32 v77, -v50, v49, v33
	v_cmp_ge_f32_e64 s[0:1], 0, v77
	v_add_u32_e32 v77, 1, v49
	s_nop 0
	v_cndmask_b32_e64 v50, v49, v50, s[0:1]
	v_fma_f32 v49, -v77, v49, v33
	v_cmp_lt_f32_e64 s[0:1], 0, v49
	s_nop 1
	v_cndmask_b32_e64 v49, v50, v77, s[0:1]
	v_mul_f32_e32 v50, 0x37800000, v49
	v_cndmask_b32_e32 v49, v49, v50, vcc
	v_cmp_class_f32_e32 vcc, v33, v199
	s_nop 1
	v_cndmask_b32_e32 v33, v49, v33, vcc
	v_div_scale_f32 v49, s[0:1], v33, v33, 1.0
	v_rcp_f32_e32 v50, v49
	s_nop 0
	v_fma_f32 v1, -v49, v50, 1.0
	v_fmac_f32_e32 v50, v1, v50
	v_div_scale_f32 v1, vcc, 1.0, v33, 1.0
	v_mul_f32_e32 v77, v1, v50
	v_fma_f32 v78, -v49, v77, v1
	v_fmac_f32_e32 v77, v78, v50
	v_fma_f32 v1, -v49, v77, v1
	v_div_fmas_f32 v1, v1, v50, v77
	v_div_fixup_f32 v1, v1, v33, 1.0
	v_mul_f32_e32 v17, v17, v1
	v_mul_f32_e32 v17, v48, v17
	v_cvt_pk_bf16_f32 v17, v17, v133
	ds_write_b16 v218, v17 offset:512
	v_mul_f32_e32 v17, v34, v1
	v_mul_f32_e32 v17, v76, v17
	v_cvt_pk_bf16_f32 v17, v17, v133
	ds_write_b16 v217, v17 offset:512
	v_mul_f32_e32 v17, v18, v1
	v_mul_f32_e32 v1, v2, v1
	v_mul_f32_e32 v17, v16, v17
	v_mul_f32_e32 v1, v0, v1
	v_cvt_pk_bf16_f32 v17, v17, v133
	ds_write_b16 v218, v17 offset:640
	v_cvt_pk_bf16_f32 v1, v1, v133
	ds_read_u16 v2, v215 offset:768
	v_rcp_f32_e32 v17, v79
	ds_read_u16 v18, v216 offset:768
	ds_read_u16 v33, v216 offset:896
	ds_read_u16 v34, v215 offset:896
	v_mul_f32_e32 v49, v210, v51
	ds_write_b16 v217, v1 offset:640
	s_waitcnt lgkmcnt(3)
	v_lshlrev_b32_e32 v18, 16, v18
	v_lshlrev_b32_e32 v2, 16, v2
	v_fma_f32 v18, -v35, v17, v18
	v_fma_f32 v2, -v49, v17, v2
	v_mul_f32_e32 v35, v18, v18
	s_waitcnt lgkmcnt(1)
	v_lshlrev_b32_e32 v34, 16, v34
	v_fmac_f32_e32 v35, v2, v2
	v_fma_f32 v19, -v19, v17, v34
	v_lshlrev_b32_e32 v33, 16, v33
	v_fmac_f32_e32 v35, v19, v19
	v_fma_f32 v3, -v3, v17, v33
	v_fmac_f32_e32 v35, v3, v3
	s_nop 1
	s_waitcnt lgkmcnt(0)
	v_add_f32_dpp v17, v35, v35 quad_perm:[1,0,3,2] row_mask:0xf bank_mask:0xf
	s_nop 1
	s_waitcnt lgkmcnt(0)
	v_add_f32_dpp v17, v17, v17 quad_perm:[2,3,0,1] row_mask:0xf bank_mask:0xf
	s_nop 1
	s_waitcnt lgkmcnt(0)
	v_add_f32_dpp v17, v17, v17 row_half_mirror row_mask:0xf bank_mask:0xf
	s_nop 1
	s_waitcnt lgkmcnt(0)
	v_add_f32_dpp v17, v17, v17 row_mirror row_mask:0xf bank_mask:0xf
	v_mov_b32_e32 v33, v17
	s_waitcnt lgkmcnt(0)
	s_nop 0
	v_permlane16_swap_b32_e32 v17, v33
	v_add_f32_e32 v17, v17, v33
	v_fmamk_f32 v17, v17, 0x3c000000, v198
	v_mul_f32_e32 v33, 0x4f800000, v17
	v_cmp_gt_f32_e32 vcc, s72, v17
	s_nop 1
	v_cndmask_b32_e32 v17, v17, v33, vcc
	v_sqrt_f32_e32 v33, v17
	s_nop 0
	v_add_u32_e32 v34, -1, v33
	v_fma_f32 v35, -v34, v33, v17
	v_cmp_ge_f32_e64 s[0:1], 0, v35
	v_add_u32_e32 v35, 1, v33
	s_nop 0
	v_cndmask_b32_e64 v34, v33, v34, s[0:1]
	v_fma_f32 v33, -v35, v33, v17
	v_cmp_lt_f32_e64 s[0:1], 0, v33
	s_nop 1
	v_cndmask_b32_e64 v33, v34, v35, s[0:1]
	v_mul_f32_e32 v34, 0x37800000, v33
	v_cndmask_b32_e32 v33, v33, v34, vcc
	v_cmp_class_f32_e32 vcc, v17, v199
	s_nop 1
	v_cndmask_b32_e32 v17, v33, v17, vcc
	v_div_scale_f32 v33, s[0:1], v17, v17, 1.0
	v_rcp_f32_e32 v34, v33
	s_nop 0
	v_fma_f32 v1, -v33, v34, 1.0
	v_fmac_f32_e32 v34, v1, v34
	v_div_scale_f32 v1, vcc, 1.0, v17, 1.0
	v_mul_f32_e32 v35, v1, v34
	v_fma_f32 v49, -v33, v35, v1
	v_fmac_f32_e32 v35, v49, v34
	v_fma_f32 v1, -v33, v35, v1
	v_div_fmas_f32 v1, v1, v34, v35
	v_div_fixup_f32 v1, v1, v17, 1.0
	v_mul_f32_e32 v2, v2, v1
	v_mul_f32_e32 v2, v48, v2
	v_cvt_pk_bf16_f32 v2, v2, v133
	ds_write_b16 v215, v2 offset:768
	v_mul_f32_e32 v2, v18, v1
	v_mul_f32_e32 v2, v76, v2
	v_cvt_pk_bf16_f32 v2, v2, v133
	ds_write_b16 v216, v2 offset:768
	v_mul_f32_e32 v2, v19, v1
	v_mul_f32_e32 v2, v16, v2
	v_mul_f32_e32 v1, v3, v1
	v_cvt_pk_bf16_f32 v2, v2, v133
	v_mul_f32_e32 v1, v0, v1
	ds_write_b16 v215, v2 offset:896
	v_cvt_pk_bf16_f32 v1, v1, v133
	ds_read_u16 v2, v222 offset:2176
	v_rcp_f32_e32 v3, v72
	ds_read_u16 v17, v221 offset:2176
	ds_read_u16 v18, v221 offset:2048
	ds_read_u16 v19, v222 offset:2048
	v_mul_f32_e32 v33, v210, v52
	ds_write_b16 v216, v1 offset:896
	s_waitcnt lgkmcnt(4)
	v_lshlrev_b32_e32 v2, 16, v2
	v_fma_f32 v2, -v33, v3, v2
	s_waitcnt lgkmcnt(3)
	v_lshlrev_b32_e32 v17, 16, v17
	v_mul_f32_e32 v33, v210, v36
	v_fma_f32 v17, -v33, v3, v17
	v_mul_f32_e32 v33, v17, v17
	s_waitcnt lgkmcnt(1)
	v_lshlrev_b32_e32 v19, 16, v19
	v_fmac_f32_e32 v33, v2, v2
	v_fma_f32 v19, -v20, v3, v19
	v_lshlrev_b32_e32 v18, 16, v18
	v_fmac_f32_e32 v33, v19, v19
	v_fma_f32 v3, -v4, v3, v18
	v_fmac_f32_e32 v33, v3, v3
	s_nop 1
	s_waitcnt lgkmcnt(0)
	v_add_f32_dpp v4, v33, v33 quad_perm:[1,0,3,2] row_mask:0xf bank_mask:0xf
	s_nop 1
	s_waitcnt lgkmcnt(0)
	v_add_f32_dpp v4, v4, v4 quad_perm:[2,3,0,1] row_mask:0xf bank_mask:0xf
	s_nop 1
	s_waitcnt lgkmcnt(0)
	v_add_f32_dpp v4, v4, v4 row_half_mirror row_mask:0xf bank_mask:0xf
	s_nop 1
	s_waitcnt lgkmcnt(0)
	v_add_f32_dpp v4, v4, v4 row_mirror row_mask:0xf bank_mask:0xf
	v_mov_b32_e32 v18, v4
	s_waitcnt lgkmcnt(0)
	s_nop 0
	v_permlane16_swap_b32_e32 v4, v18
	v_add_f32_e32 v4, v4, v18
	v_fmamk_f32 v4, v4, 0x3c000000, v198
	v_mul_f32_e32 v18, 0x4f800000, v4
	v_cmp_gt_f32_e32 vcc, s72, v4
	s_nop 1
	v_cndmask_b32_e32 v4, v4, v18, vcc
	v_sqrt_f32_e32 v18, v4
	s_nop 0
	v_add_u32_e32 v20, -1, v18
	v_fma_f32 v33, -v20, v18, v4
	v_cmp_ge_f32_e64 s[0:1], 0, v33
	v_add_u32_e32 v33, 1, v18
	s_nop 0
	v_cndmask_b32_e64 v20, v18, v20, s[0:1]
	v_fma_f32 v18, -v33, v18, v4
	v_cmp_lt_f32_e64 s[0:1], 0, v18
	s_nop 1
	v_cndmask_b32_e64 v18, v20, v33, s[0:1]
	v_mul_f32_e32 v20, 0x37800000, v18
	v_cndmask_b32_e32 v18, v18, v20, vcc
	v_cmp_class_f32_e32 vcc, v4, v199
	s_nop 1
	v_cndmask_b32_e32 v4, v18, v4, vcc
	v_div_scale_f32 v18, s[0:1], v4, v4, 1.0
	v_rcp_f32_e32 v20, v18
	s_nop 0
	v_fma_f32 v1, -v18, v20, 1.0
	v_fmac_f32_e32 v20, v1, v20
	v_div_scale_f32 v1, vcc, 1.0, v4, 1.0
	v_mul_f32_e32 v33, v1, v20
	v_fma_f32 v34, -v18, v33, v1
	v_fmac_f32_e32 v33, v34, v20
	v_fma_f32 v1, -v18, v33, v1
	v_div_fmas_f32 v1, v1, v20, v33
	v_div_fixup_f32 v1, v1, v4, 1.0
	v_mul_f32_e32 v2, v2, v1
	v_mul_f32_e32 v2, v48, v2
	v_cvt_pk_bf16_f32 v2, v2, v133
	ds_write_b16 v222, v2 offset:2176
	v_mul_f32_e32 v2, v17, v1
	v_mul_f32_e32 v2, v76, v2
	v_cvt_pk_bf16_f32 v2, v2, v133
	ds_write_b16 v221, v2 offset:2176
	v_mul_f32_e32 v2, v19, v1
	v_mul_f32_e32 v2, v16, v2
	v_mul_f32_e32 v1, v3, v1
	v_cvt_pk_bf16_f32 v2, v2, v133
	v_mul_f32_e32 v1, v0, v1
	ds_write_b16 v222, v2 offset:2048
	v_cvt_pk_bf16_f32 v1, v1, v133
	ds_read_u16 v2, v220 offset:2432
	v_rcp_f32_e32 v3, v73
	ds_read_u16 v4, v219 offset:2432
	ds_read_u16 v17, v219 offset:2304
	ds_read_u16 v18, v220 offset:2304
	v_mul_f32_e32 v19, v210, v53
	v_mul_f32_e32 v20, v210, v21
	s_waitcnt lgkmcnt(3)
	v_lshlrev_b32_e32 v2, 16, v2
	v_fma_f32 v2, -v19, v3, v2
	s_waitcnt lgkmcnt(2)
	v_lshlrev_b32_e32 v4, 16, v4
	v_mul_f32_e32 v19, v210, v37
	v_fma_f32 v4, -v19, v3, v4
	v_mul_f32_e32 v19, v4, v4
	s_waitcnt lgkmcnt(0)
	v_lshlrev_b32_e32 v18, 16, v18
	v_fmac_f32_e32 v19, v2, v2
	v_fma_f32 v18, -v20, v3, v18
	v_lshlrev_b32_e32 v17, 16, v17
	v_fmac_f32_e32 v19, v18, v18
	v_fma_f32 v3, -v5, v3, v17
	v_fmac_f32_e32 v19, v3, v3
	s_nop 1
	ds_write_b16 v221, v1 offset:2048
	s_waitcnt lgkmcnt(1)
	v_add_f32_dpp v5, v19, v19 quad_perm:[1,0,3,2] row_mask:0xf bank_mask:0xf
	s_nop 1
	s_waitcnt lgkmcnt(0)
	v_add_f32_dpp v5, v5, v5 quad_perm:[2,3,0,1] row_mask:0xf bank_mask:0xf
	s_nop 1
	s_waitcnt lgkmcnt(0)
	v_add_f32_dpp v5, v5, v5 row_half_mirror row_mask:0xf bank_mask:0xf
	s_nop 1
	s_waitcnt lgkmcnt(0)
	v_add_f32_dpp v5, v5, v5 row_mirror row_mask:0xf bank_mask:0xf
	v_mov_b32_e32 v17, v5
	s_waitcnt lgkmcnt(0)
	s_nop 0
	v_permlane16_swap_b32_e32 v5, v17
	v_add_f32_e32 v5, v5, v17
	v_fmamk_f32 v5, v5, 0x3c000000, v198
	v_mul_f32_e32 v17, 0x4f800000, v5
	v_cmp_gt_f32_e32 vcc, s72, v5
	s_nop 1
	v_cndmask_b32_e32 v5, v5, v17, vcc
	v_sqrt_f32_e32 v17, v5
	s_nop 0
	v_add_u32_e32 v19, -1, v17
	v_fma_f32 v20, -v19, v17, v5
	v_cmp_ge_f32_e64 s[0:1], 0, v20
	v_add_u32_e32 v20, 1, v17
	s_nop 0
	v_cndmask_b32_e64 v19, v17, v19, s[0:1]
	v_fma_f32 v17, -v20, v17, v5
	v_cmp_lt_f32_e64 s[0:1], 0, v17
	s_nop 1
	v_cndmask_b32_e64 v17, v19, v20, s[0:1]
	v_mul_f32_e32 v19, 0x37800000, v17
	v_cndmask_b32_e32 v17, v17, v19, vcc
	v_cmp_class_f32_e32 vcc, v5, v199
	s_nop 1
	v_cndmask_b32_e32 v5, v17, v5, vcc
	v_div_scale_f32 v17, s[0:1], v5, v5, 1.0
	v_rcp_f32_e32 v19, v17
	s_nop 0
	v_fma_f32 v1, -v17, v19, 1.0
	v_fmac_f32_e32 v19, v1, v19
	v_div_scale_f32 v1, vcc, 1.0, v5, 1.0
	v_mul_f32_e32 v20, v1, v19
	v_fma_f32 v21, -v17, v20, v1
	v_fmac_f32_e32 v20, v21, v19
	v_fma_f32 v1, -v17, v20, v1
	v_div_fmas_f32 v1, v1, v19, v20
	v_div_fixup_f32 v1, v1, v5, 1.0
	v_mul_f32_e32 v2, v2, v1
	v_mul_f32_e32 v2, v48, v2
	v_cvt_pk_bf16_f32 v2, v2, v133
	ds_write_b16 v220, v2 offset:2432
	v_mul_f32_e32 v2, v4, v1
	v_mul_f32_e32 v2, v76, v2
	v_cvt_pk_bf16_f32 v2, v2, v133
	ds_write_b16 v219, v2 offset:2432
	v_mul_f32_e32 v2, v18, v1
	v_mul_f32_e32 v2, v16, v2
	v_mul_f32_e32 v1, v3, v1
	v_cvt_pk_bf16_f32 v2, v2, v133
	v_mul_f32_e32 v1, v0, v1
	ds_write_b16 v220, v2 offset:2304
	v_cvt_pk_bf16_f32 v1, v1, v133
	ds_read_u16 v2, v218 offset:2688
	v_rcp_f32_e32 v3, v74
	ds_read_u16 v4, v217 offset:2688
	ds_read_u16 v5, v217 offset:2560
	ds_read_u16 v17, v218 offset:2560
	v_mul_f32_e32 v18, v210, v54
	v_mul_f32_e32 v19, v210, v22
	s_waitcnt lgkmcnt(3)
	v_lshlrev_b32_e32 v2, 16, v2
	v_fma_f32 v2, -v18, v3, v2
	s_waitcnt lgkmcnt(2)
	v_lshlrev_b32_e32 v4, 16, v4
	v_mul_f32_e32 v18, v210, v38
	v_fma_f32 v4, -v18, v3, v4
	v_mul_f32_e32 v18, v4, v4
	s_waitcnt lgkmcnt(0)
	v_lshlrev_b32_e32 v17, 16, v17
	v_fmac_f32_e32 v18, v2, v2
	v_fma_f32 v17, -v19, v3, v17
	v_lshlrev_b32_e32 v5, 16, v5
	v_fmac_f32_e32 v18, v17, v17
	v_fma_f32 v3, -v6, v3, v5
	v_fmac_f32_e32 v18, v3, v3
	s_nop 1
	ds_write_b16 v219, v1 offset:2304
	s_waitcnt lgkmcnt(1)
	v_add_f32_dpp v5, v18, v18 quad_perm:[1,0,3,2] row_mask:0xf bank_mask:0xf
	s_nop 1
	s_waitcnt lgkmcnt(0)
	v_add_f32_dpp v5, v5, v5 quad_perm:[2,3,0,1] row_mask:0xf bank_mask:0xf
	s_nop 1
	s_waitcnt lgkmcnt(0)
	v_add_f32_dpp v5, v5, v5 row_half_mirror row_mask:0xf bank_mask:0xf
	s_nop 1
	s_waitcnt lgkmcnt(0)
	v_add_f32_dpp v5, v5, v5 row_mirror row_mask:0xf bank_mask:0xf
	v_mov_b32_e32 v6, v5
	s_waitcnt lgkmcnt(0)
	s_nop 0
	v_permlane16_swap_b32_e32 v5, v6
	v_add_f32_e32 v5, v5, v6
	v_fmamk_f32 v5, v5, 0x3c000000, v198
	v_mul_f32_e32 v6, 0x4f800000, v5
	v_cmp_gt_f32_e32 vcc, s72, v5
	s_nop 1
	v_cndmask_b32_e32 v5, v5, v6, vcc
	v_sqrt_f32_e32 v6, v5
	s_nop 0
	v_add_u32_e32 v18, -1, v6
	v_fma_f32 v19, -v18, v6, v5
	v_cmp_ge_f32_e64 s[0:1], 0, v19
	v_add_u32_e32 v19, 1, v6
	s_nop 0
	v_cndmask_b32_e64 v18, v6, v18, s[0:1]
	v_fma_f32 v6, -v19, v6, v5
	v_cmp_lt_f32_e64 s[0:1], 0, v6
	s_nop 1
	v_cndmask_b32_e64 v6, v18, v19, s[0:1]
	v_mul_f32_e32 v18, 0x37800000, v6
	v_cndmask_b32_e32 v6, v6, v18, vcc
	v_cmp_class_f32_e32 vcc, v5, v199
	s_nop 1
	v_cndmask_b32_e32 v5, v6, v5, vcc
	v_div_scale_f32 v6, s[0:1], v5, v5, 1.0
	v_rcp_f32_e32 v18, v6
	s_nop 0
	v_fma_f32 v1, -v6, v18, 1.0
	v_fmac_f32_e32 v18, v1, v18
	v_div_scale_f32 v1, vcc, 1.0, v5, 1.0
	v_mul_f32_e32 v19, v1, v18
	v_fma_f32 v20, -v6, v19, v1
	v_fmac_f32_e32 v19, v20, v18
	v_fma_f32 v1, -v6, v19, v1
	v_div_fmas_f32 v1, v1, v18, v19
	v_div_fixup_f32 v1, v1, v5, 1.0
	v_mul_f32_e32 v2, v2, v1
	v_mul_f32_e32 v2, v48, v2
	v_cvt_pk_bf16_f32 v2, v2, v133
	ds_write_b16 v218, v2 offset:2688
	v_mul_f32_e32 v2, v4, v1
	v_mul_f32_e32 v2, v76, v2
	v_cvt_pk_bf16_f32 v2, v2, v133
	ds_write_b16 v217, v2 offset:2688
	v_mul_f32_e32 v2, v17, v1
	v_mul_f32_e32 v2, v16, v2
	v_mul_f32_e32 v1, v3, v1
	v_cvt_pk_bf16_f32 v2, v2, v133
	v_mul_f32_e32 v1, v0, v1
	ds_write_b16 v218, v2 offset:2560
	v_cvt_pk_bf16_f32 v1, v1, v133
	ds_read_u16 v2, v215 offset:2944
	v_rcp_f32_e32 v3, v75
	ds_read_u16 v4, v216 offset:2944
	ds_read_u16 v5, v216 offset:2816
	ds_read_u16 v6, v215 offset:2816
	v_mul_f32_e32 v17, v210, v55
	v_mul_f32_e32 v18, v210, v23
	s_waitcnt lgkmcnt(3)
	v_lshlrev_b32_e32 v2, 16, v2
	v_fma_f32 v2, -v17, v3, v2
	s_waitcnt lgkmcnt(2)
	v_lshlrev_b32_e32 v4, 16, v4
	v_mul_f32_e32 v17, v210, v39
	v_fma_f32 v4, -v17, v3, v4
	v_mul_f32_e32 v17, v4, v4
	s_waitcnt lgkmcnt(0)
	v_lshlrev_b32_e32 v6, 16, v6
	v_fmac_f32_e32 v17, v2, v2
	v_fma_f32 v6, -v18, v3, v6
	v_lshlrev_b32_e32 v5, 16, v5
	v_fmac_f32_e32 v17, v6, v6
	v_fma_f32 v3, -v7, v3, v5
	v_fmac_f32_e32 v17, v3, v3
	s_nop 1
	ds_write_b16 v217, v1 offset:2560
	s_waitcnt lgkmcnt(1)
	v_add_f32_dpp v5, v17, v17 quad_perm:[1,0,3,2] row_mask:0xf bank_mask:0xf
	s_nop 1
	s_waitcnt lgkmcnt(0)
	v_add_f32_dpp v5, v5, v5 quad_perm:[2,3,0,1] row_mask:0xf bank_mask:0xf
	s_nop 1
	s_waitcnt lgkmcnt(0)
	v_add_f32_dpp v5, v5, v5 row_half_mirror row_mask:0xf bank_mask:0xf
	s_nop 1
	s_waitcnt lgkmcnt(0)
	v_add_f32_dpp v5, v5, v5 row_mirror row_mask:0xf bank_mask:0xf
	v_mov_b32_e32 v7, v5
	s_waitcnt lgkmcnt(0)
	s_nop 0
	v_permlane16_swap_b32_e32 v5, v7
	v_add_f32_e32 v5, v5, v7
	v_fmamk_f32 v5, v5, 0x3c000000, v198
	v_mul_f32_e32 v7, 0x4f800000, v5
	v_cmp_gt_f32_e32 vcc, s72, v5
	s_nop 1
	v_cndmask_b32_e32 v5, v5, v7, vcc
	v_sqrt_f32_e32 v7, v5
	s_nop 0
	v_add_u32_e32 v17, -1, v7
	v_fma_f32 v18, -v17, v7, v5
	v_cmp_ge_f32_e64 s[0:1], 0, v18
	v_add_u32_e32 v18, 1, v7
	s_nop 0
	v_cndmask_b32_e64 v17, v7, v17, s[0:1]
	v_fma_f32 v7, -v18, v7, v5
	v_cmp_lt_f32_e64 s[0:1], 0, v7
	s_nop 1
	v_cndmask_b32_e64 v7, v17, v18, s[0:1]
	v_mul_f32_e32 v17, 0x37800000, v7
	v_cndmask_b32_e32 v7, v7, v17, vcc
	v_cmp_class_f32_e32 vcc, v5, v199
	s_nop 1
	v_cndmask_b32_e32 v5, v7, v5, vcc
	v_div_scale_f32 v7, s[0:1], v5, v5, 1.0
	v_rcp_f32_e32 v17, v7
	s_nop 0
	v_fma_f32 v1, -v7, v17, 1.0
	v_fmac_f32_e32 v17, v1, v17
	v_div_scale_f32 v1, vcc, 1.0, v5, 1.0
	v_mul_f32_e32 v18, v1, v17
	v_fma_f32 v19, -v7, v18, v1
	v_fmac_f32_e32 v18, v19, v17
	v_fma_f32 v1, -v7, v18, v1
	v_div_fmas_f32 v1, v1, v17, v18
	v_div_fixup_f32 v1, v1, v5, 1.0
	v_mul_f32_e32 v2, v2, v1
	v_mul_f32_e32 v2, v48, v2
	v_cvt_pk_bf16_f32 v2, v2, v133
	ds_write_b16 v215, v2 offset:2944
	v_mul_f32_e32 v2, v4, v1
	v_mul_f32_e32 v2, v76, v2
	v_cvt_pk_bf16_f32 v2, v2, v133
	ds_write_b16 v216, v2 offset:2944
	v_mul_f32_e32 v2, v6, v1
	v_mul_f32_e32 v2, v16, v2
	v_mul_f32_e32 v1, v3, v1
	v_cvt_pk_bf16_f32 v2, v2, v133
	v_mul_f32_e32 v1, v0, v1
	ds_write_b16 v215, v2 offset:2816
	v_cvt_pk_bf16_f32 v1, v1, v133
	ds_read_u16 v2, v222 offset:4096
	v_rcp_f32_e32 v3, v68
	ds_read_u16 v4, v221 offset:4096
	ds_read_u16 v5, v221 offset:4224
	ds_read_u16 v6, v222 offset:4224
	v_mul_f32_e32 v7, v210, v56
	v_mul_f32_e32 v17, v210, v24
	s_waitcnt lgkmcnt(3)
	v_lshlrev_b32_e32 v2, 16, v2
	v_fma_f32 v2, -v7, v3, v2
	s_waitcnt lgkmcnt(2)
	v_lshlrev_b32_e32 v4, 16, v4
	v_mul_f32_e32 v7, v210, v40
	v_fma_f32 v4, -v7, v3, v4
	v_mul_f32_e32 v7, v4, v4
	s_waitcnt lgkmcnt(0)
	v_lshlrev_b32_e32 v6, 16, v6
	v_fmac_f32_e32 v7, v2, v2
	v_fma_f32 v6, -v17, v3, v6
	v_lshlrev_b32_e32 v5, 16, v5
	v_fmac_f32_e32 v7, v6, v6
	v_fma_f32 v3, -v8, v3, v5
	v_fmac_f32_e32 v7, v3, v3
	s_nop 1
	ds_write_b16 v216, v1 offset:2816
	s_waitcnt lgkmcnt(1)
	v_add_f32_dpp v5, v7, v7 quad_perm:[1,0,3,2] row_mask:0xf bank_mask:0xf
	s_nop 1
	s_waitcnt lgkmcnt(0)
	v_add_f32_dpp v5, v5, v5 quad_perm:[2,3,0,1] row_mask:0xf bank_mask:0xf
	s_nop 1
	s_waitcnt lgkmcnt(0)
	v_add_f32_dpp v5, v5, v5 row_half_mirror row_mask:0xf bank_mask:0xf
	s_nop 1
	s_waitcnt lgkmcnt(0)
	v_add_f32_dpp v5, v5, v5 row_mirror row_mask:0xf bank_mask:0xf
	v_mov_b32_e32 v7, v5
	s_waitcnt lgkmcnt(0)
	s_nop 0
	v_permlane16_swap_b32_e32 v5, v7
	v_add_f32_e32 v5, v5, v7
	v_fmamk_f32 v5, v5, 0x3c000000, v198
	v_mul_f32_e32 v7, 0x4f800000, v5
	v_cmp_gt_f32_e32 vcc, s72, v5
	s_nop 1
	v_cndmask_b32_e32 v5, v5, v7, vcc
	v_sqrt_f32_e32 v7, v5
	s_nop 0
	v_add_u32_e32 v8, -1, v7
	v_fma_f32 v17, -v8, v7, v5
	v_cmp_ge_f32_e64 s[0:1], 0, v17
	v_add_u32_e32 v17, 1, v7
	s_nop 0
	v_cndmask_b32_e64 v8, v7, v8, s[0:1]
	v_fma_f32 v7, -v17, v7, v5
	v_cmp_lt_f32_e64 s[0:1], 0, v7
	s_nop 1
	v_cndmask_b32_e64 v7, v8, v17, s[0:1]
	v_mul_f32_e32 v8, 0x37800000, v7
	v_cndmask_b32_e32 v7, v7, v8, vcc
	v_cmp_class_f32_e32 vcc, v5, v199
	s_nop 1
	v_cndmask_b32_e32 v5, v7, v5, vcc
	v_div_scale_f32 v7, s[0:1], v5, v5, 1.0
	v_rcp_f32_e32 v8, v7
	s_nop 0
	v_fma_f32 v1, -v7, v8, 1.0
	v_fmac_f32_e32 v8, v1, v8
	v_div_scale_f32 v1, vcc, 1.0, v5, 1.0
	v_mul_f32_e32 v17, v1, v8
	v_fma_f32 v18, -v7, v17, v1
	v_fmac_f32_e32 v17, v18, v8
	v_fma_f32 v1, -v7, v17, v1
	v_div_fmas_f32 v1, v1, v8, v17
	v_div_fixup_f32 v1, v1, v5, 1.0
	v_mul_f32_e32 v2, v2, v1
	v_mul_f32_e32 v2, v48, v2
	v_cvt_pk_bf16_f32 v2, v2, v133
	ds_write_b16 v222, v2 offset:4096
	v_mul_f32_e32 v2, v4, v1
	v_mul_f32_e32 v2, v76, v2
	v_cvt_pk_bf16_f32 v2, v2, v133
	ds_write_b16 v221, v2 offset:4096
	v_mul_f32_e32 v2, v6, v1
	v_mul_f32_e32 v2, v16, v2
	v_mul_f32_e32 v1, v3, v1
	v_cvt_pk_bf16_f32 v2, v2, v133
	v_mul_f32_e32 v1, v0, v1
	ds_write_b16 v222, v2 offset:4224
	v_cvt_pk_bf16_f32 v1, v1, v133
	ds_read_u16 v2, v220 offset:4352
	v_rcp_f32_e32 v3, v69
	ds_read_u16 v4, v219 offset:4352
	ds_read_u16 v5, v219 offset:4480
	ds_read_u16 v6, v220 offset:4480
	v_mul_f32_e32 v7, v210, v57
	v_mul_f32_e32 v8, v210, v25
	s_waitcnt lgkmcnt(3)
	v_lshlrev_b32_e32 v2, 16, v2
	v_fma_f32 v2, -v7, v3, v2
	s_waitcnt lgkmcnt(2)
	v_lshlrev_b32_e32 v4, 16, v4
	v_mul_f32_e32 v7, v210, v41
	v_fma_f32 v4, -v7, v3, v4
	v_mul_f32_e32 v7, v4, v4
	s_waitcnt lgkmcnt(0)
	v_lshlrev_b32_e32 v6, 16, v6
	v_fmac_f32_e32 v7, v2, v2
	v_fma_f32 v6, -v8, v3, v6
	v_lshlrev_b32_e32 v5, 16, v5
	v_mul_f32_e32 v8, v210, v9
	v_fmac_f32_e32 v7, v6, v6
	v_fma_f32 v3, -v8, v3, v5
	v_fmac_f32_e32 v7, v3, v3
	s_nop 1
	ds_write_b16 v221, v1 offset:4224
	s_waitcnt lgkmcnt(1)
	v_add_f32_dpp v5, v7, v7 quad_perm:[1,0,3,2] row_mask:0xf bank_mask:0xf
	s_nop 1
	s_waitcnt lgkmcnt(0)
	v_add_f32_dpp v5, v5, v5 quad_perm:[2,3,0,1] row_mask:0xf bank_mask:0xf
	s_nop 1
	s_waitcnt lgkmcnt(0)
	v_add_f32_dpp v5, v5, v5 row_half_mirror row_mask:0xf bank_mask:0xf
	s_nop 1
	s_waitcnt lgkmcnt(0)
	v_add_f32_dpp v5, v5, v5 row_mirror row_mask:0xf bank_mask:0xf
	v_mov_b32_e32 v7, v5
	s_waitcnt lgkmcnt(0)
	s_nop 0
	v_permlane16_swap_b32_e32 v5, v7
	v_add_f32_e32 v5, v5, v7
	v_fmamk_f32 v5, v5, 0x3c000000, v198
	v_mul_f32_e32 v7, 0x4f800000, v5
	v_cmp_gt_f32_e32 vcc, s72, v5
	s_nop 1
	v_cndmask_b32_e32 v5, v5, v7, vcc
	v_sqrt_f32_e32 v7, v5
	s_nop 0
	v_add_u32_e32 v8, -1, v7
	v_fma_f32 v9, -v8, v7, v5
	v_cmp_ge_f32_e64 s[0:1], 0, v9
	v_add_u32_e32 v9, 1, v7
	s_nop 0
	v_cndmask_b32_e64 v8, v7, v8, s[0:1]
	v_fma_f32 v7, -v9, v7, v5
	v_cmp_lt_f32_e64 s[0:1], 0, v7
	s_nop 1
	v_cndmask_b32_e64 v7, v8, v9, s[0:1]
	v_mul_f32_e32 v8, 0x37800000, v7
	v_cndmask_b32_e32 v7, v7, v8, vcc
	v_cmp_class_f32_e32 vcc, v5, v199
	s_nop 1
	v_cndmask_b32_e32 v5, v7, v5, vcc
	v_div_scale_f32 v7, s[0:1], v5, v5, 1.0
	v_rcp_f32_e32 v8, v7
	s_nop 0
	v_fma_f32 v1, -v7, v8, 1.0
	v_fmac_f32_e32 v8, v1, v8
	v_div_scale_f32 v1, vcc, 1.0, v5, 1.0
	v_mul_f32_e32 v9, v1, v8
	v_fma_f32 v17, -v7, v9, v1
	v_fmac_f32_e32 v9, v17, v8
	v_fma_f32 v1, -v7, v9, v1
	v_div_fmas_f32 v1, v1, v8, v9
	v_div_fixup_f32 v1, v1, v5, 1.0
	v_mul_f32_e32 v2, v2, v1
	v_mul_f32_e32 v2, v48, v2
	v_cvt_pk_bf16_f32 v2, v2, v133
	ds_write_b16 v220, v2 offset:4352
	v_mul_f32_e32 v2, v4, v1
	v_mul_f32_e32 v2, v76, v2
	v_cvt_pk_bf16_f32 v2, v2, v133
	ds_write_b16 v219, v2 offset:4352
	v_mul_f32_e32 v2, v6, v1
	v_mul_f32_e32 v2, v16, v2
	v_mul_f32_e32 v1, v3, v1
	v_cvt_pk_bf16_f32 v2, v2, v133
	v_mul_f32_e32 v1, v0, v1
	ds_write_b16 v220, v2 offset:4480
	v_cvt_pk_bf16_f32 v1, v1, v133
	ds_read_u16 v2, v218 offset:4608
	v_rcp_f32_e32 v3, v70
	ds_read_u16 v4, v217 offset:4608
	ds_read_u16 v5, v217 offset:4736
	ds_read_u16 v6, v218 offset:4736
	v_mul_f32_e32 v7, v210, v58
	v_mul_f32_e32 v8, v210, v26
	s_waitcnt lgkmcnt(3)
	v_lshlrev_b32_e32 v2, 16, v2
	v_fma_f32 v2, -v7, v3, v2
	s_waitcnt lgkmcnt(2)
	v_lshlrev_b32_e32 v4, 16, v4
	v_mul_f32_e32 v7, v210, v42
	v_fma_f32 v4, -v7, v3, v4
	v_mul_f32_e32 v7, v4, v4
	s_waitcnt lgkmcnt(0)
	v_lshlrev_b32_e32 v6, 16, v6
	v_fmac_f32_e32 v7, v2, v2
	v_fma_f32 v6, -v8, v3, v6
	v_lshlrev_b32_e32 v5, 16, v5
	v_mul_f32_e32 v8, v210, v10
	v_fmac_f32_e32 v7, v6, v6
	v_fma_f32 v3, -v8, v3, v5
	v_fmac_f32_e32 v7, v3, v3
	s_nop 1
	ds_write_b16 v219, v1 offset:4480
	s_waitcnt lgkmcnt(1)
	v_add_f32_dpp v5, v7, v7 quad_perm:[1,0,3,2] row_mask:0xf bank_mask:0xf
	s_nop 1
	s_waitcnt lgkmcnt(0)
	v_add_f32_dpp v5, v5, v5 quad_perm:[2,3,0,1] row_mask:0xf bank_mask:0xf
	s_nop 1
	s_waitcnt lgkmcnt(0)
	v_add_f32_dpp v5, v5, v5 row_half_mirror row_mask:0xf bank_mask:0xf
	s_nop 1
	s_waitcnt lgkmcnt(0)
	v_add_f32_dpp v5, v5, v5 row_mirror row_mask:0xf bank_mask:0xf
	v_mov_b32_e32 v7, v5
	s_waitcnt lgkmcnt(0)
	s_nop 0
	v_permlane16_swap_b32_e32 v5, v7
	v_add_f32_e32 v5, v5, v7
	v_fmamk_f32 v5, v5, 0x3c000000, v198
	v_mul_f32_e32 v7, 0x4f800000, v5
	v_cmp_gt_f32_e32 vcc, s72, v5
	s_nop 1
	v_cndmask_b32_e32 v5, v5, v7, vcc
	v_sqrt_f32_e32 v7, v5
	s_nop 0
	v_add_u32_e32 v8, -1, v7
	v_fma_f32 v9, -v8, v7, v5
	v_cmp_ge_f32_e64 s[0:1], 0, v9
	v_add_u32_e32 v9, 1, v7
	s_nop 0
	v_cndmask_b32_e64 v8, v7, v8, s[0:1]
	v_fma_f32 v7, -v9, v7, v5
	v_cmp_lt_f32_e64 s[0:1], 0, v7
	s_nop 1
	v_cndmask_b32_e64 v7, v8, v9, s[0:1]
	v_mul_f32_e32 v8, 0x37800000, v7
	v_cndmask_b32_e32 v7, v7, v8, vcc
	v_cmp_class_f32_e32 vcc, v5, v199
	s_nop 1
	v_cndmask_b32_e32 v5, v7, v5, vcc
	v_div_scale_f32 v7, s[0:1], v5, v5, 1.0
	v_rcp_f32_e32 v8, v7
	s_nop 0
	v_fma_f32 v1, -v7, v8, 1.0
	v_fmac_f32_e32 v8, v1, v8
	v_div_scale_f32 v1, vcc, 1.0, v5, 1.0
	v_mul_f32_e32 v9, v1, v8
	v_fma_f32 v10, -v7, v9, v1
	v_fmac_f32_e32 v9, v10, v8
	v_fma_f32 v1, -v7, v9, v1
	v_div_fmas_f32 v1, v1, v8, v9
	v_div_fixup_f32 v1, v1, v5, 1.0
	v_mul_f32_e32 v2, v2, v1
	v_mul_f32_e32 v2, v48, v2
	v_cvt_pk_bf16_f32 v2, v2, v133
	ds_write_b16 v218, v2 offset:4608
	v_mul_f32_e32 v2, v4, v1
	v_mul_f32_e32 v2, v76, v2
	v_cvt_pk_bf16_f32 v2, v2, v133
	ds_write_b16 v217, v2 offset:4608
	v_mul_f32_e32 v2, v6, v1
	v_mul_f32_e32 v2, v16, v2
	v_mul_f32_e32 v1, v3, v1
	v_cvt_pk_bf16_f32 v2, v2, v133
	v_mul_f32_e32 v1, v0, v1
	ds_write_b16 v218, v2 offset:4736
	v_cvt_pk_bf16_f32 v1, v1, v133
	ds_read_u16 v2, v215 offset:4864
	v_rcp_f32_e32 v3, v71
	ds_read_u16 v4, v216 offset:4864
	ds_read_u16 v5, v216 offset:4992
	ds_read_u16 v6, v215 offset:4992
	v_mul_f32_e32 v7, v210, v59
	v_mul_f32_e32 v8, v210, v27
	s_waitcnt lgkmcnt(3)
	v_lshlrev_b32_e32 v2, 16, v2
	v_fma_f32 v2, -v7, v3, v2
	s_waitcnt lgkmcnt(2)
	v_lshlrev_b32_e32 v4, 16, v4
	v_mul_f32_e32 v7, v210, v43
	v_fma_f32 v4, -v7, v3, v4
	v_mul_f32_e32 v7, v4, v4
	s_waitcnt lgkmcnt(0)
	v_lshlrev_b32_e32 v6, 16, v6
	v_fmac_f32_e32 v7, v2, v2
	v_fma_f32 v6, -v8, v3, v6
	v_lshlrev_b32_e32 v5, 16, v5
	v_mul_f32_e32 v8, v210, v11
	v_fmac_f32_e32 v7, v6, v6
	v_fma_f32 v3, -v8, v3, v5
	v_fmac_f32_e32 v7, v3, v3
	s_nop 1
	ds_write_b16 v217, v1 offset:4736
	s_waitcnt lgkmcnt(1)
	v_add_f32_dpp v5, v7, v7 quad_perm:[1,0,3,2] row_mask:0xf bank_mask:0xf
	s_nop 1
	s_waitcnt lgkmcnt(0)
	v_add_f32_dpp v5, v5, v5 quad_perm:[2,3,0,1] row_mask:0xf bank_mask:0xf
	s_nop 1
	s_waitcnt lgkmcnt(0)
	v_add_f32_dpp v5, v5, v5 row_half_mirror row_mask:0xf bank_mask:0xf
	s_nop 1
	s_waitcnt lgkmcnt(0)
	v_add_f32_dpp v5, v5, v5 row_mirror row_mask:0xf bank_mask:0xf
	v_mov_b32_e32 v7, v5
	s_waitcnt lgkmcnt(0)
	s_nop 0
	v_permlane16_swap_b32_e32 v5, v7
	v_add_f32_e32 v5, v5, v7
	v_fmamk_f32 v5, v5, 0x3c000000, v198
	v_mul_f32_e32 v7, 0x4f800000, v5
	v_cmp_gt_f32_e32 vcc, s72, v5
	s_nop 1
	v_cndmask_b32_e32 v5, v5, v7, vcc
	v_sqrt_f32_e32 v7, v5
	s_nop 0
	v_add_u32_e32 v8, -1, v7
	v_fma_f32 v9, -v8, v7, v5
	v_cmp_ge_f32_e64 s[0:1], 0, v9
	v_add_u32_e32 v9, 1, v7
	s_nop 0
	v_cndmask_b32_e64 v8, v7, v8, s[0:1]
	v_fma_f32 v7, -v9, v7, v5
	v_cmp_lt_f32_e64 s[0:1], 0, v7
	s_nop 1
	v_cndmask_b32_e64 v7, v8, v9, s[0:1]
	v_mul_f32_e32 v8, 0x37800000, v7
	v_cndmask_b32_e32 v7, v7, v8, vcc
	v_cmp_class_f32_e32 vcc, v5, v199
	s_nop 1
	v_cndmask_b32_e32 v5, v7, v5, vcc
	v_div_scale_f32 v7, s[0:1], v5, v5, 1.0
	v_rcp_f32_e32 v8, v7
	s_nop 0
	v_fma_f32 v1, -v7, v8, 1.0
	v_fmac_f32_e32 v8, v1, v8
	v_div_scale_f32 v1, vcc, 1.0, v5, 1.0
	v_mul_f32_e32 v9, v1, v8
	v_fma_f32 v10, -v7, v9, v1
	v_fmac_f32_e32 v9, v10, v8
	v_fma_f32 v1, -v7, v9, v1
	v_div_fmas_f32 v1, v1, v8, v9
	v_div_fixup_f32 v1, v1, v5, 1.0
	v_mul_f32_e32 v2, v2, v1
	v_mul_f32_e32 v2, v48, v2
	v_cvt_pk_bf16_f32 v2, v2, v133
	ds_write_b16 v215, v2 offset:4864
	v_mul_f32_e32 v2, v4, v1
	v_mul_f32_e32 v2, v76, v2
	v_cvt_pk_bf16_f32 v2, v2, v133
	ds_write_b16 v216, v2 offset:4864
	v_mul_f32_e32 v2, v6, v1
	v_mul_f32_e32 v2, v16, v2
	v_mul_f32_e32 v1, v3, v1
	v_cvt_pk_bf16_f32 v2, v2, v133
	v_mul_f32_e32 v1, v0, v1
	ds_write_b16 v215, v2 offset:4992
	v_cvt_pk_bf16_f32 v1, v1, v133
	ds_read_u16 v2, v222 offset:6272
	v_rcp_f32_e32 v3, v64
	ds_read_u16 v4, v221 offset:6272
	ds_read_u16 v5, v221 offset:6144
	ds_read_u16 v6, v222 offset:6144
	v_mul_f32_e32 v7, v210, v60
	v_mul_f32_e32 v8, v210, v28
	s_waitcnt lgkmcnt(3)
	v_lshlrev_b32_e32 v2, 16, v2
	v_fma_f32 v2, -v7, v3, v2
	s_waitcnt lgkmcnt(2)
	v_lshlrev_b32_e32 v4, 16, v4
	v_mul_f32_e32 v7, v210, v44
	v_fma_f32 v4, -v7, v3, v4
	v_mul_f32_e32 v7, v4, v4
	s_waitcnt lgkmcnt(0)
	v_lshlrev_b32_e32 v6, 16, v6
	v_fmac_f32_e32 v7, v2, v2
	v_fma_f32 v6, -v8, v3, v6
	v_lshlrev_b32_e32 v5, 16, v5
	v_mul_f32_e32 v8, v210, v12
	v_fmac_f32_e32 v7, v6, v6
	v_fma_f32 v3, -v8, v3, v5
	v_fmac_f32_e32 v7, v3, v3
	s_nop 1
	ds_write_b16 v216, v1 offset:4992
	s_waitcnt lgkmcnt(1)
	v_add_f32_dpp v5, v7, v7 quad_perm:[1,0,3,2] row_mask:0xf bank_mask:0xf
	s_nop 1
	s_waitcnt lgkmcnt(0)
	v_add_f32_dpp v5, v5, v5 quad_perm:[2,3,0,1] row_mask:0xf bank_mask:0xf
	s_nop 1
	s_waitcnt lgkmcnt(0)
	v_add_f32_dpp v5, v5, v5 row_half_mirror row_mask:0xf bank_mask:0xf
	s_nop 1
	s_waitcnt lgkmcnt(0)
	v_add_f32_dpp v5, v5, v5 row_mirror row_mask:0xf bank_mask:0xf
	v_mov_b32_e32 v7, v5
	s_waitcnt lgkmcnt(0)
	s_nop 0
	v_permlane16_swap_b32_e32 v5, v7
	v_add_f32_e32 v5, v5, v7
	v_fmamk_f32 v5, v5, 0x3c000000, v198
	v_mul_f32_e32 v7, 0x4f800000, v5
	v_cmp_gt_f32_e32 vcc, s72, v5
	s_nop 1
	v_cndmask_b32_e32 v5, v5, v7, vcc
	v_sqrt_f32_e32 v7, v5
	s_nop 0
	v_add_u32_e32 v8, -1, v7
	v_fma_f32 v9, -v8, v7, v5
	v_cmp_ge_f32_e64 s[0:1], 0, v9
	v_add_u32_e32 v9, 1, v7
	s_nop 0
	v_cndmask_b32_e64 v8, v7, v8, s[0:1]
	v_fma_f32 v7, -v9, v7, v5
	v_cmp_lt_f32_e64 s[0:1], 0, v7
	s_nop 1
	v_cndmask_b32_e64 v7, v8, v9, s[0:1]
	v_mul_f32_e32 v8, 0x37800000, v7
	v_cndmask_b32_e32 v7, v7, v8, vcc
	v_cmp_class_f32_e32 vcc, v5, v199
	s_nop 1
	v_cndmask_b32_e32 v5, v7, v5, vcc
	v_div_scale_f32 v7, s[0:1], v5, v5, 1.0
	v_rcp_f32_e32 v8, v7
	s_nop 0
	v_fma_f32 v1, -v7, v8, 1.0
	v_fmac_f32_e32 v8, v1, v8
	v_div_scale_f32 v1, vcc, 1.0, v5, 1.0
	v_mul_f32_e32 v9, v1, v8
	v_fma_f32 v10, -v7, v9, v1
	v_fmac_f32_e32 v9, v10, v8
	v_fma_f32 v1, -v7, v9, v1
	v_div_fmas_f32 v1, v1, v8, v9
	v_div_fixup_f32 v1, v1, v5, 1.0
	v_mul_f32_e32 v2, v2, v1
	v_mul_f32_e32 v2, v48, v2
	v_cvt_pk_bf16_f32 v2, v2, v133
	ds_write_b16 v222, v2 offset:6272
	v_mul_f32_e32 v2, v4, v1
	v_mul_f32_e32 v2, v76, v2
	v_cvt_pk_bf16_f32 v2, v2, v133
	ds_write_b16 v221, v2 offset:6272
	v_mul_f32_e32 v2, v6, v1
	v_mul_f32_e32 v2, v16, v2
	v_mul_f32_e32 v1, v3, v1
	v_cvt_pk_bf16_f32 v2, v2, v133
	v_mul_f32_e32 v1, v0, v1
	ds_write_b16 v222, v2 offset:6144
	v_cvt_pk_bf16_f32 v1, v1, v133
	ds_read_u16 v2, v220 offset:6528
	v_rcp_f32_e32 v3, v65
	ds_read_u16 v4, v219 offset:6528
	ds_read_u16 v5, v219 offset:6400
	ds_read_u16 v6, v220 offset:6400
	v_mul_f32_e32 v7, v210, v61
	v_mul_f32_e32 v8, v210, v29
	s_waitcnt lgkmcnt(3)
	v_lshlrev_b32_e32 v2, 16, v2
	v_fma_f32 v2, -v7, v3, v2
	s_waitcnt lgkmcnt(2)
	v_lshlrev_b32_e32 v4, 16, v4
	v_mul_f32_e32 v7, v210, v45
	v_fma_f32 v4, -v7, v3, v4
	v_mul_f32_e32 v7, v4, v4
	s_waitcnt lgkmcnt(0)
	v_lshlrev_b32_e32 v6, 16, v6
	v_fmac_f32_e32 v7, v2, v2
	v_fma_f32 v6, -v8, v3, v6
	v_lshlrev_b32_e32 v5, 16, v5
	v_mul_f32_e32 v8, v210, v13
	v_fmac_f32_e32 v7, v6, v6
	v_fma_f32 v3, -v8, v3, v5
	v_fmac_f32_e32 v7, v3, v3
	s_nop 1
	ds_write_b16 v221, v1 offset:6144
	s_waitcnt lgkmcnt(1)
	v_add_f32_dpp v5, v7, v7 quad_perm:[1,0,3,2] row_mask:0xf bank_mask:0xf
	s_nop 1
	s_waitcnt lgkmcnt(0)
	v_add_f32_dpp v5, v5, v5 quad_perm:[2,3,0,1] row_mask:0xf bank_mask:0xf
	s_nop 1
	s_waitcnt lgkmcnt(0)
	v_add_f32_dpp v5, v5, v5 row_half_mirror row_mask:0xf bank_mask:0xf
	s_nop 1
	s_waitcnt lgkmcnt(0)
	v_add_f32_dpp v5, v5, v5 row_mirror row_mask:0xf bank_mask:0xf
	v_mov_b32_e32 v7, v5
	s_waitcnt lgkmcnt(0)
	s_nop 0
	v_permlane16_swap_b32_e32 v5, v7
	v_add_f32_e32 v5, v5, v7
	v_fmamk_f32 v5, v5, 0x3c000000, v198
	v_mul_f32_e32 v7, 0x4f800000, v5
	v_cmp_gt_f32_e32 vcc, s72, v5
	s_nop 1
	v_cndmask_b32_e32 v5, v5, v7, vcc
	v_sqrt_f32_e32 v7, v5
	s_nop 0
	v_add_u32_e32 v8, -1, v7
	v_fma_f32 v9, -v8, v7, v5
	v_cmp_ge_f32_e64 s[0:1], 0, v9
	v_add_u32_e32 v9, 1, v7
	s_nop 0
	v_cndmask_b32_e64 v8, v7, v8, s[0:1]
	v_fma_f32 v7, -v9, v7, v5
	v_cmp_lt_f32_e64 s[0:1], 0, v7
	s_nop 1
	v_cndmask_b32_e64 v7, v8, v9, s[0:1]
	v_mul_f32_e32 v8, 0x37800000, v7
	v_cndmask_b32_e32 v7, v7, v8, vcc
	v_cmp_class_f32_e32 vcc, v5, v199
	s_nop 1
	v_cndmask_b32_e32 v5, v7, v5, vcc
	v_div_scale_f32 v7, s[0:1], v5, v5, 1.0
	v_rcp_f32_e32 v8, v7
	s_nop 0
	v_fma_f32 v1, -v7, v8, 1.0
	v_fmac_f32_e32 v8, v1, v8
	v_div_scale_f32 v1, vcc, 1.0, v5, 1.0
	v_mul_f32_e32 v9, v1, v8
	v_fma_f32 v10, -v7, v9, v1
	v_fmac_f32_e32 v9, v10, v8
	v_fma_f32 v1, -v7, v9, v1
	v_div_fmas_f32 v1, v1, v8, v9
	v_div_fixup_f32 v1, v1, v5, 1.0
	v_mul_f32_e32 v2, v2, v1
	v_mul_f32_e32 v2, v48, v2
	v_cvt_pk_bf16_f32 v2, v2, v133
	ds_write_b16 v220, v2 offset:6528
	v_mul_f32_e32 v2, v4, v1
	v_mul_f32_e32 v2, v76, v2
	v_cvt_pk_bf16_f32 v2, v2, v133
	ds_write_b16 v219, v2 offset:6528
	v_mul_f32_e32 v2, v6, v1
	v_mul_f32_e32 v2, v16, v2
	v_mul_f32_e32 v1, v3, v1
	v_cvt_pk_bf16_f32 v2, v2, v133
	v_mul_f32_e32 v1, v0, v1
	ds_write_b16 v220, v2 offset:6400
	v_cvt_pk_bf16_f32 v1, v1, v133
	ds_read_u16 v2, v218 offset:6784
	v_rcp_f32_e32 v3, v66
	ds_read_u16 v4, v217 offset:6784
	ds_read_u16 v5, v217 offset:6656
	ds_read_u16 v6, v218 offset:6656
	v_mul_f32_e32 v7, v210, v62
	v_mul_f32_e32 v8, v210, v30
	s_waitcnt lgkmcnt(3)
	v_lshlrev_b32_e32 v2, 16, v2
	v_fma_f32 v2, -v7, v3, v2
	s_waitcnt lgkmcnt(2)
	v_lshlrev_b32_e32 v4, 16, v4
	v_mul_f32_e32 v7, v210, v46
	v_fma_f32 v4, -v7, v3, v4
	v_mul_f32_e32 v7, v4, v4
	s_waitcnt lgkmcnt(0)
	v_lshlrev_b32_e32 v6, 16, v6
	v_fmac_f32_e32 v7, v2, v2
	v_fma_f32 v6, -v8, v3, v6
	v_lshlrev_b32_e32 v5, 16, v5
	v_mul_f32_e32 v8, v210, v14
	v_fmac_f32_e32 v7, v6, v6
	v_fma_f32 v3, -v8, v3, v5
	v_fmac_f32_e32 v7, v3, v3
	s_nop 1
	ds_write_b16 v219, v1 offset:6400
	s_waitcnt lgkmcnt(1)
	v_add_f32_dpp v5, v7, v7 quad_perm:[1,0,3,2] row_mask:0xf bank_mask:0xf
	s_nop 1
	s_waitcnt lgkmcnt(0)
	v_add_f32_dpp v5, v5, v5 quad_perm:[2,3,0,1] row_mask:0xf bank_mask:0xf
	s_nop 1
	s_waitcnt lgkmcnt(0)
	v_add_f32_dpp v5, v5, v5 row_half_mirror row_mask:0xf bank_mask:0xf
	s_nop 1
	s_waitcnt lgkmcnt(0)
	v_add_f32_dpp v5, v5, v5 row_mirror row_mask:0xf bank_mask:0xf
	v_mov_b32_e32 v7, v5
	s_waitcnt lgkmcnt(0)
	s_nop 0
	v_permlane16_swap_b32_e32 v5, v7
	v_add_f32_e32 v5, v5, v7
	v_fmamk_f32 v5, v5, 0x3c000000, v198
	v_mul_f32_e32 v7, 0x4f800000, v5
	v_cmp_gt_f32_e32 vcc, s72, v5
	s_nop 1
	v_cndmask_b32_e32 v5, v5, v7, vcc
	v_sqrt_f32_e32 v7, v5
	s_nop 0
	v_add_u32_e32 v8, -1, v7
	v_fma_f32 v9, -v8, v7, v5
	v_cmp_ge_f32_e64 s[0:1], 0, v9
	v_add_u32_e32 v9, 1, v7
	s_nop 0
	v_cndmask_b32_e64 v8, v7, v8, s[0:1]
	v_fma_f32 v7, -v9, v7, v5
	v_cmp_lt_f32_e64 s[0:1], 0, v7
	s_nop 1
	v_cndmask_b32_e64 v7, v8, v9, s[0:1]
	v_mul_f32_e32 v8, 0x37800000, v7
	v_cndmask_b32_e32 v7, v7, v8, vcc
	v_cmp_class_f32_e32 vcc, v5, v199
	s_nop 1
	v_cndmask_b32_e32 v5, v7, v5, vcc
	v_div_scale_f32 v7, s[0:1], v5, v5, 1.0
	v_rcp_f32_e32 v8, v7
	s_nop 0
	v_fma_f32 v1, -v7, v8, 1.0
	v_fmac_f32_e32 v8, v1, v8
	v_div_scale_f32 v1, vcc, 1.0, v5, 1.0
	v_mul_f32_e32 v9, v1, v8
	v_fma_f32 v10, -v7, v9, v1
	v_fmac_f32_e32 v9, v10, v8
	v_fma_f32 v1, -v7, v9, v1
	v_div_fmas_f32 v1, v1, v8, v9
	v_div_fixup_f32 v1, v1, v5, 1.0
	v_mul_f32_e32 v2, v2, v1
	v_mul_f32_e32 v2, v48, v2
	v_cvt_pk_bf16_f32 v2, v2, v133
	ds_write_b16 v218, v2 offset:6784
	v_mul_f32_e32 v2, v4, v1
	v_mul_f32_e32 v2, v76, v2
	v_cvt_pk_bf16_f32 v2, v2, v133
	ds_write_b16 v217, v2 offset:6784
	v_mul_f32_e32 v2, v6, v1
	v_mul_f32_e32 v2, v16, v2
	v_mul_f32_e32 v1, v3, v1
	v_cvt_pk_bf16_f32 v2, v2, v133
	v_mul_f32_e32 v1, v0, v1
	ds_write_b16 v218, v2 offset:6656
	v_cvt_pk_bf16_f32 v1, v1, v133
	ds_read_u16 v2, v215 offset:7040
	v_rcp_f32_e32 v3, v67
	ds_read_u16 v4, v216 offset:7040
	ds_read_u16 v5, v216 offset:6912
	ds_read_u16 v6, v215 offset:6912
	v_mul_f32_e32 v7, v210, v63
	v_mul_f32_e32 v8, v210, v31
	s_waitcnt lgkmcnt(3)
	v_lshlrev_b32_e32 v2, 16, v2
	v_fma_f32 v2, -v7, v3, v2
	s_waitcnt lgkmcnt(2)
	v_lshlrev_b32_e32 v4, 16, v4
	v_mul_f32_e32 v7, v210, v47
	v_fma_f32 v4, -v7, v3, v4
	v_mul_f32_e32 v7, v4, v4
	s_waitcnt lgkmcnt(0)
	v_lshlrev_b32_e32 v6, 16, v6
	v_fmac_f32_e32 v7, v2, v2
	v_fma_f32 v6, -v8, v3, v6
	v_lshlrev_b32_e32 v5, 16, v5
	v_mul_f32_e32 v8, v210, v15
	v_fmac_f32_e32 v7, v6, v6
	v_fma_f32 v3, -v8, v3, v5
	v_fmac_f32_e32 v7, v3, v3
	s_nop 1
	ds_write_b16 v217, v1 offset:6656
	s_waitcnt lgkmcnt(1)
	v_add_f32_dpp v5, v7, v7 quad_perm:[1,0,3,2] row_mask:0xf bank_mask:0xf
	s_nop 1
	s_waitcnt lgkmcnt(0)
	v_add_f32_dpp v5, v5, v5 quad_perm:[2,3,0,1] row_mask:0xf bank_mask:0xf
	s_nop 1
	s_waitcnt lgkmcnt(0)
	v_add_f32_dpp v5, v5, v5 row_half_mirror row_mask:0xf bank_mask:0xf
	s_nop 1
	s_waitcnt lgkmcnt(0)
	v_add_f32_dpp v5, v5, v5 row_mirror row_mask:0xf bank_mask:0xf
	v_mov_b32_e32 v7, v5
	s_waitcnt lgkmcnt(0)
	s_nop 0
	v_permlane16_swap_b32_e32 v5, v7
	v_add_f32_e32 v5, v5, v7
	v_fmamk_f32 v5, v5, 0x3c000000, v198
	v_mul_f32_e32 v7, 0x4f800000, v5
	v_cmp_gt_f32_e32 vcc, s72, v5
	s_nop 1
	v_cndmask_b32_e32 v5, v5, v7, vcc
	v_sqrt_f32_e32 v7, v5
	s_nop 0
	v_add_u32_e32 v8, -1, v7
	v_fma_f32 v9, -v8, v7, v5
	v_cmp_ge_f32_e64 s[0:1], 0, v9
	v_add_u32_e32 v9, 1, v7
	s_nop 0
	v_cndmask_b32_e64 v8, v7, v8, s[0:1]
	v_fma_f32 v7, -v9, v7, v5
	v_cmp_lt_f32_e64 s[0:1], 0, v7
	s_nop 1
	v_cndmask_b32_e64 v7, v8, v9, s[0:1]
	v_mul_f32_e32 v8, 0x37800000, v7
	v_cndmask_b32_e32 v7, v7, v8, vcc
	v_cmp_class_f32_e32 vcc, v5, v199
	s_nop 1
	v_cndmask_b32_e32 v5, v7, v5, vcc
	v_div_scale_f32 v7, s[0:1], v5, v5, 1.0
	v_rcp_f32_e32 v8, v7
	s_nop 0
	v_fma_f32 v1, -v7, v8, 1.0
	v_fmac_f32_e32 v8, v1, v8
	v_div_scale_f32 v1, vcc, 1.0, v5, 1.0
	v_mul_f32_e32 v9, v1, v8
	v_fma_f32 v10, -v7, v9, v1
	v_fmac_f32_e32 v9, v10, v8
	v_fma_f32 v1, -v7, v9, v1
	v_div_fmas_f32 v1, v1, v8, v9
	v_div_fixup_f32 v1, v1, v5, 1.0
	v_mul_f32_e32 v2, v2, v1
	v_mul_f32_e32 v2, v48, v2
	v_cvt_pk_bf16_f32 v2, v2, v133
	ds_write_b16 v215, v2 offset:7040
	v_mul_f32_e32 v2, v4, v1
	v_mul_f32_e32 v2, v76, v2
	v_cvt_pk_bf16_f32 v2, v2, v133
	ds_write_b16 v216, v2 offset:7040
	v_mul_f32_e32 v2, v6, v1
	v_mul_f32_e32 v1, v3, v1
	v_mul_f32_e32 v2, v16, v2
	v_mul_f32_e32 v0, v0, v1
	v_cvt_pk_bf16_f32 v2, v2, v133
	ds_write_b16 v215, v2 offset:6912
	v_cvt_pk_bf16_f32 v0, v0, v133
	ds_write_b16 v216, v0 offset:6912
	s_waitcnt lgkmcnt(0)
	ds_read_b128 v[0:3], v200
	v_lshl_add_u64 v[8:9], s[62:63], 0, v[134:135]
	v_lshl_add_u64 v[10:11], v[152:153], 0, s[2:3]
	v_or_b32_e32 v4, v8, v128
	v_mad_u64_u32 v[12:13], s[0:1], v4, s70, v[10:11]
	v_mul_lo_u32 v9, v9, s70
	ds_read_b128 v[4:7], v201
	v_add_u32_e32 v13, v9, v13
	s_waitcnt lgkmcnt(1)
	global_store_dwordx4 v[12:13], v[0:3], off
	s_nop 1
	v_or_b32_e32 v0, v8, v136
	v_mad_u64_u32 v[0:1], s[0:1], v0, s70, v[10:11]
	v_add_u32_e32 v1, v9, v1
	s_waitcnt lgkmcnt(0)
	global_store_dwordx4 v[0:1], v[4:7], off
	ds_read_b128 v[0:3], v202
	s_nop 0
	v_or_b32_e32 v4, v8, v138
	v_mad_u64_u32 v[12:13], s[0:1], v4, s70, v[10:11]
	ds_read_b128 v[4:7], v203
	v_add_u32_e32 v13, v9, v13
	s_waitcnt lgkmcnt(1)
	global_store_dwordx4 v[12:13], v[0:3], off
	s_nop 1
	v_or_b32_e32 v0, v8, v140
	v_mad_u64_u32 v[0:1], s[0:1], v0, s70, v[10:11]
	v_add_u32_e32 v1, v9, v1
	s_waitcnt lgkmcnt(0)
	global_store_dwordx4 v[0:1], v[4:7], off
	ds_read_b128 v[0:3], v204
	s_nop 0
	v_or_b32_e32 v4, v8, v142
	v_mad_u64_u32 v[12:13], s[0:1], v4, s70, v[10:11]
	ds_read_b128 v[4:7], v205
	v_add_u32_e32 v13, v9, v13
	s_waitcnt lgkmcnt(1)
	global_store_dwordx4 v[12:13], v[0:3], off
	s_nop 1
	v_or_b32_e32 v0, v8, v144
	v_mad_u64_u32 v[0:1], s[0:1], v0, s70, v[10:11]
	v_add_u32_e32 v1, v9, v1
	s_waitcnt lgkmcnt(0)
	global_store_dwordx4 v[0:1], v[4:7], off
	ds_read_b128 v[0:3], v206
	s_nop 0
	v_or_b32_e32 v4, v8, v146
	v_mad_u64_u32 v[12:13], s[0:1], v4, s70, v[10:11]
	ds_read_b128 v[4:7], v207
	v_add_u32_e32 v13, v9, v13
	s_waitcnt lgkmcnt(1)
	global_store_dwordx4 v[12:13], v[0:3], off
	s_nop 1
	v_or_b32_e32 v0, v8, v148
	v_mad_u64_u32 v[0:1], s[0:1], v0, s70, v[10:11]
	v_add_u32_e32 v1, v9, v1
	s_waitcnt lgkmcnt(0)
	global_store_dwordx4 v[0:1], v[4:7], off
	s_cbranch_scc1 .LBB0_1068

.LBB0_1202:
	s_ashr_i32 s1, s0, 31
	s_mul_i32 s10, s0, 0x2c00
	s_mul_hi_i32 s11, s0, 0x2c00
	s_add_u32 s10, s4, s10
	s_addc_u32 s11, s5, s11
	v_lshl_add_u64 v[16:17], s[10:11], 0, v[36:37]
	s_lshl_b64 s[16:17], s[0:1], 11
	v_add_co_u32_e32 v20, vcc, 0x2000, v16
	v_lshl_add_u64 v[18:19], v[38:39], 0, s[16:17]
	s_nop 0
	v_addc_co_u32_e32 v21, vcc, 0, v17, vcc
	global_load_dwordx4 v[50:53], v[20:21], off
	global_load_dwordx4 v[24:27], v[18:19], off offset:1024
	v_add_co_u32_e32 v20, vcc, s13, v16
	global_load_dwordx4 v[46:49], v[18:19], off
	s_nop 0
	v_addc_co_u32_e32 v21, vcc, 0, v17, vcc
	global_load_dwordx4 v[42:45], v[20:21], off offset:2048
	v_lshl_add_u64 v[20:21], v[16:17], 0, s[6:7]
	v_lshl_add_u64 v[16:17], v[16:17], 0, s[8:9]
	global_load_dwordx4 v[32:35], v[16:17], off offset:1024
	s_waitcnt lgkmcnt(0)
	global_load_dwordx4 v[28:31], v[20:21], off offset:1024
	s_add_i32 s15, s0, s83
	s_min_i32 s0, s15, 0xffff
	s_ashr_i32 s1, s0, 31
	s_mul_i32 s16, s0, 0x2c00
	s_mul_hi_i32 s17, s0, 0x2c00
	s_add_u32 s16, s4, s16
	s_addc_u32 s17, s5, s17
	v_lshl_add_u64 v[54:55], s[16:17], 0, v[36:37]
	v_add_co_u32_e32 v58, vcc, s12, v54
	s_lshl_b64 s[0:1], s[0:1], 11
	s_nop 0
	v_addc_co_u32_e32 v59, vcc, 0, v55, vcc
	v_add_co_u32_e32 v60, vcc, s13, v54
	s_cmp_gt_i32 s15, 0xffff
	s_nop 0
	v_addc_co_u32_e32 v61, vcc, 0, v55, vcc
	global_load_dwordx4 v[16:19], v[58:59], off
	global_load_dwordx4 v[20:23], v[60:61], off offset:2048
	v_lshl_add_u64 v[96:97], v[38:39], 0, s[0:1]
	global_load_dwordx4 v[80:83], v[96:97], off
	v_lshl_add_u64 v[98:99], v[54:55], 0, s[6:7]
	global_load_dwordx4 v[84:87], v[98:99], off offset:1024
	v_lshl_add_u64 v[98:99], v[54:55], 0, s[8:9]
	global_load_dwordx4 v[88:91], v[98:99], off offset:1024
	global_load_dwordx4 v[92:95], v[96:97], off offset:1024
	s_waitcnt vmcnt(4)
	v_lshlrev_b32_e32 v70, 16, v50
	v_and_b32_e32 v71, 0xffff0000, v50
	v_lshlrev_b32_e32 v50, 16, v51
	v_and_b32_e32 v51, 0xffff0000, v51
	v_lshlrev_b32_e32 v58, 16, v46
	v_and_b32_e32 v59, 0xffff0000, v46
	v_lshlrev_b32_e32 v46, 16, v47
	v_and_b32_e32 v47, 0xffff0000, v47
	v_lshlrev_b32_e32 v60, 16, v48
	v_and_b32_e32 v61, 0xffff0000, v48
	v_lshlrev_b32_e32 v72, 16, v52
	v_and_b32_e32 v73, 0xffff0000, v52
	v_lshlrev_b32_e32 v74, 16, v42
	v_and_b32_e32 v75, 0xffff0000, v42
	v_lshlrev_b32_e32 v42, 16, v43
	v_and_b32_e32 v43, 0xffff0000, v43
	v_pk_add_f32 v[46:47], v[50:51], v[46:47]
	v_lshlrev_b32_e32 v50, 16, v44
	v_and_b32_e32 v51, 0xffff0000, v44
	v_pk_add_f32 v[58:59], v[70:71], v[58:59]
	v_pk_add_f32 v[60:61], v[72:73], v[60:61]
	v_lshlrev_b32_e32 v70, 16, v45
	v_and_b32_e32 v71, 0xffff0000, v45
	v_mul_f32_e32 v44, 0xbfb8aa3b, v74
	v_mul_f32_e32 v45, 0xbfb8aa3b, v75
	v_mul_f32_e32 v48, 0xbfb8aa3b, v42
	v_mul_f32_e32 v56, 0xbfb8aa3b, v43
	v_mul_f32_e32 v72, 0xbfb8aa3b, v50
	v_mul_f32_e32 v73, 0xbfb8aa3b, v51
	v_exp_f32_e32 v44, v44
	v_exp_f32_e32 v45, v45
	v_exp_f32_e32 v48, v48
	v_exp_f32_e32 v56, v56
	v_exp_f32_e32 v72, v72
	v_exp_f32_e32 v73, v73
	v_add_f32_e32 v44, 1.0, v44
	v_add_f32_e32 v45, 1.0, v45
	v_add_f32_e32 v48, 1.0, v48
	v_add_f32_e32 v56, 1.0, v56
	v_add_f32_e32 v76, 1.0, v72
	v_add_f32_e32 v77, 1.0, v73
	v_rcp_f32_e32 v44, v44
	v_rcp_f32_e32 v45, v45
	v_rcp_f32_e32 v72, v48
	v_rcp_f32_e32 v73, v56
	v_rcp_f32_e32 v76, v76
	v_rcp_f32_e32 v77, v77
	v_mul_f32_e32 v78, 0xbfb8aa3b, v70
	v_pk_mul_f32 v[44:45], v[44:45], v[74:75]
	v_pk_mul_f32 v[72:73], v[72:73], v[42:43]
	v_pk_mul_f32 v[50:51], v[76:77], v[50:51]
	v_exp_f32_e32 v48, v78
	v_pk_mul_f32 v[42:43], v[58:59], v[44:45]
	v_pk_mul_f32 v[44:45], v[46:47], v[72:73]
	v_pk_mul_f32 v[46:47], v[60:61], v[50:51]
	v_mul_f32_e32 v50, 0xbfb8aa3b, v71
	v_exp_f32_e32 v51, v50
	v_add_f32_e32 v48, 1.0, v48
	v_rcp_f32_e32 v50, v48
	v_lshlrev_b32_e32 v52, 16, v53
	v_add_f32_e32 v48, 1.0, v51
	v_rcp_f32_e32 v51, v48
	v_and_b32_e32 v53, 0xffff0000, v53
	v_lshlrev_b32_e32 v48, 16, v49
	v_and_b32_e32 v49, 0xffff0000, v49
	v_pk_add_f32 v[48:49], v[52:53], v[48:49]
	v_lshlrev_b32_e32 v52, 16, v32
	v_pk_mul_f32 v[50:51], v[50:51], v[70:71]
	v_and_b32_e32 v53, 0xffff0000, v32
	v_mul_f32_e32 v32, 0xbfb8aa3b, v52
	v_pk_mul_f32 v[48:49], v[48:49], v[50:51]
	v_exp_f32_e32 v32, v32
	v_mul_f32_e32 v51, 0xbfb8aa3b, v53
	v_exp_f32_e32 v56, v51
	v_lshlrev_b32_e32 v50, 16, v28
	v_and_b32_e32 v51, 0xffff0000, v28
	v_add_f32_e32 v28, 1.0, v32
	v_rcp_f32_e32 v58, v28
	v_add_f32_e32 v28, 1.0, v56
	v_rcp_f32_e32 v59, v28
	v_lshlrev_b32_e32 v60, 16, v24
	v_and_b32_e32 v61, 0xffff0000, v24
	v_lshlrev_b32_e32 v32, 16, v33
	v_pk_add_f32 v[50:51], v[50:51], v[60:61]
	v_pk_mul_f32 v[52:53], v[58:59], v[52:53]
	v_and_b32_e32 v33, 0xffff0000, v33
	v_mul_f32_e32 v24, 0xbfb8aa3b, v32
	v_pk_mul_f32 v[50:51], v[50:51], v[52:53]
	v_exp_f32_e32 v24, v24
	v_mul_f32_e32 v52, 0xbfb8aa3b, v33
	v_exp_f32_e32 v53, v52
	v_lshlrev_b32_e32 v28, 16, v29
	v_add_f32_e32 v24, 1.0, v24
	v_rcp_f32_e32 v52, v24
	v_add_f32_e32 v24, 1.0, v53
	v_rcp_f32_e32 v53, v24
	v_and_b32_e32 v29, 0xffff0000, v29
	v_lshlrev_b32_e32 v24, 16, v25
	v_and_b32_e32 v25, 0xffff0000, v25
	v_pk_add_f32 v[24:25], v[28:29], v[24:25]
	v_pk_mul_f32 v[28:29], v[52:53], v[32:33]
	v_lshlrev_b32_e32 v58, 16, v26
	v_pk_mul_f32 v[52:53], v[24:25], v[28:29]
	v_lshlrev_b32_e32 v28, 16, v34
	v_and_b32_e32 v29, 0xffff0000, v34
	v_mul_f32_e32 v25, 0xbfb8aa3b, v28
	v_exp_f32_e32 v32, v25
	v_mul_f32_e32 v25, 0xbfb8aa3b, v29
	v_exp_f32_e32 v33, v25
	v_lshlrev_b32_e32 v24, 16, v30
	v_and_b32_e32 v25, 0xffff0000, v30
	v_add_f32_e32 v30, 1.0, v32
	v_rcp_f32_e32 v32, v30
	v_add_f32_e32 v30, 1.0, v33
	v_rcp_f32_e32 v33, v30
	v_and_b32_e32 v59, 0xffff0000, v26
	v_pk_add_f32 v[24:25], v[24:25], v[58:59]
	v_pk_mul_f32 v[28:29], v[32:33], v[28:29]
	s_nop 0
	v_pk_mul_f32 v[58:59], v[24:25], v[28:29]
	v_lshlrev_b32_e32 v28, 16, v35
	v_and_b32_e32 v29, 0xffff0000, v35
	v_mul_f32_e32 v25, 0xbfb8aa3b, v28
	v_exp_f32_e32 v26, v25
	v_mul_f32_e32 v25, 0xbfb8aa3b, v29
	v_exp_f32_e32 v32, v25
	v_lshlrev_b32_e32 v24, 16, v31
	v_add_f32_e32 v26, 1.0, v26
	v_rcp_f32_e32 v30, v26
	v_add_f32_e32 v26, 1.0, v32
	v_and_b32_e32 v25, 0xffff0000, v31
	v_rcp_f32_e32 v31, v26
	v_lshlrev_b32_e32 v26, 16, v27
	v_and_b32_e32 v27, 0xffff0000, v27
	v_pk_add_f32 v[24:25], v[24:25], v[26:27]
	v_pk_mul_f32 v[26:27], v[30:31], v[28:29]
	v_mov_b32_e32 v28, v47
	v_pk_mul_f32 v[74:75], v[24:25], v[26:27]
	v_mov_b32_e32 v26, v43
	v_mov_b32_e32 v27, v45
	v_mov_b32_e32 v24, v42
	v_mov_b32_e32 v25, v44
	v_pk_mul_f32 v[26:27], v[26:27], v[26:27]
	v_mov_b32_e32 v29, v49
	v_pk_fma_f32 v[24:25], v[24:25], v[24:25], v[26:27]
	v_mov_b32_e32 v26, v46
	v_pk_add_f32 v[24:25], v[24:25], v[24:25] op_sel_hi:[0,1]
	v_mov_b32_e32 v27, v48
	v_pk_mul_f32 v[28:29], v[28:29], v[28:29]
	v_mul_f32_e32 v24, v50, v50
	v_pk_fma_f32 v[26:27], v[26:27], v[26:27], v[28:29]
	v_pk_fma_f32 v[28:29], v[50:51], v[50:51], v[24:25] op_sel_hi:[1,1,0]
	v_mul_f32_e32 v24, v52, v52
	v_pk_add_f32 v[26:27], v[26:27], v[26:27] op_sel_hi:[0,1]
	v_pk_fma_f32 v[30:31], v[52:53], v[52:53], v[24:25] op_sel_hi:[1,1,0]
	v_pk_mul_f32 v[32:33], v[58:59], v[58:59]
	v_pk_mul_f32 v[34:35], v[74:75], v[74:75]
	v_mov_b32_e32 v24, v32
	v_mov_b32_e32 v26, v33
	v_mov_b32_e32 v28, v34
	v_mov_b32_e32 v30, v35
	v_pk_add_f32 v[24:25], v[24:25], v[26:27]
	v_pk_add_f32 v[26:27], v[28:29], v[30:31]
	s_nop 0
	v_pk_add_f32 v[24:25], v[24:25], v[26:27]
	s_nop 0
	v_add_f32_e32 v24, v24, v25
	s_nop 1
	s_waitcnt lgkmcnt(0)
	v_add_f32_dpp v24, v24, v24 quad_perm:[1,0,3,2] row_mask:0xf bank_mask:0xf
	s_nop 1
	s_waitcnt lgkmcnt(0)
	v_add_f32_dpp v24, v24, v24 quad_perm:[2,3,0,1] row_mask:0xf bank_mask:0xf
	s_nop 1
	s_waitcnt lgkmcnt(0)
	v_add_f32_dpp v24, v24, v24 row_half_mirror row_mask:0xf bank_mask:0xf
	s_nop 1
	s_waitcnt lgkmcnt(0)
	v_add_f32_dpp v24, v24, v24 row_mirror row_mask:0xf bank_mask:0xf
	v_mov_b32_e32 v25, v24
	s_waitcnt lgkmcnt(0)
	s_nop 0
	v_permlane16_swap_b32_e32 v24, v25
	v_add_f32_e32 v24, v24, v25
	v_mov_b32_e32 v25, v24
	s_waitcnt lgkmcnt(0)
	s_nop 0
	v_permlane32_swap_b32_e32 v24, v25
	v_add_f32_e32 v24, v24, v25
	v_fmamk_f32 v24, v24, 0x3a800000, v67
	v_mul_f32_e32 v25, 0x4f800000, v24
	v_cmp_gt_f32_e32 vcc, s14, v24
	s_nop 1
	v_cndmask_b32_e32 v30, v24, v25, vcc
	v_sqrt_f32_e32 v31, v30
	s_nop 0
	s_nop 0
	v_add_u32_e32 v32, -1, v31
	v_fma_f32 v33, -v32, v31, v30
	v_cmp_ge_f32_e64 s[0:1], 0, v33
	v_add_u32_e32 v33, 1, v31
	s_waitcnt vmcnt(3)
	v_mov_b32_e32 v70, v80
	v_mov_b32_e32 v71, v81
	v_mov_b32_e32 v72, v82
	v_mov_b32_e32 v73, v83
	v_lshlrev_b32_e32 v78, 16, v70
	v_cndmask_b32_e64 v32, v31, v32, s[0:1]
	v_fma_f32 v31, -v33, v31, v30
	v_cmp_lt_f32_e64 s[0:1], 0, v31
	v_and_b32_e32 v79, 0xffff0000, v70
	s_nop 0
	v_cndmask_b32_e64 v31, v32, v33, s[0:1]
	v_mul_f32_e32 v32, 0x37800000, v31
	v_cndmask_b32_e32 v31, v31, v32, vcc
	v_cmp_class_f32_e32 vcc, v30, v68
	s_nop 0
	s_nop 0
	v_cndmask_b32_e32 v56, v31, v30, vcc
	s_nop 0
	v_div_scale_f32 v60, s[0:1], v56, v56, 1.0
	v_rcp_f32_e32 v61, v60
	s_nop 0
	v_fma_f32 v54, -v60, v61, 1.0
	v_fmac_f32_e32 v61, v54, v61
	v_div_scale_f32 v54, vcc, 1.0, v56, 1.0
	v_mul_f32_e32 v55, v54, v61
	v_fma_f32 v76, -v60, v55, v54
	v_fmac_f32_e32 v55, v76, v61
	v_fma_f32 v54, -v60, v55, v54
	v_div_fmas_f32 v54, v54, v61, v55
	v_div_fixup_f32 v56, v54, v56, 1.0
	v_pk_mul_f32 v[54:55], v[74:75], v[56:57] op_sel_hi:[1,0]
	v_lshlrev_b32_e32 v74, 16, v20
	v_and_b32_e32 v75, 0xffff0000, v20
	v_mul_f32_e32 v20, 0xbfb8aa3b, v74
	v_pk_mul_f32 v[60:61], v[58:59], v[56:57] op_sel_hi:[1,0]
	v_exp_f32_e32 v20, v20
	v_mul_f32_e32 v59, 0xbfb8aa3b, v75
	v_exp_f32_e32 v77, v59
	v_lshlrev_b32_e32 v58, 16, v16
	v_and_b32_e32 v59, 0xffff0000, v16
	v_add_f32_e32 v16, 1.0, v20
	v_rcp_f32_e32 v76, v16
	v_add_f32_e32 v16, 1.0, v77
	v_rcp_f32_e32 v77, v16
	v_lshlrev_b32_e32 v20, 16, v21
	v_pk_add_f32 v[58:59], v[58:59], v[78:79]
	v_and_b32_e32 v21, 0xffff0000, v21
	v_pk_mul_f32 v[74:75], v[76:77], v[74:75]
	v_mul_f32_e32 v70, 0xbfb8aa3b, v20
	v_pk_mul_f32 v[58:59], v[58:59], v[74:75]
	v_exp_f32_e32 v70, v70
	v_mul_f32_e32 v74, 0xbfb8aa3b, v21
	v_exp_f32_e32 v75, v74
	v_lshlrev_b32_e32 v16, 16, v17
	v_add_f32_e32 v70, 1.0, v70
	v_rcp_f32_e32 v74, v70
	v_add_f32_e32 v70, 1.0, v75
	v_rcp_f32_e32 v75, v70
	v_and_b32_e32 v17, 0xffff0000, v17
	v_lshlrev_b32_e32 v70, 16, v71
	v_and_b32_e32 v71, 0xffff0000, v71
	v_pk_add_f32 v[16:17], v[16:17], v[70:71]
	v_pk_mul_f32 v[20:21], v[74:75], v[20:21]
	v_lshlrev_b32_e32 v70, 16, v22
	v_pk_mul_f32 v[16:17], v[16:17], v[20:21]
	v_and_b32_e32 v71, 0xffff0000, v22
	v_mul_f32_e32 v21, 0xbfb8aa3b, v70
	v_exp_f32_e32 v22, v21
	v_mul_f32_e32 v21, 0xbfb8aa3b, v71
	v_exp_f32_e32 v75, v21
	v_lshlrev_b32_e32 v20, 16, v18
	v_and_b32_e32 v21, 0xffff0000, v18
	v_add_f32_e32 v18, 1.0, v22
	v_rcp_f32_e32 v74, v18
	v_add_f32_e32 v18, 1.0, v75
	v_rcp_f32_e32 v75, v18
	v_lshlrev_b32_e32 v76, 16, v72
	v_and_b32_e32 v77, 0xffff0000, v72
	v_pk_add_f32 v[20:21], v[20:21], v[76:77]
	v_pk_mul_f32 v[70:71], v[74:75], v[70:71]
	v_lshlrev_b32_e32 v22, 16, v23
	v_and_b32_e32 v23, 0xffff0000, v23
	v_pk_mul_f32 v[20:21], v[20:21], v[70:71]
	v_mul_f32_e32 v70, 0xbfb8aa3b, v22
	v_mul_f32_e32 v71, 0xbfb8aa3b, v23
	v_exp_f32_e32 v70, v70
	v_exp_f32_e32 v71, v71
	v_lshlrev_b32_e32 v18, 16, v19
	v_and_b32_e32 v19, 0xffff0000, v19
	v_add_f32_e32 v70, 1.0, v70
	v_add_f32_e32 v71, 1.0, v71
	v_rcp_f32_e32 v70, v70
	v_rcp_f32_e32 v71, v71
	v_lshlrev_b32_e32 v72, 16, v73
	v_and_b32_e32 v73, 0xffff0000, v73
	v_pk_add_f32 v[18:19], v[18:19], v[72:73]
	v_pk_mul_f32 v[22:23], v[70:71], v[22:23]
	s_waitcnt vmcnt(1)
	v_mov_b32_e32 v24, v84
	v_mov_b32_e32 v25, v85
	v_mov_b32_e32 v26, v86
	v_mov_b32_e32 v27, v87
	v_mov_b32_e32 v32, v88
	v_mov_b32_e32 v33, v89
	v_mov_b32_e32 v34, v90
	v_mov_b32_e32 v35, v91
	v_lshlrev_b32_e32 v70, 16, v32
	v_pk_mul_f32 v[18:19], v[18:19], v[22:23]
	v_and_b32_e32 v71, 0xffff0000, v32
	v_mul_f32_e32 v23, 0xbfb8aa3b, v70
	v_exp_f32_e32 v32, v23
	v_mul_f32_e32 v23, 0xbfb8aa3b, v71
	v_exp_f32_e32 v73, v23
	v_lshlrev_b32_e32 v22, 16, v24
	v_and_b32_e32 v23, 0xffff0000, v24
	v_add_f32_e32 v24, 1.0, v32
	v_rcp_f32_e32 v72, v24
	v_add_f32_e32 v24, 1.0, v73
	v_rcp_f32_e32 v73, v24
	s_waitcnt vmcnt(0)
	v_mov_b32_e32 v28, v92
	v_mov_b32_e32 v29, v93
	v_mov_b32_e32 v30, v94
	v_mov_b32_e32 v31, v95
	v_lshlrev_b32_e32 v74, 16, v28
	v_and_b32_e32 v75, 0xffff0000, v28
	v_lshlrev_b32_e32 v32, 16, v33
	v_pk_add_f32 v[22:23], v[22:23], v[74:75]
	v_pk_mul_f32 v[70:71], v[72:73], v[70:71]
	v_and_b32_e32 v33, 0xffff0000, v33
	v_mul_f32_e32 v28, 0xbfb8aa3b, v32
	v_pk_mul_f32 v[22:23], v[22:23], v[70:71]
	v_exp_f32_e32 v28, v28
	v_mul_f32_e32 v70, 0xbfb8aa3b, v33
	v_exp_f32_e32 v71, v70
	v_lshlrev_b32_e32 v24, 16, v25
	v_add_f32_e32 v28, 1.0, v28
	v_rcp_f32_e32 v70, v28
	v_add_f32_e32 v28, 1.0, v71
	v_rcp_f32_e32 v71, v28
	v_and_b32_e32 v25, 0xffff0000, v25
	v_lshlrev_b32_e32 v28, 16, v29
	v_and_b32_e32 v29, 0xffff0000, v29
	v_pk_add_f32 v[24:25], v[24:25], v[28:29]
	v_pk_mul_f32 v[28:29], v[70:71], v[32:33]
	v_lshlrev_b32_e32 v32, 16, v34
	v_pk_mul_f32 v[24:25], v[24:25], v[28:29]
	v_and_b32_e32 v33, 0xffff0000, v34
	v_mul_f32_e32 v29, 0xbfb8aa3b, v32
	v_exp_f32_e32 v34, v29
	v_mul_f32_e32 v29, 0xbfb8aa3b, v33
	v_exp_f32_e32 v71, v29
	v_lshlrev_b32_e32 v28, 16, v26
	v_and_b32_e32 v29, 0xffff0000, v26
	v_add_f32_e32 v26, 1.0, v34
	v_rcp_f32_e32 v70, v26
	v_add_f32_e32 v26, 1.0, v71
	v_rcp_f32_e32 v71, v26
	v_lshlrev_b32_e32 v72, 16, v30
	v_and_b32_e32 v73, 0xffff0000, v30
	v_pk_add_f32 v[28:29], v[28:29], v[72:73]
	v_pk_mul_f32 v[32:33], v[70:71], v[32:33]
	v_lshlrev_b32_e32 v26, 16, v27
	v_pk_mul_f32 v[28:29], v[28:29], v[32:33]
	v_lshlrev_b32_e32 v32, 16, v35
	v_and_b32_e32 v33, 0xffff0000, v35
	v_mul_f32_e32 v30, 0xbfb8aa3b, v32
	v_exp_f32_e32 v30, v30
	v_mul_f32_e32 v34, 0xbfb8aa3b, v33
	v_exp_f32_e32 v35, v34
	v_and_b32_e32 v27, 0xffff0000, v27
	v_add_f32_e32 v30, 1.0, v30
	v_rcp_f32_e32 v34, v30
	v_add_f32_e32 v30, 1.0, v35
	v_rcp_f32_e32 v35, v30
	v_lshlrev_b32_e32 v30, 16, v31
	v_and_b32_e32 v31, 0xffff0000, v31
	v_pk_add_f32 v[26:27], v[26:27], v[30:31]
	v_pk_mul_f32 v[30:31], v[34:35], v[32:33]
	v_pk_mul_f32 v[32:33], v[16:17], v[16:17]
	v_pk_mul_f32 v[26:27], v[26:27], v[30:31]
	v_pk_mul_f32 v[30:31], v[58:59], v[58:59]
	v_pk_mul_f32 v[34:35], v[20:21], v[20:21]
	v_pk_mul_f32 v[70:71], v[18:19], v[18:19]
	v_pk_mul_f32 v[72:73], v[22:23], v[22:23]
	v_pk_mul_f32 v[74:75], v[24:25], v[24:25]
	v_add_f32_e32 v70, v70, v71
	v_add_f32_e32 v34, v34, v35
	v_add_f32_e32 v32, v32, v33
	v_add_f32_e32 v30, v30, v31
	v_add_f32_e32 v34, v34, v70
	v_add_f32_e32 v30, v30, v32
	v_add_f32_e32 v31, v74, v75
	v_add_f32_e32 v32, v72, v73
	v_pk_mul_f32 v[76:77], v[28:29], v[28:29]
	v_pk_mul_f32 v[78:79], v[26:27], v[26:27]
	v_add_f32_e32 v30, v30, v34
	v_add_f32_e32 v31, v32, v31
	v_add_f32_e32 v30, v30, v31
	v_add_f32_e32 v31, v78, v79
	v_add_f32_e32 v32, v76, v77
	v_add_f32_e32 v31, v32, v31
	v_add_f32_e32 v70, v31, v30
	s_nop 1
	v_pk_mul_f32 v[34:35], v[12:13], v[60:61]
	v_pk_mul_f32 v[32:33], v[52:53], v[56:57] op_sel_hi:[1,0]
	v_pk_mul_f32 v[30:31], v[50:51], v[56:57] op_sel_hi:[1,0]
	v_pk_mul_f32 v[50:51], v[10:11], v[32:33]
	s_waitcnt lgkmcnt(0)
	v_add_f32_dpp v60, v70, v70 quad_perm:[1,0,3,2] row_mask:0xf bank_mask:0xf
	s_nop 1
	v_pk_mul_f32 v[32:33], v[48:49], v[56:57] op_sel_hi:[1,0]
	v_pk_mul_f32 v[52:53], v[8:9], v[30:31]
	v_pk_mul_f32 v[30:31], v[46:47], v[56:57] op_sel_hi:[1,0]
	v_pk_mul_f32 v[46:47], v[6:7], v[32:33]
	s_waitcnt lgkmcnt(0)
	v_add_f32_dpp v48, v60, v60 quad_perm:[2,3,0,1] row_mask:0xf bank_mask:0xf
	s_nop 1
	v_pk_mul_f32 v[32:33], v[4:5], v[30:31]
	v_pk_mul_f32 v[30:31], v[42:43], v[56:57] op_sel_hi:[1,0]
	v_pk_mul_f32 v[42:43], v[44:45], v[56:57] op_sel_hi:[1,0]
	v_pk_mul_f32 v[30:31], v[0:1], v[30:31]
	s_waitcnt lgkmcnt(0)
	v_add_f32_dpp v44, v48, v48 row_half_mirror row_mask:0xf bank_mask:0xf
	s_nop 1
	v_pk_mul_f32 v[42:43], v[2:3], v[42:43]
	v_cvt_pk_bf16_f32 v30, v30, v31
	v_pk_mul_f32 v[54:55], v[14:15], v[54:55]
	v_cvt_pk_bf16_f32 v31, v42, v43
	s_waitcnt lgkmcnt(0)
	v_add_f32_dpp v42, v44, v44 row_mirror row_mask:0xf bank_mask:0xf
	ds_bpermute_b32 v43, v65, v42
	v_cvt_pk_bf16_f32 v32, v32, v33
	v_cvt_pk_bf16_f32 v33, v46, v47
	global_store_dwordx4 v36, v[30:33], s[10:11] offset:2048
	s_waitcnt lgkmcnt(0)
	s_nop 0
	v_add_f32_e32 v30, v42, v43
	ds_bpermute_b32 v31, v66, v30
	v_cvt_pk_bf16_f32 v32, v52, v53
	v_cvt_pk_bf16_f32 v33, v50, v51
	v_cvt_pk_bf16_f32 v34, v34, v35
	v_cvt_pk_bf16_f32 v35, v54, v55
	global_store_dwordx4 v36, v[32:35], s[10:11] offset:3072
	s_cbranch_scc1 .LBB0_1201
	s_waitcnt lgkmcnt(0)
	v_add_f32_e32 v30, v30, v31
	v_fmamk_f32 v30, v30, 0x3a800000, v67
	v_mul_f32_e32 v31, 0x4f800000, v30
	v_cmp_gt_f32_e32 vcc, s14, v30
	s_nop 1
	v_cndmask_b32_e32 v30, v30, v31, vcc
	v_sqrt_f32_e32 v31, v30
	s_nop 0
	v_add_u32_e32 v32, -1, v31
	v_fma_f32 v34, -v32, v31, v30
	v_add_u32_e32 v33, 1, v31
	v_cmp_ge_f32_e64 s[0:1], 0, v34
	s_nop 1
	v_cndmask_b32_e64 v32, v31, v32, s[0:1]
	v_fma_f32 v31, -v33, v31, v30
	v_cmp_lt_f32_e64 s[0:1], 0, v31
	s_nop 1
	v_cndmask_b32_e64 v31, v32, v33, s[0:1]
	v_mul_f32_e32 v32, 0x37800000, v31
	v_cndmask_b32_e32 v31, v31, v32, vcc
	v_cmp_class_f32_e32 vcc, v30, v68
	s_nop 1
	v_cndmask_b32_e32 v30, v31, v30, vcc
	v_div_scale_f32 v31, s[0:1], v30, v30, 1.0
	v_rcp_f32_e32 v32, v31
	s_nop 0
	v_fma_f32 v33, -v31, v32, 1.0
	v_fmac_f32_e32 v32, v33, v32
	v_div_scale_f32 v33, vcc, 1.0, v30, 1.0
	v_mul_f32_e32 v34, v33, v32
	v_fma_f32 v35, -v31, v34, v33
	v_fmac_f32_e32 v34, v35, v32
	v_fma_f32 v31, -v31, v34, v33
	v_div_fmas_f32 v31, v31, v32, v34
	v_div_fixup_f32 v30, v31, v30, 1.0
	v_pk_mul_f32 v[20:21], v[20:21], v[30:31] op_sel_hi:[1,0]
	v_pk_mul_f32 v[18:19], v[18:19], v[30:31] op_sel_hi:[1,0]
	v_pk_mul_f32 v[16:17], v[16:17], v[30:31] op_sel_hi:[1,0]
	v_pk_mul_f32 v[32:33], v[6:7], v[18:19]
	v_pk_mul_f32 v[18:19], v[4:5], v[20:21]
	v_pk_mul_f32 v[20:21], v[58:59], v[30:31] op_sel_hi:[1,0]
	v_pk_mul_f32 v[28:29], v[28:29], v[30:31] op_sel_hi:[1,0]
	v_pk_mul_f32 v[26:27], v[26:27], v[30:31] op_sel_hi:[1,0]
	v_pk_mul_f32 v[22:23], v[22:23], v[30:31] op_sel_hi:[1,0]
	v_pk_mul_f32 v[24:25], v[24:25], v[30:31] op_sel_hi:[1,0]
	v_pk_mul_f32 v[30:31], v[2:3], v[16:17]
	v_pk_mul_f32 v[16:17], v[0:1], v[20:21]
	v_mad_i64_i32 v[20:21], s[0:1], s15, v69, v[40:41]
	v_cvt_pk_bf16_f32 v16, v16, v17
	v_cvt_pk_bf16_f32 v17, v30, v31
	v_cvt_pk_bf16_f32 v18, v18, v19
	v_cvt_pk_bf16_f32 v19, v32, v33
	v_pk_mul_f32 v[26:27], v[14:15], v[26:27]
	v_pk_mul_f32 v[28:29], v[12:13], v[28:29]
	v_pk_mul_f32 v[24:25], v[10:11], v[24:25]
	v_pk_mul_f32 v[22:23], v[8:9], v[22:23]
	global_store_dwordx4 v[20:21], v[16:19], off offset:2048
	s_nop 1
	v_cvt_pk_bf16_f32 v16, v22, v23
	v_cvt_pk_bf16_f32 v17, v24, v25
	v_cvt_pk_bf16_f32 v18, v28, v29
	v_cvt_pk_bf16_f32 v19, v26, v27
	global_store_dwordx4 v[20:21], v[16:19], off offset:3072
	s_branch .LBB0_1201

.LBB0_1339:
	s_ashr_i32 s1, s0, 31
	s_lshl_b64 s[6:7], s[0:1], 11
	v_lshl_add_u64 v[48:49], v[42:43], 0, s[6:7]
	global_load_dwordx4 v[32:35], v[48:49], off offset:1024
	global_load_dwordx4 v[36:39], v[48:49], off
	v_lshl_add_u64 v[48:49], v[40:41], 0, s[6:7]
	global_load_dwordx4 v[52:55], v[48:49], off
	s_waitcnt lgkmcnt(0)
	global_load_dwordx4 v[56:59], v[48:49], off offset:1024
	s_add_i32 s4, s0, s83
	s_min_i32 s0, s4, 0xffff
	s_ashr_i32 s1, s0, 31
	s_lshl_b64 s[0:1], s[0:1], 11
	v_lshl_add_u64 v[76:77], v[42:43], 0, s[0:1]
	v_lshl_add_u64 v[96:97], v[46:47], 0, s[6:7]
	s_cmp_lt_i32 s4, 0x10000
	s_waitcnt vmcnt(0)
	v_lshlrev_b32_e32 v48, 16, v34
	v_lshlrev_b32_e32 v64, 16, v36
	v_lshlrev_b32_e32 v66, 16, v37
	v_and_b32_e32 v71, 0xffff0000, v39
	v_and_b32_e32 v70, 0xffff0000, v38
	v_and_b32_e32 v49, 0xffff0000, v34
	v_and_b32_e32 v65, 0xffff0000, v36
	v_and_b32_e32 v67, 0xffff0000, v37
	v_lshlrev_b32_e32 v69, 16, v39
	v_lshlrev_b32_e32 v68, 16, v38
	v_lshlrev_b32_e32 v72, 16, v32
	v_and_b32_e32 v73, 0xffff0000, v32
	v_lshlrev_b32_e32 v74, 16, v33
	v_mul_f32_e32 v32, v64, v64
	v_mul_f32_e32 v34, v66, v66
	v_pk_mul_f32 v[36:37], v[70:71], v[70:71]
	v_lshlrev_b32_e32 v50, 16, v35
	v_and_b32_e32 v51, 0xffff0000, v35
	v_and_b32_e32 v75, 0xffff0000, v33
	v_mul_f32_e32 v38, v72, v72
	v_mul_f32_e32 v60, v74, v74
	v_pk_fma_f32 v[32:33], v[64:65], v[64:65], v[32:33] op_sel_hi:[1,1,0]
	v_pk_fma_f32 v[34:35], v[66:67], v[66:67], v[34:35] op_sel_hi:[1,1,0]
	v_pk_fma_f32 v[36:37], v[68:69], v[68:69], v[36:37]
	v_pk_fma_f32 v[38:39], v[72:73], v[72:73], v[38:39] op_sel_hi:[1,1,0]
	v_pk_fma_f32 v[60:61], v[74:75], v[74:75], v[60:61] op_sel_hi:[1,1,0]
	v_pk_add_f32 v[36:37], v[36:37], v[36:37] op_sel_hi:[0,1]
	v_pk_add_f32 v[32:33], v[32:33], v[34:35]
	v_mul_f32_e32 v62, v48, v48
	v_mul_f32_e32 v38, v50, v50
	v_mul_f32_e32 v60, v51, v51
	v_mul_f32_e32 v36, v49, v49
	v_mov_b32_e32 v63, v33
	v_pk_add_f32 v[32:33], v[38:39], v[60:61]
	v_pk_add_f32 v[34:35], v[62:63], v[36:37]
	v_lshlrev_b32_e32 v82, 16, v57
	v_pk_add_f32 v[32:33], v[34:35], v[32:33]
	v_and_b32_e32 v99, 0xffff0000, v58
	v_add_f32_e32 v32, v32, v33
	s_nop 1
	v_lshlrev_b32_e32 v100, 16, v59
	s_waitcnt lgkmcnt(0)
	v_add_f32_dpp v34, v32, v32 quad_perm:[1,0,3,2] row_mask:0xf bank_mask:0xf
	s_nop 1
	v_lshl_add_u64 v[32:33], v[40:41], 0, s[0:1]
	global_load_dwordx4 v[60:63], v[32:33], off
	global_load_dwordx4 v[92:95], v[32:33], off offset:1024
	s_waitcnt lgkmcnt(0)
	v_add_f32_dpp v78, v34, v34 quad_perm:[2,3,0,1] row_mask:0xf bank_mask:0xf
	s_nop 1
	global_load_dwordx4 v[36:39], v[76:77], off
	global_load_dwordx4 v[32:35], v[76:77], off offset:1024
	v_lshlrev_b32_e32 v76, 16, v52
	v_and_b32_e32 v77, 0xffff0000, v52
	v_lshlrev_b32_e32 v52, 16, v53
	s_waitcnt lgkmcnt(0)
	v_add_f32_dpp v80, v78, v78 row_half_mirror row_mask:0xf bank_mask:0xf
	s_nop 1
	v_and_b32_e32 v53, 0xffff0000, v53
	v_lshlrev_b32_e32 v78, 16, v54
	v_and_b32_e32 v79, 0xffff0000, v54
	v_lshlrev_b32_e32 v54, 16, v55
	s_waitcnt lgkmcnt(0)
	v_add_f32_dpp v83, v80, v80 row_mirror row_mask:0xf bank_mask:0xf
	v_mov_b32_e32 v98, v83
	v_lshlrev_b32_e32 v80, 16, v56
	v_and_b32_e32 v81, 0xffff0000, v56
	v_and_b32_e32 v55, 0xffff0000, v55
	s_waitcnt lgkmcnt(0)
	v_permlane16_swap_b32_e32 v83, v98
	v_add_f32_e32 v56, v83, v98
	v_mov_b32_e32 v101, v56
	v_and_b32_e32 v83, 0xffff0000, v57
	v_lshlrev_b32_e32 v98, 16, v58
	s_waitcnt lgkmcnt(0)
	v_permlane32_swap_b32_e32 v56, v101
	v_add_f32_e32 v56, v56, v101
	v_fmamk_f32 v56, v56, 0x3a800000, v90
	v_mul_f32_e32 v57, 0x4f800000, v56
	v_cmp_gt_f32_e32 vcc, s8, v56
	v_and_b32_e32 v101, 0xffff0000, v59
	s_waitcnt vmcnt(0)
	v_lshlrev_b32_e32 v104, 16, v33
	v_cndmask_b32_e32 v58, v56, v57, vcc
	v_sqrt_f32_e32 v102, v58
	v_mov_b32_e32 v56, v68
	v_mov_b32_e32 v57, v70
	v_and_b32_e32 v105, 0xffff0000, v33
	v_add_u32_e32 v59, -1, v102
	v_add_u32_e32 v68, 1, v102
	v_fma_f32 v70, -v59, v102, v58
	v_fma_f32 v103, -v68, v102, v58
	v_cmp_ge_f32_e64 s[0:1], 0, v70
	v_mov_b32_e32 v70, v69
	s_nop 0
	v_cndmask_b32_e64 v59, v102, v59, s[0:1]
	v_cmp_lt_f32_e64 s[0:1], 0, v103
	s_nop 1
	v_cndmask_b32_e64 v59, v59, v68, s[0:1]
	v_mul_f32_e32 v68, 0x37800000, v59
	v_cndmask_b32_e32 v59, v59, v68, vcc
	v_cmp_class_f32_e32 vcc, v58, v91
	s_nop 1
	v_cndmask_b32_e32 v58, v59, v58, vcc
	v_div_scale_f32 v59, s[0:1], v58, v58, 1.0
	v_rcp_f32_e32 v68, v59
	v_div_scale_f32 v69, vcc, 1.0, v58, 1.0
	v_fma_f32 v102, -v59, v68, 1.0
	v_fmac_f32_e32 v68, v102, v68
	v_mul_f32_e32 v102, v69, v68
	v_fma_f32 v103, -v59, v102, v69
	v_fmac_f32_e32 v102, v103, v68
	v_fma_f32 v59, -v59, v102, v69
	v_div_fmas_f32 v59, v59, v68, v102
	v_div_fixup_f32 v58, v59, v58, 1.0
	v_pk_mul_f32 v[64:65], v[58:59], v[64:65] op_sel_hi:[0,1]
	v_pk_mul_f32 v[66:67], v[58:59], v[66:67] op_sel_hi:[0,1]
	v_pk_mul_f32 v[68:69], v[58:59], v[56:57] op_sel_hi:[0,1]
	v_pk_mul_f32 v[56:57], v[58:59], v[70:71] op_sel_hi:[0,1]
	v_pk_mul_f32 v[70:71], v[58:59], v[72:73] op_sel_hi:[0,1]
	v_pk_mul_f32 v[72:73], v[58:59], v[74:75] op_sel_hi:[0,1]
	v_pk_mul_f32 v[102:103], v[58:59], v[48:49] op_sel_hi:[0,1]
	v_pk_mul_f32 v[50:51], v[58:59], v[50:51] op_sel_hi:[0,1]
	v_pk_fma_f32 v[48:49], v[2:3], v[66:67], v[52:53]
	v_pk_fma_f32 v[52:53], v[0:1], v[64:65], v[76:77]
	v_pk_fma_f32 v[56:57], v[6:7], v[56:57], v[54:55]
	v_pk_fma_f32 v[58:59], v[4:5], v[68:69], v[78:79]
	v_pk_fma_f32 v[74:75], v[14:15], v[50:51], v[100:101]
	v_pk_mul_f32 v[50:51], v[48:49], v[48:49]
	v_pk_mul_f32 v[54:55], v[52:53], v[52:53]
	v_pk_mul_f32 v[66:67], v[56:57], v[56:57]
	v_pk_mul_f32 v[68:69], v[58:59], v[58:59]
	v_pk_fma_f32 v[64:65], v[10:11], v[72:73], v[82:83]
	v_pk_fma_f32 v[70:71], v[8:9], v[70:71], v[80:81]
	v_pk_mov_b32 v[80:81], v[54:55], v[50:51] op_sel:[1,0]
	v_mov_b32_e32 v55, v51
	v_pk_mov_b32 v[50:51], v[68:69], v[66:67] op_sel:[1,0]
	v_mov_b32_e32 v69, v67
	v_mul_f32_e32 v72, v70, v70
	v_mul_f32_e32 v76, v64, v64
	v_pk_add_f32 v[54:55], v[80:81], v[54:55]
	v_pk_add_f32 v[50:51], v[50:51], v[68:69]
	v_pk_fma_f32 v[78:79], v[12:13], v[102:103], v[98:99]
	v_pk_fma_f32 v[66:67], v[70:71], v[70:71], v[72:73] op_sel_hi:[1,1,0]
	v_pk_fma_f32 v[72:73], v[64:65], v[64:65], v[76:77] op_sel_hi:[1,1,0]
	v_pk_add_f32 v[54:55], v[54:55], v[54:55] op_sel_hi:[0,1]
	v_pk_add_f32 v[50:51], v[50:51], v[50:51] op_sel_hi:[0,1]
	v_mul_f32_e32 v66, v78, v78
	v_mul_f32_e32 v72, v79, v79
	v_mul_f32_e32 v54, v74, v74
	v_mul_f32_e32 v50, v75, v75
	v_pk_add_f32 v[66:67], v[66:67], v[72:73]
	v_pk_add_f32 v[50:51], v[54:55], v[50:51]
	v_lshlrev_b32_e32 v82, 16, v60
	v_pk_add_f32 v[50:51], v[66:67], v[50:51]
	v_and_b32_e32 v83, 0xffff0000, v60
	v_add_f32_e32 v50, v50, v51
	s_nop 1
	v_lshlrev_b32_e32 v80, 16, v61
	v_and_b32_e32 v81, 0xffff0000, v61
	v_lshlrev_b32_e32 v66, 16, v92
	v_and_b32_e32 v67, 0xffff0000, v92
	s_waitcnt lgkmcnt(0)
	v_add_f32_dpp v50, v50, v50 quad_perm:[1,0,3,2] row_mask:0xf bank_mask:0xf
	s_nop 1
	v_lshlrev_b32_e32 v76, 16, v62
	v_and_b32_e32 v77, 0xffff0000, v62
	v_lshlrev_b32_e32 v72, 16, v63
	v_and_b32_e32 v73, 0xffff0000, v63
	s_waitcnt lgkmcnt(0)
	v_add_f32_dpp v50, v50, v50 quad_perm:[2,3,0,1] row_mask:0xf bank_mask:0xf
	s_nop 1
	v_lshlrev_b32_e32 v62, 16, v93
	v_and_b32_e32 v63, 0xffff0000, v93
	v_lshlrev_b32_e32 v68, 16, v35
	v_and_b32_e32 v69, 0xffff0000, v35
	s_waitcnt lgkmcnt(0)
	v_add_f32_dpp v60, v50, v50 row_half_mirror row_mask:0xf bank_mask:0xf
	s_nop 1
	v_lshlrev_b32_e32 v54, 16, v94
	v_and_b32_e32 v55, 0xffff0000, v94
	v_lshlrev_b32_e32 v50, 16, v95
	v_and_b32_e32 v51, 0xffff0000, v95
	s_waitcnt lgkmcnt(0)
	v_add_f32_dpp v92, v60, v60 row_mirror row_mask:0xf bank_mask:0xf
	v_mov_b32_e32 v93, v92
	v_lshlrev_b32_e32 v60, 16, v34
	v_and_b32_e32 v61, 0xffff0000, v34
	v_lshlrev_b32_e32 v100, 16, v32
	v_and_b32_e32 v101, 0xffff0000, v32
	s_waitcnt lgkmcnt(0)
	v_permlane16_swap_b32_e32 v92, v93
	v_add_f32_e32 v34, v92, v93
	v_mov_b32_e32 v35, v34
	v_cvt_pk_bf16_f32 v92, v52, v53
	v_cvt_pk_bf16_f32 v93, v48, v49
	v_cvt_pk_bf16_f32 v94, v58, v59
	v_cvt_pk_bf16_f32 v95, v56, v57
	s_waitcnt lgkmcnt(0)
	v_permlane32_swap_b32_e32 v34, v35
	v_add_f32_e32 v34, v34, v35
	v_fmamk_f32 v34, v34, 0x3a800000, v90
	v_mul_f32_e32 v35, 0x4f800000, v34
	v_cmp_gt_f32_e32 vcc, s8, v34
	global_store_dwordx4 v[96:97], v[92:95], off
	v_mul_f32_e32 v32, v100, v100
	v_cndmask_b32_e32 v34, v34, v35, vcc
	v_sqrt_f32_e32 v35, v34
	v_cvt_pk_bf16_f32 v92, v70, v71
	v_cvt_pk_bf16_f32 v93, v64, v65
	v_pk_fma_f32 v[102:103], v[100:101], v[100:101], v[32:33] op_sel_hi:[1,1,0]
	v_add_u32_e32 v94, -1, v35
	v_add_u32_e32 v95, 1, v35
	v_fma_f32 v98, -v94, v35, v34
	v_fma_f32 v99, -v95, v35, v34
	v_cmp_ge_f32_e64 s[0:1], 0, v98
	v_mul_f32_e32 v32, v104, v104
	v_pk_fma_f32 v[32:33], v[104:105], v[104:105], v[32:33] op_sel_hi:[1,1,0]
	v_cndmask_b32_e64 v35, v35, v94, s[0:1]
	v_cmp_lt_f32_e64 s[0:1], 0, v99
	v_mul_f32_e32 v102, v68, v68
	v_mul_f32_e32 v32, v69, v69
	v_cndmask_b32_e64 v35, v35, v95, s[0:1]
	v_mul_f32_e32 v94, 0x37800000, v35
	v_cndmask_b32_e32 v35, v35, v94, vcc
	v_cmp_class_f32_e32 vcc, v34, v91
	v_cvt_pk_bf16_f32 v94, v78, v79
	v_cvt_pk_bf16_f32 v95, v74, v75
	global_store_dwordx4 v[96:97], v[92:95], off offset:1024
	v_lshlrev_b32_e32 v97, 16, v39
	v_cndmask_b32_e32 v108, v35, v34, vcc
	v_div_scale_f32 v34, s[0:1], v108, v108, 1.0
	v_rcp_f32_e32 v109, v34
	v_and_b32_e32 v93, 0xffff0000, v36
	v_lshlrev_b32_e32 v96, 16, v38
	v_and_b32_e32 v39, 0xffff0000, v39
	v_fma_f32 v35, -v34, v109, 1.0
	v_fmac_f32_e32 v109, v35, v109
	v_div_scale_f32 v35, vcc, 1.0, v108, 1.0
	v_mul_f32_e32 v110, v35, v109
	v_fma_f32 v92, -v34, v110, v35
	v_fmac_f32_e32 v110, v92, v109
	v_lshlrev_b32_e32 v92, 16, v36
	v_lshlrev_b32_e32 v36, 16, v37
	v_and_b32_e32 v38, 0xffff0000, v38
	v_fma_f32 v111, -v34, v110, v35
	v_mul_f32_e32 v34, v92, v92
	v_and_b32_e32 v37, 0xffff0000, v37
	v_mul_f32_e32 v94, v36, v36
	v_pk_mul_f32 v[98:99], v[38:39], v[38:39]
	v_pk_fma_f32 v[34:35], v[92:93], v[92:93], v[34:35] op_sel_hi:[1,1,0]
	v_pk_fma_f32 v[94:95], v[36:37], v[36:37], v[94:95] op_sel_hi:[1,1,0]
	v_pk_fma_f32 v[98:99], v[96:97], v[96:97], v[98:99]
	v_pk_add_f32 v[34:35], v[34:35], v[94:95]
	v_pk_add_f32 v[98:99], v[98:99], v[98:99] op_sel_hi:[0,1]
	v_mul_f32_e32 v98, v61, v61
	v_mul_f32_e32 v106, v60, v60
	v_mov_b32_e32 v107, v35
	v_pk_add_f32 v[34:35], v[106:107], v[98:99]
	v_pk_add_f32 v[32:33], v[102:103], v[32:33]
	s_nop 0
	v_pk_add_f32 v[32:33], v[34:35], v[32:33]
	s_nop 0
	v_add_f32_e32 v33, v32, v33
	s_nop 1
	v_div_fmas_f32 v32, v111, v109, v110
	v_div_fixup_f32 v32, v32, v108, 1.0
	v_pk_mul_f32 v[34:35], v[78:79], v[32:33] op_sel_hi:[1,0]
	s_waitcnt lgkmcnt(0)
	v_add_f32_dpp v33, v33, v33 quad_perm:[1,0,3,2] row_mask:0xf bank_mask:0xf
	s_nop 1
	v_pk_mul_f32 v[74:75], v[74:75], v[32:33] op_sel_hi:[1,0]
	v_pk_mul_f32 v[78:79], v[28:29], v[34:35]
	v_pk_mul_f32 v[34:35], v[70:71], v[32:33] op_sel_hi:[1,0]
	v_pk_mul_f32 v[74:75], v[30:31], v[74:75]
	s_waitcnt lgkmcnt(0)
	v_add_f32_dpp v33, v33, v33 quad_perm:[2,3,0,1] row_mask:0xf bank_mask:0xf
	s_nop 1
	v_pk_mul_f32 v[64:65], v[64:65], v[32:33] op_sel_hi:[1,0]
	v_pk_mul_f32 v[70:71], v[24:25], v[34:35]
	v_pk_mul_f32 v[34:35], v[58:59], v[32:33] op_sel_hi:[1,0]
	v_pk_mul_f32 v[64:65], v[26:27], v[64:65]
	s_waitcnt lgkmcnt(0)
	v_add_f32_dpp v33, v33, v33 row_half_mirror row_mask:0xf bank_mask:0xf
	s_nop 1
	v_pk_mul_f32 v[56:57], v[56:57], v[32:33] op_sel_hi:[1,0]
	v_pk_mul_f32 v[52:53], v[52:53], v[32:33] op_sel_hi:[1,0]
	v_pk_mul_f32 v[34:35], v[20:21], v[34:35]
	v_pk_mul_f32 v[56:57], v[22:23], v[56:57]
	s_waitcnt lgkmcnt(0)
	v_add_f32_dpp v58, v33, v33 row_mirror row_mask:0xf bank_mask:0xf
	v_mov_b32_e32 v59, v58
	v_pk_mul_f32 v[32:33], v[48:49], v[32:33] op_sel_hi:[1,0]
	s_waitcnt lgkmcnt(0)
	v_permlane16_swap_b32_e32 v58, v59
	v_add_f32_e32 v58, v58, v59
	v_mov_b32_e32 v59, v58
	v_pk_mul_f32 v[48:49], v[18:19], v[32:33]
	v_pk_mul_f32 v[32:33], v[16:17], v[52:53]
	v_lshl_add_u64 v[52:53], v[44:45], 0, s[6:7]
	v_cvt_pk_bf16_f32 v32, v32, v33
	v_cvt_pk_bf16_f32 v33, v48, v49
	s_waitcnt lgkmcnt(0)
	v_permlane32_swap_b32_e32 v58, v59
	v_add_f32_e32 v48, v58, v59
	v_fmamk_f32 v48, v48, 0x3a800000, v90
	v_mul_f32_e32 v49, 0x4f800000, v48
	v_cmp_gt_f32_e32 vcc, s8, v48
	v_cvt_pk_bf16_f32 v34, v34, v35
	v_cvt_pk_bf16_f32 v35, v56, v57
	global_store_dwordx4 v[52:53], v[32:35], off
	s_mov_b64 s[6:7], -1
	v_cndmask_b32_e32 v48, v48, v49, vcc
	v_sqrt_f32_e32 v49, v48
	v_cvt_pk_bf16_f32 v32, v70, v71
	v_cvt_pk_bf16_f32 v33, v64, v65
	s_nop 0
	v_add_u32_e32 v34, -1, v49
	v_fma_f32 v35, -v34, v49, v48
	v_cmp_ge_f32_e64 s[0:1], 0, v35
	v_add_u32_e32 v35, 1, v49
	s_nop 0
	v_cndmask_b32_e64 v34, v49, v34, s[0:1]
	v_fma_f32 v49, -v35, v49, v48
	v_cmp_lt_f32_e64 s[0:1], 0, v49
	s_nop 1
	v_cndmask_b32_e64 v34, v34, v35, s[0:1]
	v_mul_f32_e32 v35, 0x37800000, v34
	v_cndmask_b32_e32 v34, v34, v35, vcc
	v_cmp_class_f32_e32 vcc, v48, v91
	s_nop 1
	v_cndmask_b32_e32 v48, v34, v48, vcc
	v_div_scale_f32 v49, s[0:1], v48, v48, 1.0
	v_rcp_f32_e32 v56, v49
	v_cvt_pk_bf16_f32 v34, v78, v79
	v_cvt_pk_bf16_f32 v35, v74, v75
	global_store_dwordx4 v[52:53], v[32:35], off offset:1024
	s_cselect_b64 s[0:1], -1, 0
	s_nop 0
	v_fma_f32 v32, -v49, v56, 1.0
	v_fmac_f32_e32 v56, v32, v56
	v_div_scale_f32 v32, vcc, 1.0, v48, 1.0
	v_mul_f32_e32 v33, v32, v56
	v_fma_f32 v34, -v49, v33, v32
	v_fmac_f32_e32 v33, v34, v56
	v_fma_f32 v32, -v49, v33, v32
	v_div_fmas_f32 v32, v32, v56, v33
	v_div_fixup_f32 v56, v32, v48, 1.0
	v_pk_mul_f32 v[32:33], v[56:57], v[36:37] op_sel_hi:[0,1]
	v_mov_b32_e32 v36, v97
	v_mov_b32_e32 v37, v39
	v_mov_b32_e32 v97, v38
	v_pk_mul_f32 v[34:35], v[56:57], v[92:93] op_sel_hi:[0,1]
	v_pk_mul_f32 v[36:37], v[56:57], v[36:37] op_sel_hi:[0,1]
	v_pk_mul_f32 v[38:39], v[56:57], v[96:97] op_sel_hi:[0,1]
	v_pk_mul_f32 v[48:49], v[56:57], v[104:105] op_sel_hi:[0,1]
	v_pk_mul_f32 v[52:53], v[56:57], v[100:101] op_sel_hi:[0,1]
	v_pk_mul_f32 v[58:59], v[56:57], v[68:69] op_sel_hi:[0,1]
	v_pk_mul_f32 v[56:57], v[56:57], v[60:61] op_sel_hi:[0,1]
	v_pk_fma_f32 v[34:35], v[0:1], v[34:35], v[82:83]
	v_pk_fma_f32 v[32:33], v[2:3], v[32:33], v[80:81]
	v_pk_fma_f32 v[38:39], v[4:5], v[38:39], v[76:77]
	v_pk_fma_f32 v[36:37], v[6:7], v[36:37], v[72:73]
	v_pk_fma_f32 v[52:53], v[8:9], v[52:53], v[66:67]
	v_pk_fma_f32 v[48:49], v[10:11], v[48:49], v[62:63]
	v_pk_fma_f32 v[54:55], v[12:13], v[56:57], v[54:55]
	v_pk_fma_f32 v[50:51], v[14:15], v[58:59], v[50:51]
	s_and_b64 vcc, exec, s[0:1]
	s_cbranch_vccnz .LBB0_1341
	s_mov_b64 s[6:7], 0

.LBB0_1343:
	s_nop 1
	v_mul_f32_e32 v56, v34, v34
	v_mul_f32_e32 v57, v32, v32
	v_fmac_f32_e32 v56, v35, v35
	v_fmac_f32_e32 v57, v33, v33
	v_add_f32_e32 v56, v57, v56
	v_mul_f32_e32 v57, v38, v38
	v_mul_f32_e32 v58, v36, v36
	v_fmac_f32_e32 v57, v39, v39
	v_fmac_f32_e32 v58, v37, v37
	v_add_f32_e32 v57, v58, v57
	v_add_f32_e32 v56, v57, v56
	v_mul_f32_e32 v57, v52, v52
	v_mul_f32_e32 v58, v48, v48
	v_fmac_f32_e32 v57, v53, v53
	v_fmac_f32_e32 v58, v49, v49
	v_add_f32_e32 v57, v58, v57
	v_add_f32_e32 v56, v57, v56
	v_mul_f32_e32 v57, v54, v54
	v_mul_f32_e32 v58, v50, v50
	v_fmac_f32_e32 v57, v55, v55
	v_fmac_f32_e32 v58, v51, v51
	v_add_f32_e32 v57, v58, v57
	v_add_f32_e32 v56, v57, v56
	s_nop 1
	s_andn2_b64 vcc, exec, s[0:1]
	s_waitcnt lgkmcnt(0)
	v_add_f32_dpp v56, v56, v56 quad_perm:[1,0,3,2] row_mask:0xf bank_mask:0xf
	s_nop 1
	s_waitcnt lgkmcnt(0)
	v_add_f32_dpp v56, v56, v56 quad_perm:[2,3,0,1] row_mask:0xf bank_mask:0xf
	s_nop 1
	s_waitcnt lgkmcnt(0)
	v_add_f32_dpp v56, v56, v56 row_half_mirror row_mask:0xf bank_mask:0xf
	s_nop 1
	s_waitcnt lgkmcnt(0)
	v_add_f32_dpp v56, v56, v56 row_mirror row_mask:0xf bank_mask:0xf
	v_mov_b32_e32 v57, v56
	s_waitcnt lgkmcnt(0)
	s_nop 0
	v_permlane16_swap_b32_e32 v56, v57
	v_add_f32_e32 v56, v56, v57
	ds_bpermute_b32 v57, v89, v56
	s_cbranch_vccnz .LBB0_1338
	s_waitcnt lgkmcnt(0)
	v_add_f32_e32 v56, v56, v57
	v_fmamk_f32 v56, v56, 0x3a800000, v90
	v_mul_f32_e32 v57, 0x4f800000, v56
	v_cmp_gt_f32_e32 vcc, s8, v56
	s_ashr_i32 s5, s4, 31
	s_nop 0
	v_cndmask_b32_e32 v56, v56, v57, vcc
	v_sqrt_f32_e32 v57, v56
	s_nop 0
	v_add_u32_e32 v58, -1, v57
	v_fma_f32 v60, -v58, v57, v56
	v_add_u32_e32 v59, 1, v57
	v_cmp_ge_f32_e64 s[0:1], 0, v60
	s_nop 1
	v_cndmask_b32_e64 v58, v57, v58, s[0:1]
	v_fma_f32 v57, -v59, v57, v56
	v_cmp_lt_f32_e64 s[0:1], 0, v57
	s_nop 1
	v_cndmask_b32_e64 v57, v58, v59, s[0:1]
	v_mul_f32_e32 v58, 0x37800000, v57
	v_cndmask_b32_e32 v57, v57, v58, vcc
	v_cmp_class_f32_e32 vcc, v56, v91
	s_nop 1
	v_cndmask_b32_e32 v56, v57, v56, vcc
	v_div_scale_f32 v57, s[0:1], v56, v56, 1.0
	v_rcp_f32_e32 v58, v57
	s_lshl_b64 s[0:1], s[4:5], 11
	v_fma_f32 v59, -v57, v58, 1.0
	v_fmac_f32_e32 v58, v59, v58
	v_div_scale_f32 v59, vcc, 1.0, v56, 1.0
	v_mul_f32_e32 v60, v59, v58
	v_fma_f32 v61, -v57, v60, v59
	v_fmac_f32_e32 v60, v61, v58
	v_fma_f32 v57, -v57, v60, v59
	v_div_fmas_f32 v57, v57, v58, v60
	v_div_fixup_f32 v56, v57, v56, 1.0
	v_pk_mul_f32 v[34:35], v[34:35], v[56:57] op_sel_hi:[1,0]
	v_pk_mul_f32 v[32:33], v[32:33], v[56:57] op_sel_hi:[1,0]
	v_pk_mul_f32 v[54:55], v[54:55], v[56:57] op_sel_hi:[1,0]
	v_pk_mul_f32 v[50:51], v[50:51], v[56:57] op_sel_hi:[1,0]
	v_pk_mul_f32 v[52:53], v[52:53], v[56:57] op_sel_hi:[1,0]
	v_pk_mul_f32 v[48:49], v[48:49], v[56:57] op_sel_hi:[1,0]
	v_pk_mul_f32 v[38:39], v[38:39], v[56:57] op_sel_hi:[1,0]
	v_pk_mul_f32 v[36:37], v[36:37], v[56:57] op_sel_hi:[1,0]
	v_pk_mul_f32 v[56:57], v[18:19], v[32:33]
	v_pk_mul_f32 v[32:33], v[16:17], v[34:35]
	v_pk_mul_f32 v[36:37], v[22:23], v[36:37]
	v_pk_mul_f32 v[38:39], v[20:21], v[38:39]
	v_lshl_add_u64 v[58:59], v[44:45], 0, s[0:1]
	v_cvt_pk_bf16_f32 v32, v32, v33
	v_cvt_pk_bf16_f32 v33, v56, v57
	v_cvt_pk_bf16_f32 v34, v38, v39
	v_cvt_pk_bf16_f32 v35, v36, v37
	v_pk_mul_f32 v[50:51], v[30:31], v[50:51]
	v_pk_mul_f32 v[54:55], v[28:29], v[54:55]
	v_pk_mul_f32 v[48:49], v[26:27], v[48:49]
	v_pk_mul_f32 v[52:53], v[24:25], v[52:53]
	global_store_dwordx4 v[58:59], v[32:35], off
	s_nop 1
	v_cvt_pk_bf16_f32 v32, v52, v53
	v_cvt_pk_bf16_f32 v33, v48, v49
	v_cvt_pk_bf16_f32 v34, v54, v55
	v_cvt_pk_bf16_f32 v35, v50, v51
	global_store_dwordx4 v[58:59], v[32:35], off offset:1024
	s_branch .LBB0_1338

.LBB0_1553:
	s_ashr_i32 s5, s4, 31
	s_lshl_b64 s[0:1], s[4:5], 11
	v_lshl_add_u64 v[36:37], v[40:41], 0, s[0:1]
	global_load_dwordx4 v[32:35], v[36:37], off
	global_load_dwordx4 v[46:49], v[36:37], off offset:1024
	v_lshl_add_u64 v[36:37], v[42:43], 0, s[0:1]
	s_add_i32 s6, s4, s83
	s_waitcnt lgkmcnt(0)
	global_load_dwordx4 v[50:53], v[36:37], off
	global_load_dwordx4 v[54:57], v[36:37], off offset:1024
	s_min_i32 s0, s6, 0xffff
	s_ashr_i32 s1, s0, 31
	s_lshl_b64 s[0:1], s[0:1], 11
	v_lshl_add_u64 v[58:59], v[42:43], 0, s[0:1]
	global_load_dwordx4 v[36:39], v[58:59], off
	s_waitcnt vmcnt(0)
	v_and_b32_e32 v61, 0xffff0000, v32
	v_and_b32_e32 v63, 0xffff0000, v33
	v_and_b32_e32 v65, 0xffff0000, v34
	v_and_b32_e32 v83, 0xffff0000, v35
	v_lshlrev_b32_e32 v60, 16, v32
	v_lshlrev_b32_e32 v62, 16, v33
	v_lshlrev_b32_e32 v64, 16, v34
	v_lshlrev_b32_e32 v82, 16, v35
	v_and_b32_e32 v85, 0xffff0000, v46
	v_and_b32_e32 v87, 0xffff0000, v47
	v_mul_f32_e32 v32, v61, v61
	v_mul_f32_e32 v33, v63, v63
	v_mul_f32_e32 v34, v65, v65
	v_mul_f32_e32 v35, v83, v83
	v_lshlrev_b32_e32 v84, 16, v46
	v_lshlrev_b32_e32 v86, 16, v47
	v_and_b32_e32 v89, 0xffff0000, v48
	v_and_b32_e32 v91, 0xffff0000, v49
	v_mul_f32_e32 v46, v85, v85
	v_mul_f32_e32 v47, v87, v87
	v_fmac_f32_e32 v32, v60, v60
	v_fmac_f32_e32 v33, v62, v62
	v_fmac_f32_e32 v34, v64, v64
	v_fmac_f32_e32 v35, v82, v82
	v_lshlrev_b32_e32 v88, 16, v48
	v_lshlrev_b32_e32 v90, 16, v49
	v_mul_f32_e32 v48, v89, v89
	v_mul_f32_e32 v49, v91, v91
	v_fmac_f32_e32 v46, v84, v84
	v_fmac_f32_e32 v47, v86, v86
	v_add_f32_e32 v32, v32, v33
	v_add_f32_e32 v33, v34, v35
	v_fmac_f32_e32 v48, v88, v88
	v_fmac_f32_e32 v49, v90, v90
	v_add_f32_e32 v34, v46, v47
	v_add_f32_e32 v32, v32, v33
	v_add_f32_e32 v35, v48, v49
	v_add_f32_e32 v32, v32, v34
	v_add_f32_e32 v48, v35, v32
	s_nop 1
	global_load_dwordx4 v[32:35], v[58:59], off offset:1024
	v_lshl_add_u64 v[46:47], v[40:41], 0, s[0:1]
	global_load_dwordx4 v[66:69], v[46:47], off
	global_load_dwordx4 v[78:81], v[46:47], off offset:1024
	v_lshlrev_b32_e32 v58, 16, v50
	s_waitcnt lgkmcnt(0)
	v_add_f32_dpp v48, v48, v48 quad_perm:[1,0,3,2] row_mask:0xf bank_mask:0xf
	s_nop 1
	v_and_b32_e32 v59, 0xffff0000, v50
	v_lshlrev_b32_e32 v92, 16, v51
	v_and_b32_e32 v93, 0xffff0000, v51
	v_lshlrev_b32_e32 v94, 16, v52
	s_waitcnt lgkmcnt(0)
	v_add_f32_dpp v46, v48, v48 quad_perm:[2,3,0,1] row_mask:0xf bank_mask:0xf
	s_nop 1
	v_lshlrev_b32_e32 v48, 16, v37
	v_and_b32_e32 v95, 0xffff0000, v52
	v_lshlrev_b32_e32 v96, 16, v53
	v_and_b32_e32 v97, 0xffff0000, v53
	s_waitcnt lgkmcnt(0)
	v_add_f32_dpp v46, v46, v46 row_half_mirror row_mask:0xf bank_mask:0xf
	s_nop 1
	v_lshlrev_b32_e32 v98, 16, v54
	v_and_b32_e32 v99, 0xffff0000, v54
	v_lshlrev_b32_e32 v100, 16, v55
	v_and_b32_e32 v101, 0xffff0000, v55
	s_waitcnt lgkmcnt(0)
	v_add_f32_dpp v46, v46, v46 row_mirror row_mask:0xf bank_mask:0xf
	v_mov_b32_e32 v47, v46
	v_lshlrev_b32_e32 v102, 16, v56
	v_and_b32_e32 v103, 0xffff0000, v56
	v_lshlrev_b32_e32 v104, 16, v57
	v_and_b32_e32 v105, 0xffff0000, v57
	s_waitcnt lgkmcnt(0)
	v_permlane16_swap_b32_e32 v46, v47
	v_add_f32_e32 v49, v46, v47
	v_mov_b32_e32 v50, v49
	v_lshlrev_b32_e32 v46, 16, v36
	v_and_b32_e32 v47, 0xffff0000, v36
	s_waitcnt lgkmcnt(0)
	v_permlane32_swap_b32_e32 v49, v50
	v_add_f32_e32 v36, v49, v50
	v_fmamk_f32 v36, v36, 0x3a800000, v76
	v_mul_f32_e32 v49, 0x4f800000, v36
	v_cmp_gt_f32_e32 vcc, s8, v36
	s_nop 1
	v_cndmask_b32_e32 v50, v36, v49, vcc
	v_sqrt_f32_e32 v51, v50
	v_and_b32_e32 v49, 0xffff0000, v37
	v_lshlrev_b32_e32 v36, 16, v38
	v_and_b32_e32 v37, 0xffff0000, v38
	v_add_u32_e32 v38, -1, v51
	v_add_u32_e32 v52, 1, v51
	v_fma_f32 v53, -v38, v51, v50
	v_fma_f32 v54, -v52, v51, v50
	v_cmp_ge_f32_e64 s[0:1], 0, v53
	s_nop 1
	v_cndmask_b32_e64 v38, v51, v38, s[0:1]
	v_cmp_lt_f32_e64 s[0:1], 0, v54
	s_nop 1
	v_cndmask_b32_e64 v38, v38, v52, s[0:1]
	v_mul_f32_e32 v51, 0x37800000, v38
	v_cndmask_b32_e32 v38, v38, v51, vcc
	v_cmp_class_f32_e32 vcc, v50, v77
	s_nop 1
	v_cndmask_b32_e32 v50, v38, v50, vcc
	v_div_scale_f32 v51, s[0:1], v50, v50, 1.0
	v_rcp_f32_e32 v52, v51
	v_div_scale_f32 v53, vcc, 1.0, v50, 1.0
	v_lshlrev_b32_e32 v38, 16, v39
	v_fma_f32 v54, -v51, v52, 1.0
	v_fmac_f32_e32 v52, v54, v52
	v_mul_f32_e32 v54, v53, v52
	v_fma_f32 v55, -v51, v54, v53
	v_fmac_f32_e32 v54, v55, v52
	v_fma_f32 v51, -v51, v54, v53
	v_div_fmas_f32 v51, v51, v52, v54
	v_div_fixup_f32 v50, v51, v50, 1.0
	v_mul_f32_e32 v50, 0.5, v50
	v_pk_mul_f32 v[52:53], v[50:51], v[62:63] op_sel_hi:[0,1]
	v_pk_mul_f32 v[54:55], v[50:51], v[60:61] op_sel_hi:[0,1]
	v_pk_mul_f32 v[56:57], v[50:51], v[82:83] op_sel_hi:[0,1]
	v_pk_mul_f32 v[60:61], v[50:51], v[64:65] op_sel_hi:[0,1]
	v_pk_mul_f32 v[62:63], v[50:51], v[84:85] op_sel_hi:[0,1]
	v_pk_mul_f32 v[64:65], v[50:51], v[86:87] op_sel_hi:[0,1]
	v_pk_mul_f32 v[82:83], v[50:51], v[88:89] op_sel_hi:[0,1]
	v_pk_mul_f32 v[84:85], v[50:51], v[90:91] op_sel_hi:[0,1]
	v_pk_fma_f32 v[50:51], v[0:1], v[54:55], v[58:59]
	v_pk_fma_f32 v[52:53], v[2:3], v[52:53], v[92:93]
	v_pk_fma_f32 v[54:55], v[4:5], v[60:61], v[94:95]
	v_pk_fma_f32 v[56:57], v[6:7], v[56:57], v[96:97]
	v_pk_fma_f32 v[58:59], v[10:11], v[64:65], v[100:101]
	v_pk_fma_f32 v[60:61], v[8:9], v[62:63], v[98:99]
	v_pk_fma_f32 v[62:63], v[14:15], v[84:85], v[104:105]
	v_pk_fma_f32 v[64:65], v[12:13], v[82:83], v[102:103]
	v_pk_mul_f32 v[82:83], v[52:53], v[52:53]
	v_pk_mul_f32 v[84:85], v[50:51], v[50:51]
	v_pk_mul_f32 v[86:87], v[56:57], v[56:57]
	v_pk_mul_f32 v[88:89], v[54:55], v[54:55]
	v_pk_mov_b32 v[94:95], v[84:85], v[82:83] op_sel:[1,0]
	v_mov_b32_e32 v85, v83
	v_pk_mov_b32 v[82:83], v[88:89], v[86:87] op_sel:[1,0]
	v_mov_b32_e32 v89, v87
	v_mul_f32_e32 v90, v60, v60
	v_mul_f32_e32 v92, v58, v58
	v_pk_add_f32 v[84:85], v[94:95], v[84:85]
	v_pk_add_f32 v[82:83], v[82:83], v[88:89]
	v_pk_fma_f32 v[86:87], v[60:61], v[60:61], v[90:91] op_sel_hi:[1,1,0]
	v_pk_fma_f32 v[90:91], v[58:59], v[58:59], v[92:93] op_sel_hi:[1,1,0]
	v_pk_add_f32 v[84:85], v[84:85], v[84:85] op_sel_hi:[0,1]
	v_pk_add_f32 v[82:83], v[82:83], v[82:83] op_sel_hi:[0,1]
	v_mul_f32_e32 v86, v64, v64
	v_mul_f32_e32 v90, v65, v65
	v_mul_f32_e32 v84, v62, v62
	v_mul_f32_e32 v82, v63, v63
	v_pk_add_f32 v[86:87], v[86:87], v[90:91]
	v_pk_add_f32 v[82:83], v[84:85], v[82:83]
	s_waitcnt vmcnt(2)
	v_lshlrev_b32_e32 v84, 16, v33
	v_pk_add_f32 v[82:83], v[86:87], v[82:83]
	s_waitcnt vmcnt(0)
	v_lshlrev_b32_e32 v90, 16, v78
	v_add_f32_e32 v85, v82, v83
	s_nop 1
	v_lshlrev_b32_e32 v82, 16, v32
	v_and_b32_e32 v83, 0xffff0000, v32
	v_lshlrev_b32_e32 v32, 16, v34
	v_lshlrev_b32_e32 v92, 16, v80
	s_waitcnt lgkmcnt(0)
	v_add_f32_dpp v87, v85, v85 quad_perm:[1,0,3,2] row_mask:0xf bank_mask:0xf
	s_nop 1
	v_and_b32_e32 v85, 0xffff0000, v33
	v_and_b32_e32 v33, 0xffff0000, v34
	v_lshlrev_b32_e32 v86, 16, v66
	v_and_b32_e32 v39, 0xffff0000, v39
	s_waitcnt lgkmcnt(0)
	v_add_f32_dpp v34, v87, v87 quad_perm:[2,3,0,1] row_mask:0xf bank_mask:0xf
	s_nop 1
	v_and_b32_e32 v87, 0xffff0000, v66
	v_lshlrev_b32_e32 v66, 16, v67
	v_and_b32_e32 v67, 0xffff0000, v67
	v_mul_f32_e32 v95, v87, v87
	s_waitcnt lgkmcnt(0)
	v_add_f32_dpp v34, v34, v34 row_half_mirror row_mask:0xf bank_mask:0xf
	s_nop 1
	v_mul_f32_e32 v96, v67, v67
	v_lshlrev_b32_e32 v88, 16, v68
	v_and_b32_e32 v89, 0xffff0000, v68
	v_lshlrev_b32_e32 v68, 16, v69
	v_and_b32_e32 v69, 0xffff0000, v69
	s_waitcnt lgkmcnt(0)
	v_add_f32_dpp v34, v34, v34 row_mirror row_mask:0xf bank_mask:0xf
	v_fmac_f32_e32 v95, v86, v86
	v_fmac_f32_e32 v96, v66, v66
	v_mov_b32_e32 v93, v34
	v_add_f32_e32 v95, v95, v96
	v_mul_f32_e32 v96, v89, v89
	v_mul_f32_e32 v97, v69, v69
	v_fmac_f32_e32 v96, v88, v88
	v_fmac_f32_e32 v97, v68, v68
	v_and_b32_e32 v91, 0xffff0000, v78
	v_lshlrev_b32_e32 v78, 16, v79
	v_and_b32_e32 v79, 0xffff0000, v79
	v_add_f32_e32 v96, v96, v97
	v_add_f32_e32 v95, v95, v96
	v_mul_f32_e32 v96, v91, v91
	v_mul_f32_e32 v97, v79, v79
	v_fmac_f32_e32 v96, v90, v90
	v_fmac_f32_e32 v97, v78, v78
	s_waitcnt lgkmcnt(0)
	v_permlane16_swap_b32_e32 v34, v93
	v_add_f32_e32 v34, v34, v93
	v_and_b32_e32 v93, 0xffff0000, v80
	v_lshlrev_b32_e32 v80, 16, v81
	v_and_b32_e32 v81, 0xffff0000, v81
	v_add_f32_e32 v96, v96, v97
	v_add_f32_e32 v95, v95, v96
	v_mul_f32_e32 v96, v93, v93
	v_mul_f32_e32 v97, v81, v81
	v_fmac_f32_e32 v96, v92, v92
	v_fmac_f32_e32 v97, v80, v80
	v_add_f32_e32 v96, v96, v97
	v_add_f32_e32 v95, v96, v95
	s_nop 1
	v_mov_b32_e32 v94, v34
	s_waitcnt lgkmcnt(0)
	v_add_f32_dpp v95, v95, v95 quad_perm:[1,0,3,2] row_mask:0xf bank_mask:0xf
	s_nop 1
	s_waitcnt lgkmcnt(0)
	v_permlane32_swap_b32_e32 v34, v94
	v_add_f32_e32 v34, v34, v94
	v_fmamk_f32 v34, v34, 0x3a800000, v76
	v_mul_f32_e32 v94, 0x4f800000, v34
	v_cmp_gt_f32_e32 vcc, s8, v34
	s_waitcnt lgkmcnt(0)
	v_add_f32_dpp v95, v95, v95 quad_perm:[2,3,0,1] row_mask:0xf bank_mask:0xf
	s_nop 1
	v_cndmask_b32_e32 v34, v34, v94, vcc
	v_sqrt_f32_e32 v97, v34
	v_lshlrev_b32_e32 v94, 16, v35
	s_waitcnt lgkmcnt(0)
	v_add_f32_dpp v95, v95, v95 row_half_mirror row_mask:0xf bank_mask:0xf
	v_add_u32_e32 v98, -1, v97
	v_fma_f32 v99, -v98, v97, v34
	v_cmp_ge_f32_e64 s[0:1], 0, v99
	v_add_u32_e32 v99, 1, v97
	s_nop 1
	v_cndmask_b32_e64 v98, v97, v98, s[0:1]
	v_fma_f32 v97, -v99, v97, v34
	v_cmp_lt_f32_e64 s[0:1], 0, v97
	s_nop 1
	v_cndmask_b32_e64 v97, v98, v99, s[0:1]
	v_mul_f32_e32 v98, 0x37800000, v97
	v_cndmask_b32_e32 v97, v97, v98, vcc
	v_cmp_class_f32_e32 vcc, v34, v77
	s_nop 1
	v_cndmask_b32_e32 v97, v97, v34, vcc
	s_waitcnt lgkmcnt(0)
	v_add_f32_dpp v34, v95, v95 row_mirror row_mask:0xf bank_mask:0xf
	v_mov_b32_e32 v96, v34
	v_and_b32_e32 v95, 0xffff0000, v35
	v_div_scale_f32 v98, s[0:1], v97, v97, 1.0
	v_rcp_f32_e32 v99, v98
	s_waitcnt lgkmcnt(0)
	v_permlane16_swap_b32_e32 v34, v96
	v_add_f32_e32 v34, v34, v96
	v_mov_b32_e32 v35, v34
	v_fma_f32 v96, -v98, v99, 1.0
	v_fmac_f32_e32 v99, v96, v99
	v_div_scale_f32 v96, vcc, 1.0, v97, 1.0
	s_waitcnt lgkmcnt(0)
	v_permlane32_swap_b32_e32 v34, v35
	v_add_f32_e32 v34, v34, v35
	v_fmamk_f32 v34, v34, 0x3a800000, v76
	v_mul_f32_e32 v35, 0x4f800000, v34
	v_cmp_gt_f32_e64 s[0:1], s8, v34
	v_mul_f32_e32 v100, v96, v99
	v_fma_f32 v101, -v98, v100, v96
	v_cndmask_b32_e64 v34, v34, v35, s[0:1]
	v_sqrt_f32_e32 v35, v34
	v_fmac_f32_e32 v100, v101, v99
	v_fma_f32 v96, -v98, v100, v96
	v_div_fmas_f32 v98, v96, v99, v100
	v_add_u32_e32 v101, -1, v35
	v_fma_f32 v102, -v101, v35, v34
	v_cmp_ge_f32_e64 s[2:3], 0, v102
	v_add_u32_e32 v102, 1, v35
	s_nop 0
	v_cndmask_b32_e64 v101, v35, v101, s[2:3]
	v_fma_f32 v35, -v102, v35, v34
	v_cmp_lt_f32_e64 s[2:3], 0, v35
	s_nop 1
	v_cndmask_b32_e64 v35, v101, v102, s[2:3]
	v_mul_f32_e32 v101, 0x37800000, v35
	v_cndmask_b32_e64 v35, v35, v101, s[0:1]
	v_cmp_class_f32_e64 s[0:1], v34, v77
	s_nop 1
	v_cndmask_b32_e64 v34, v35, v34, s[0:1]
	v_div_scale_f32 v35, s[0:1], v34, v34, 1.0
	v_rcp_f32_e32 v101, v35
	s_lshl_b64 s[0:1], s[4:5], 12
	s_cmp_gt_i32 s6, 0xffff
	v_fma_f32 v96, -v35, v101, 1.0
	v_fmac_f32_e32 v101, v96, v101
	v_div_scale_f32 v96, vcc, 1.0, v34, 1.0
	v_mul_f32_e32 v99, v96, v101
	v_fma_f32 v100, -v35, v99, v96
	v_fmac_f32_e32 v99, v100, v101
	v_fma_f32 v35, -v35, v99, v96
	v_div_fmas_f32 v35, v35, v101, v99
	v_div_fixup_f32 v34, v35, v34, 1.0
	v_mul_f32_e32 v96, 0.5, v34
	v_pk_mul_f32 v[34:35], v[96:97], v[66:67] op_sel_hi:[0,1]
	v_pk_mul_f32 v[86:87], v[96:97], v[86:87] op_sel_hi:[0,1]
	v_pk_fma_f32 v[34:35], v[2:3], v[34:35], v[48:49]
	v_pk_mul_f32 v[48:49], v[96:97], v[88:89] op_sel_hi:[0,1]
	v_pk_fma_f32 v[46:47], v[0:1], v[86:87], v[46:47]
	v_pk_fma_f32 v[36:37], v[4:5], v[48:49], v[36:37]
	v_pk_mul_f32 v[48:49], v[96:97], v[78:79] op_sel_hi:[0,1]
	v_pk_mul_f32 v[78:79], v[96:97], v[92:93] op_sel_hi:[0,1]
	v_pk_mul_f32 v[66:67], v[96:97], v[68:69] op_sel_hi:[0,1]
	v_pk_fma_f32 v[32:33], v[12:13], v[78:79], v[32:33]
	v_mul_f32_e32 v78, v47, v47
	v_mul_f32_e32 v79, v35, v35
	v_pk_fma_f32 v[38:39], v[6:7], v[66:67], v[38:39]
	v_fmac_f32_e32 v78, v46, v46
	v_fmac_f32_e32 v79, v34, v34
	v_pk_mul_f32 v[68:69], v[96:97], v[80:81] op_sel_hi:[0,1]
	v_add_f32_e32 v78, v78, v79
	v_mul_f32_e32 v79, v37, v37
	v_mul_f32_e32 v80, v39, v39
	v_pk_mul_f32 v[66:67], v[96:97], v[90:91] op_sel_hi:[0,1]
	v_fmac_f32_e32 v79, v36, v36
	v_fmac_f32_e32 v80, v38, v38
	v_pk_fma_f32 v[48:49], v[10:11], v[48:49], v[84:85]
	v_pk_fma_f32 v[66:67], v[8:9], v[66:67], v[82:83]
	v_add_f32_e32 v79, v79, v80
	v_add_f32_e32 v78, v78, v79
	v_mul_f32_e32 v79, v67, v67
	v_mul_f32_e32 v80, v49, v49
	v_fmac_f32_e32 v79, v66, v66
	v_fmac_f32_e32 v80, v48, v48
	v_pk_fma_f32 v[68:69], v[14:15], v[68:69], v[94:95]
	v_add_f32_e32 v79, v79, v80
	v_add_f32_e32 v78, v79, v78
	v_mul_f32_e32 v79, v33, v33
	v_mul_f32_e32 v80, v69, v69
	v_fmac_f32_e32 v79, v32, v32
	v_fmac_f32_e32 v80, v68, v68
	v_add_f32_e32 v79, v79, v80
	v_add_f32_e32 v79, v79, v78
	s_nop 1
	v_div_fixup_f32 v78, v98, v97, 1.0
	v_pk_mul_f32 v[80:81], v[64:65], v[78:79] op_sel_hi:[1,0]
	v_pk_mul_f32 v[62:63], v[62:63], v[78:79] op_sel_hi:[1,0]
	s_waitcnt lgkmcnt(0)
	v_add_f32_dpp v79, v79, v79 quad_perm:[1,0,3,2] row_mask:0xf bank_mask:0xf
	s_nop 1
	v_pk_mul_f32 v[64:65], v[30:31], v[62:63]
	v_pk_mul_f32 v[62:63], v[28:29], v[80:81]
	v_pk_mul_f32 v[80:81], v[60:61], v[78:79] op_sel_hi:[1,0]
	v_pk_mul_f32 v[58:59], v[58:59], v[78:79] op_sel_hi:[1,0]
	s_waitcnt lgkmcnt(0)
	v_add_f32_dpp v79, v79, v79 quad_perm:[2,3,0,1] row_mask:0xf bank_mask:0xf
	s_nop 1
	v_pk_mul_f32 v[54:55], v[54:55], v[78:79] op_sel_hi:[1,0]
	v_pk_mul_f32 v[56:57], v[56:57], v[78:79] op_sel_hi:[1,0]
	v_pk_mul_f32 v[60:61], v[26:27], v[58:59]
	v_pk_mul_f32 v[58:59], v[24:25], v[80:81]
	s_waitcnt lgkmcnt(0)
	v_add_f32_dpp v79, v79, v79 row_half_mirror row_mask:0xf bank_mask:0xf
	s_nop 1
	v_pk_mul_f32 v[50:51], v[50:51], v[78:79] op_sel_hi:[1,0]
	v_pk_mul_f32 v[52:53], v[52:53], v[78:79] op_sel_hi:[1,0]
	v_pk_mul_f32 v[50:51], v[16:17], v[50:51]
	v_pk_mul_f32 v[52:53], v[18:19], v[52:53]
	s_waitcnt lgkmcnt(0)
	v_add_f32_dpp v80, v79, v79 row_mirror row_mask:0xf bank_mask:0xf
	ds_bpermute_b32 v81, v74, v80
	v_lshl_add_u64 v[78:79], v[44:45], 0, s[0:1]
	global_store_dwordx4 v[78:79], v[50:53], off
	v_pk_mul_f32 v[56:57], v[22:23], v[56:57]
	v_pk_mul_f32 v[54:55], v[20:21], v[54:55]
	s_waitcnt lgkmcnt(0)
	v_add_f32_e32 v50, v80, v81
	ds_bpermute_b32 v51, v75, v50
	global_store_dwordx4 v[78:79], v[54:57], off offset:16
	global_store_dwordx4 v[78:79], v[58:61], off offset:2048
	global_store_dwordx4 v[78:79], v[62:65], off offset:2064
	s_cbranch_scc1 .LBB0_1552
	s_waitcnt lgkmcnt(0)
	v_add_f32_e32 v50, v50, v51
	v_fmamk_f32 v50, v50, 0x3a800000, v76
	v_mul_f32_e32 v51, 0x4f800000, v50
	v_cmp_gt_f32_e32 vcc, s8, v50
	s_ashr_i32 s7, s6, 31
	s_nop 0
	v_cndmask_b32_e32 v50, v50, v51, vcc
	v_sqrt_f32_e32 v51, v50
	s_nop 0
	v_add_u32_e32 v52, -1, v51
	v_fma_f32 v54, -v52, v51, v50
	v_add_u32_e32 v53, 1, v51
	v_cmp_ge_f32_e64 s[0:1], 0, v54
	s_nop 1
	v_cndmask_b32_e64 v52, v51, v52, s[0:1]
	v_fma_f32 v51, -v53, v51, v50
	v_cmp_lt_f32_e64 s[0:1], 0, v51
	s_nop 1
	v_cndmask_b32_e64 v51, v52, v53, s[0:1]
	v_mul_f32_e32 v52, 0x37800000, v51
	v_cndmask_b32_e32 v51, v51, v52, vcc
	v_cmp_class_f32_e32 vcc, v50, v77
	s_nop 1
	v_cndmask_b32_e32 v50, v51, v50, vcc
	v_div_scale_f32 v51, s[0:1], v50, v50, 1.0
	v_rcp_f32_e32 v52, v51
	s_lshl_b64 s[0:1], s[6:7], 12
	v_fma_f32 v53, -v51, v52, 1.0
	v_fmac_f32_e32 v52, v53, v52
	v_div_scale_f32 v53, vcc, 1.0, v50, 1.0
	v_mul_f32_e32 v54, v53, v52
	v_fma_f32 v55, -v51, v54, v53
	v_fmac_f32_e32 v54, v55, v52
	v_fma_f32 v51, -v51, v54, v53
	v_div_fmas_f32 v51, v51, v52, v54
	v_div_fixup_f32 v58, v51, v50, 1.0
	v_pk_mul_f32 v[32:33], v[32:33], v[58:59] op_sel_hi:[1,0]
	v_pk_mul_f32 v[50:51], v[68:69], v[58:59] op_sel_hi:[1,0]
	v_pk_mul_f32 v[34:35], v[34:35], v[58:59] op_sel_hi:[1,0]
	v_pk_mul_f32 v[52:53], v[30:31], v[50:51]
	v_pk_mul_f32 v[50:51], v[28:29], v[32:33]
	v_pk_mul_f32 v[32:33], v[66:67], v[58:59] op_sel_hi:[1,0]
	v_pk_mul_f32 v[48:49], v[48:49], v[58:59] op_sel_hi:[1,0]
	v_pk_mul_f32 v[54:55], v[24:25], v[32:33]
	v_pk_mul_f32 v[32:33], v[36:37], v[58:59] op_sel_hi:[1,0]
	v_pk_mul_f32 v[36:37], v[38:39], v[58:59] op_sel_hi:[1,0]
	v_pk_mul_f32 v[34:35], v[18:19], v[34:35]
	v_pk_mul_f32 v[38:39], v[22:23], v[36:37]
	v_pk_mul_f32 v[36:37], v[20:21], v[32:33]
	v_pk_mul_f32 v[32:33], v[46:47], v[58:59] op_sel_hi:[1,0]
	v_lshl_add_u64 v[46:47], v[44:45], 0, s[0:1]
	v_pk_mul_f32 v[32:33], v[16:17], v[32:33]
	v_pk_mul_f32 v[56:57], v[26:27], v[48:49]
	global_store_dwordx4 v[46:47], v[32:35], off
	global_store_dwordx4 v[46:47], v[36:39], off offset:16
	global_store_dwordx4 v[46:47], v[54:57], off offset:2048
	global_store_dwordx4 v[46:47], v[50:53], off offset:2064
	s_branch .LBB0_1552
